# v72 + MLA attention K/V LDS-DMA addresses: v_lshl_add_u64 replaced by v_lshlrev_b32 with SGPR-base global_load_lds
# speedup vs baseline: 1.0069x; 1.0002x over previous
.LBB0_1759:
	s_setprio 0
	v_readfirstlane_b32 s12, v222
	s_and_b32 s6, s12, 0xffffffc0
	v_or_b32_e32 v0, s6, v145
	v_mul_hi_i32 v1, v0, s16
	v_lshrrev_b32_e32 v2, 31, v1
	v_ashrrev_i32_e32 v1, 2, v1
	v_add_u32_e32 v2, v1, v2
	s_ashr_i32 s10, s21, 9
	v_lshrrev_b32_e32 v163, 1, v2
	s_ashr_i32 s11, s10, 31
	v_mad_u64_u32 v[164:165], s[8:9], v2, s17, v[0:1]
	v_xor_b32_e32 v1, v163, v222
	s_lshl_b64 s[2:3], s[10:11], 13
	v_bfi_b32 v1, -8, v164, v1
	v_cmp_lt_i32_e32 vcc, 15, v1
	v_add_u32_e32 v2, s2, v2
	s_and_saveexec_b64 s[8:9], vcc
	s_xor_b64 s[8:9], exec, s[8:9]
	v_lshl_add_u32 v159, v2, 6, v187
	s_or_saveexec_b64 s[8:9], s[8:9]
	s_bfe_u32 s6, s21, 0x40005
	s_lshl_b32 s13, s6, 7
	v_mov_b32_e32 v153, 0x1000
	s_xor_b64 exec, exec, s[8:9]
	v_lshl_or_b32 v2, v2, 11, s13
	v_add_u32_e32 v159, 0x8000000, v2
	v_mov_b32_e32 v153, 0x20000
	s_or_b64 exec, exec, s[8:9]
	v_add_u32_e32 v2, 0x200, v0
	v_mul_hi_i32 v3, v2, s16
	v_lshrrev_b32_e32 v4, 31, v3
	v_ashrrev_i32_e32 v3, 2, v3
	v_add_u32_e32 v4, v3, v4
	v_mad_u64_u32 v[166:167], s[8:9], v4, s17, v[2:3]
	v_lshrrev_b32_e32 v167, 1, v4
	v_xor_b32_e32 v3, v167, v222
	v_bfi_b32 v3, -8, v166, v3
	v_cmp_lt_i32_e32 vcc, 15, v3
	v_add_u32_e32 v4, s2, v4
	s_and_saveexec_b64 s[8:9], vcc
	s_xor_b64 s[8:9], exec, s[8:9]
	v_lshl_add_u32 v161, v4, 6, v187
	s_or_saveexec_b64 s[8:9], s[8:9]
	v_mov_b32_e32 v155, 0x1000
	s_xor_b64 exec, exec, s[8:9]
	v_lshl_or_b32 v4, v4, 11, s13
	v_add_u32_e32 v161, 0x8000000, v4
	v_mov_b32_e32 v155, 0x20000
	s_or_b64 exec, exec, s[8:9]
	v_add_u32_e32 v4, 0x400, v0
	v_mul_hi_i32 v5, v4, s16
	v_lshrrev_b32_e32 v6, 31, v5
	v_ashrrev_i32_e32 v5, 2, v5
	v_add_u32_e32 v5, v5, v6
	v_mad_u64_u32 v[168:169], s[8:9], v5, s17, v[4:5]
	v_lshrrev_b32_e32 v169, 1, v5
	v_xor_b32_e32 v4, v169, v222
	v_bfi_b32 v4, -8, v168, v4
	v_cmp_lt_i32_e32 vcc, 15, v4
	v_add_u32_e32 v5, s2, v5
	s_and_saveexec_b64 s[8:9], vcc
	s_xor_b64 s[8:9], exec, s[8:9]
	v_lshl_add_u32 v165, v5, 6, v187
	s_or_saveexec_b64 s[8:9], s[8:9]
	v_mov_b32_e32 v157, 0x1000
	s_xor_b64 exec, exec, s[8:9]
	v_lshl_or_b32 v5, v5, 11, s13
	v_add_u32_e32 v165, 0x8000000, v5
	v_mov_b32_e32 v157, 0x20000
	s_or_b64 exec, exec, s[8:9]
	s_not_b32 s8, s21
	s_lshl_b32 s8, s8, 8
	s_lshr_b32 s24, s12, 6
	s_and_b32 s11, s8, 0x1f00
	s_lshl_b32 s26, s24, 5
	s_or_b32 s13, s13, 0xc000000
	s_or_b32 s8, s2, s11
	s_add_u32 s22, s8, s26
	v_or_b32_e32 v5, s22, v144
	v_mov_b64_e32 v[6:7], s[4:5]
	s_addc_u32 s23, s3, 0
	v_mad_u64_u32 v[6:7], s[8:9], v5, s18, v[6:7]
	s_mulk_i32 s6, 0xc0
	v_mad_i32_i24 v7, s23, v188, v7
	s_lshl_b32 s6, s6, 1
	v_lshl_add_u64 v[6:7], v[6:7], 0, s[6:7]
	v_mov_b32_e32 v151, v147
	v_lshl_add_u64 v[6:7], v[6:7], 0, v[150:151]
	v_ashrrev_i32_e32 v8, 31, v0
	v_ashrrev_i32_e32 v9, 31, v2
	global_load_dwordx4 v[96:99], v[6:7], off
	global_load_dwordx4 v[100:103], v[6:7], off offset:32
	global_load_dwordx4 v[104:107], v[6:7], off offset:64
	global_load_dwordx4 v[108:111], v[6:7], off offset:96
	global_load_dwordx4 v[112:115], v[6:7], off offset:128
	global_load_dwordx4 v[116:119], v[6:7], off offset:160
	global_load_dwordx4 v[120:123], v[6:7], off offset:192
	global_load_dwordx4 v[124:127], v[6:7], off offset:224
	global_load_dwordx4 v[128:131], v[6:7], off offset:256
	global_load_dwordx4 v[132:135], v[6:7], off offset:288
	global_load_dwordx4 v[136:139], v[6:7], off offset:320
	global_load_dwordx4 v[140:143], v[6:7], off offset:352
	v_lshl_add_u32 v6, v3, 3, v161
	v_lshl_add_u32 v4, v4, 3, v165
	v_mov_b32_e32 v7, v147
	v_mov_b32_e32 v5, v147
	v_lshrrev_b32_e32 v14, 28, v8
	v_lshrrev_b32_e32 v15, 28, v9
	v_lshl_add_u64 v[10:11], v[6:7], 1, s[84:85]
	v_lshl_add_u64 v[12:13], v[4:5], 1, s[84:85]
	v_add_u32_e32 v5, v0, v14
	v_add_u32_e32 v7, v2, v15
	v_ashrrev_i32_e32 v170, 4, v5
	v_and_b32_e32 v5, 0x1ffffff0, v5
	v_ashrrev_i32_e32 v171, 4, v7
	v_sub_u32_e32 v0, v0, v5
	v_lshlrev_b32_e32 v5, 2, v170
	v_add_lshl_u32 v15, v170, s2, 11
	v_add_lshl_u32 v17, v171, s2, 11
	s_lshl_b32 s2, s24, 10
	v_lshl_add_u32 v146, v1, 3, v159
	v_bfe_u32 v14, v170, 2, 2
	v_and_b32_e32 v5, 12, v5
	s_add_i32 s25, s2, 0
	v_lshl_add_u64 v[8:9], v[146:147], 1, s[84:85]
	v_and_b32_e32 v7, 0x1ffffff0, v7
	v_bitop3_b32 v0, v5, v0, v14 bitop3:0x36
	s_mov_b32 m0, s25
	v_sub_u32_e32 v2, v2, v7
	v_lshlrev_b32_e32 v7, 2, v171
	v_lshlrev_b32_e32 v189, 3, v0
	global_load_lds_dwordx4 v[8:9], off
	s_add_i32 m0, s25, 0x2000
	v_mov_b32_e32 v1, v147
	v_bfe_u32 v16, v171, 2, 2
	v_and_b32_e32 v7, 12, v7
	v_add3_u32 v0, s13, v15, v189
	global_load_lds_dwordx4 v[10:11], off
	s_add_i32 m0, s25, 0x4000
	v_bitop3_b32 v2, v7, v2, v16 bitop3:0x36
	v_lshlrev_b32_e32 v8, 1, v0
	global_load_lds_dwordx4 v[12:13], off
	s_add_i32 m0, s25, 0x6000
	v_lshlrev_b32_e32 v190, 3, v2
	global_load_lds_dwordx4 v8, s[84:85]
	s_add_i32 m0, s25, 0x8000
	v_mov_b32_e32 v3, v147
	v_add3_u32 v2, s13, v17, v190
	s_cmpk_gt_u32 s12, 0xff
	v_lshlrev_b32_e32 v10, 1, v2
	s_cselect_b64 s[8:9], -1, 0
	s_cmpk_lt_u32 s12, 0x100
	v_add_u32_e32 v146, v146, v153
	global_load_lds_dwordx4 v10, s[84:85]
	s_cselect_b64 s[12:13], -1, 0
	s_add_i32 m0, s25, 0xa000
	v_lshl_add_u64 v[8:9], v[146:147], 1, s[84:85]
	v_add_u32_e32 v146, v6, v155
	s_waitcnt vmcnt(0) lgkmcnt(0)
	s_barrier
	s_waitcnt vmcnt(0)
	global_load_lds_dwordx4 v[8:9], off
	v_lshlrev_b32_e32 v6, 1, v146
	s_add_i32 m0, s25, 0xc000
	v_add_u32_e32 v146, v4, v157
	global_load_lds_dwordx4 v6, s[84:85]
	v_lshlrev_b32_e32 v4, 1, v146
	s_add_i32 m0, s25, 0xe000
	v_add_u32_e32 v146, 0x20000, v0
	global_load_lds_dwordx4 v4, s[84:85]
	s_add_i32 m0, s25, 0x10000
	v_lshlrev_b32_e32 v0, 1, v146
	v_add_u32_e32 v146, 0x20000, v2
	global_load_lds_dwordx4 v0, s[84:85]
	v_lshlrev_b32_e32 v0, 1, v146
	s_add_i32 m0, s25, 0x12000
	v_add_u32_e32 v36, 0, v149
	global_load_lds_dwordx4 v0, s[84:85]
	ds_read_b128 v[0:3], v36
	v_add_u32_e32 v40, 0, v172
	ds_read_b128 v[4:7], v40
	v_add_u32_e32 v44, 0, v173
	v_add_u32_e32 v64, 0, v174
	ds_read_b128 v[8:11], v44
	ds_read_b128 v[12:15], v64
	s_waitcnt lgkmcnt(3)
	v_mfma_f32_32x32x16_bf16 v[48:63], v[0:3], v[96:99], 0
	ds_read_b128 v[0:3], v36 offset:128
	s_and_b64 vcc, exec, s[12:13]
	s_waitcnt lgkmcnt(3)
	v_mfma_f32_32x32x16_bf16 v[48:63], v[4:7], v[100:103], v[48:63]
	ds_read_b128 v[4:7], v40 offset:128
	s_waitcnt lgkmcnt(3)
	v_mfma_f32_32x32x16_bf16 v[48:63], v[8:11], v[104:107], v[48:63]
	ds_read_b128 v[8:11], v44 offset:128
	s_waitcnt lgkmcnt(3)
	v_mfma_f32_32x32x16_bf16 v[48:63], v[12:15], v[108:111], v[48:63]
	ds_read_b128 v[12:15], v64 offset:128
	s_waitcnt lgkmcnt(3)
	v_mfma_f32_32x32x16_bf16 v[48:63], v[0:3], v[112:115], v[48:63]
	ds_read_b128 v[0:3], v36 offset:256
	s_waitcnt lgkmcnt(3)
	v_mfma_f32_32x32x16_bf16 v[48:63], v[4:7], v[116:119], v[48:63]
	ds_read_b128 v[4:7], v40 offset:256
	s_waitcnt lgkmcnt(3)
	v_mfma_f32_32x32x16_bf16 v[48:63], v[8:11], v[120:123], v[48:63]
	ds_read_b128 v[8:11], v44 offset:256
	s_waitcnt lgkmcnt(3)
	v_mfma_f32_32x32x16_bf16 v[48:63], v[12:15], v[124:127], v[48:63]
	ds_read_b128 v[12:15], v64 offset:256
	s_waitcnt lgkmcnt(3)
	v_mfma_f32_32x32x16_bf16 v[48:63], v[0:3], v[128:131], v[48:63]
	ds_read_b128 v[0:3], v36 offset:12288
	s_waitcnt lgkmcnt(3)
	v_mfma_f32_32x32x16_bf16 v[48:63], v[4:7], v[132:135], v[48:63]
	ds_read_b128 v[4:7], v40 offset:12288
	s_waitcnt lgkmcnt(3)
	v_mfma_f32_32x32x16_bf16 v[48:63], v[8:11], v[136:139], v[48:63]
	ds_read_b128 v[8:11], v44 offset:12288
	s_waitcnt lgkmcnt(2)
	v_mfma_f32_32x32x16_bf16 v[80:95], v[0:3], v[96:99], 0
	ds_read_b128 v[16:19], v64 offset:12288
	s_waitcnt lgkmcnt(2)
	v_mfma_f32_32x32x16_bf16 v[80:95], v[4:7], v[100:103], v[80:95]
	ds_read_b128 v[20:23], v36 offset:12416
	s_waitcnt lgkmcnt(2)
	v_mfma_f32_32x32x16_bf16 v[80:95], v[8:11], v[104:107], v[80:95]
	ds_read_b128 v[24:27], v40 offset:12416
	s_waitcnt lgkmcnt(2)
	v_mfma_f32_32x32x16_bf16 v[80:95], v[16:19], v[108:111], v[80:95]
	ds_read_b128 v[28:31], v44 offset:12416
	s_waitcnt lgkmcnt(2)
	v_mfma_f32_32x32x16_bf16 v[80:95], v[20:23], v[112:115], v[80:95]
	ds_read_b128 v[32:35], v64 offset:12416
	s_waitcnt lgkmcnt(2)
	v_mfma_f32_32x32x16_bf16 v[80:95], v[24:27], v[116:119], v[80:95]
	ds_read_b128 v[36:39], v36 offset:12544
	s_waitcnt lgkmcnt(2)
	v_mfma_f32_32x32x16_bf16 v[80:95], v[28:31], v[120:123], v[80:95]
	ds_read_b128 v[40:43], v40 offset:12544
	s_waitcnt lgkmcnt(2)
	v_mfma_f32_32x32x16_bf16 v[80:95], v[32:35], v[124:127], v[80:95]
	ds_read_b128 v[44:47], v44 offset:12544
	s_waitcnt lgkmcnt(2)
	v_mfma_f32_32x32x16_bf16 v[80:95], v[36:39], v[128:131], v[80:95]
	ds_read_b128 v[64:67], v64 offset:12544
	s_waitcnt lgkmcnt(2)
	v_mfma_f32_32x32x16_bf16 v[80:95], v[40:43], v[132:135], v[80:95]
	s_waitcnt lgkmcnt(1)
	v_mfma_f32_32x32x16_bf16 v[80:95], v[44:47], v[136:139], v[80:95]
	s_waitcnt lgkmcnt(0)
	v_mfma_f32_32x32x16_bf16 v[80:95], v[64:67], v[140:143], v[80:95]
	v_mfma_f32_32x32x16_bf16 v[48:63], v[12:15], v[140:143], v[48:63]
	s_cbranch_vccnz .LBB0_1773
	s_waitcnt vmcnt(0) lgkmcnt(0)
	s_barrier

.LBB0_1778:
	s_add_i32 s10, s25, s26
	v_lshlrev_b32_e32 v190, 1, v146
	s_mov_b32 m0, s10
	v_mov_b32_e32 v165, v147
	global_load_lds_dwordx4 v190, s[84:85]
	v_lshlrev_b32_e32 v190, 1, v164
	s_add_i32 m0, s10, 0x2000
	v_mov_b32_e32 v167, v147
	global_load_lds_dwordx4 v190, s[84:85]
	v_lshlrev_b32_e32 v190, 1, v166
	s_add_i32 m0, s10, 0x4000
	v_mov_b32_e32 v171, v147
	global_load_lds_dwordx4 v190, s[84:85]
	s_add_i32 m0, s10, 0x6000
	v_lshlrev_b32_e32 v190, 1, v170
	v_mov_b32_e32 v169, v147
	global_load_lds_dwordx4 v190, s[84:85]
	v_lshlrev_b32_e32 v190, 1, v168
	s_add_i32 m0, s10, 0x8000
	s_nop 0
	global_load_lds_dwordx4 v190, s[84:85]

.LBB0_1794:
	s_andn2_b64 vcc, exec, s[2:3]
	s_cbranch_vccnz .LBB0_2068
	s_lshl_b32 s2, s68, 5
	s_and_b32 s2, s2, 0xe0
	s_ashr_i32 s7, s68, 3
	s_add_i32 s2, s2, s7
	v_readfirstlane_b32 s14, v222
	s_ashr_i32 s12, s2, 6
	s_bfe_u32 s6, s2, 0x40002
	s_movk_i32 s2, 0xffc0
	v_mov_b32_e32 v0, s14
	v_bfi_b32 v0, s2, v0, v222
	s_mov_b32 s2, 0x2aaaaaab
	s_waitcnt lgkmcnt(0)
	v_mul_hi_i32 v1, v0, s2
	v_lshrrev_b32_e32 v2, 31, v1
	v_ashrrev_i32_e32 v1, 2, v1
	v_add_u32_e32 v2, v1, v2
	s_movk_i32 s2, 0xffe8
	v_lshrrev_b32_e32 v150, 1, v2
	s_ashr_i32 s13, s12, 31
	v_mad_u64_u32 v[144:145], s[2:3], v2, s2, v[0:1]
	v_xor_b32_e32 v1, v150, v222
	s_lshl_b64 s[8:9], s[12:13], 13
	v_bfi_b32 v1, -8, v144, v1
	v_cmp_lt_i32_e32 vcc, 15, v1
	v_add_u32_e32 v2, s8, v2
	s_and_saveexec_b64 s[2:3], vcc
	s_xor_b64 s[2:3], exec, s[2:3]
	v_mov_b32_e32 v3, 0xbfff80
	v_lshl_add_u32 v145, v2, 6, v3
	s_or_saveexec_b64 s[2:3], s[2:3]
	s_lshl_b32 s17, s6, 7
	v_mov_b32_e32 v154, 0x1000
	s_xor_b64 exec, exec, s[2:3]
	v_lshl_or_b32 v2, v2, 11, s17
	v_add_u32_e32 v145, 0x8000000, v2
	v_mov_b32_e32 v154, 0x20000
	s_or_b64 exec, exec, s[2:3]
	v_add_u32_e32 v2, 0x200, v0
	s_mov_b32 s2, 0x2aaaaaab
	v_mul_hi_i32 v3, v2, s2
	v_lshrrev_b32_e32 v4, 31, v3
	v_ashrrev_i32_e32 v3, 2, v3
	v_add_u32_e32 v4, v3, v4
	s_movk_i32 s2, 0xffe8
	v_lshrrev_b32_e32 v151, 1, v4
	v_mad_u64_u32 v[146:147], s[2:3], v4, s2, v[2:3]
	v_xor_b32_e32 v3, v151, v222
	v_bfi_b32 v3, -8, v146, v3
	v_cmp_lt_i32_e32 vcc, 15, v3
	v_add_u32_e32 v4, s8, v4
	s_and_saveexec_b64 s[2:3], vcc
	s_xor_b64 s[2:3], exec, s[2:3]
	v_mov_b32_e32 v5, 0xbfff80
	v_lshl_add_u32 v147, v4, 6, v5
	s_or_saveexec_b64 s[2:3], s[2:3]
	v_mov_b32_e32 v155, 0x1000
	s_xor_b64 exec, exec, s[2:3]
	v_lshl_or_b32 v4, v4, 11, s17
	v_add_u32_e32 v147, 0x8000000, v4
	v_mov_b32_e32 v155, 0x20000
	s_or_b64 exec, exec, s[2:3]
	v_add_u32_e32 v4, 0x400, v0
	s_mov_b32 s2, 0x2aaaaaab
	v_mul_hi_i32 v5, v4, s2
	v_lshrrev_b32_e32 v6, 31, v5
	v_ashrrev_i32_e32 v5, 2, v5
	v_add_u32_e32 v5, v5, v6
	s_movk_i32 s2, 0xffe8
	v_lshrrev_b32_e32 v152, 1, v5
	v_mad_u64_u32 v[148:149], s[2:3], v5, s2, v[4:5]
	v_xor_b32_e32 v4, v152, v222
	v_bfi_b32 v4, -8, v148, v4
	v_cmp_lt_i32_e32 vcc, 15, v4
	v_add_u32_e32 v5, s8, v5
	s_and_saveexec_b64 s[2:3], vcc
	s_xor_b64 s[2:3], exec, s[2:3]
	v_mov_b32_e32 v6, 0xbfff80
	v_lshl_add_u32 v149, v5, 6, v6
	s_or_saveexec_b64 s[2:3], s[2:3]
	v_and_b32_e32 v197, 63, v222
	v_mov_b32_e32 v156, 0x1000
	s_xor_b64 exec, exec, s[2:3]
	v_lshl_or_b32 v5, v5, 11, s17
	v_add_u32_e32 v149, 0x8000000, v5
	v_mov_b32_e32 v156, 0x20000
	s_or_b64 exec, exec, s[2:3]
	s_lshl_b32 s2, s7, 8
	s_and_b32 s16, s2, 0x300
	s_lshr_b32 s21, s14, 6
	s_xor_b32 s13, s16, 0x1f00
	s_lshl_b32 s22, s21, 5
	s_or_b32 s18, s17, 0xc000000
	s_or_b32 s2, s8, s13
	v_and_b32_e32 v194, 31, v222
	s_add_u32 s19, s2, s22
	v_or_b32_e32 v5, s19, v194
	s_movk_i32 s2, 0x1800
	v_mov_b64_e32 v[8:9], s[4:5]
	v_lshl_add_u32 v10, v1, 3, v145
	v_ashrrev_i32_e32 v1, 31, v0
	s_addc_u32 s20, s9, 0
	v_mad_u64_u32 v[8:9], s[2:3], v5, s2, v[8:9]
	v_mov_b32_e32 v5, 0x1800
	s_mulk_i32 s6, 0xc0
	v_lshrrev_b32_e32 v1, 28, v1
	v_lshrrev_b32_e32 v161, 5, v197
	s_mov_b32 s7, 0
	v_mad_i32_i24 v9, s20, v5, v9
	s_lshl_b32 s6, s6, 1
	v_add_u32_e32 v1, v0, v1
	v_mov_b32_e32 v7, 0
	v_lshl_add_u64 v[8:9], v[8:9], 0, s[6:7]
	v_lshlrev_b32_e32 v6, 4, v161
	v_ashrrev_i32_e32 v153, 4, v1
	v_and_b32_e32 v1, 0x1ffffff0, v1
	v_lshl_add_u64 v[8:9], v[8:9], 0, v[6:7]
	v_sub_u32_e32 v0, v0, v1
	v_lshlrev_b32_e32 v1, 2, v153
	global_load_dwordx4 v[96:99], v[8:9], off
	global_load_dwordx4 v[100:103], v[8:9], off offset:32
	global_load_dwordx4 v[104:107], v[8:9], off offset:64
	global_load_dwordx4 v[108:111], v[8:9], off offset:96
	global_load_dwordx4 v[112:115], v[8:9], off offset:128
	global_load_dwordx4 v[116:119], v[8:9], off offset:160
	global_load_dwordx4 v[120:123], v[8:9], off offset:192
	global_load_dwordx4 v[124:127], v[8:9], off offset:224
	global_load_dwordx4 v[128:131], v[8:9], off offset:256
	global_load_dwordx4 v[132:135], v[8:9], off offset:288
	global_load_dwordx4 v[136:139], v[8:9], off offset:320
	global_load_dwordx4 v[140:143], v[8:9], off offset:352
	v_lshl_add_u32 v8, v3, 3, v147
	v_and_b32_e32 v1, 12, v1
	v_bfe_u32 v3, v153, 2, 2
	v_bitop3_b32 v0, v1, v0, v3 bitop3:0x36
	v_lshlrev_b32_e32 v158, 3, v0
	v_add_lshl_u32 v0, v153, s8, 11
	v_add3_u32 v12, s18, v0, v158
	v_ashrrev_i32_e32 v0, 31, v2
	v_lshrrev_b32_e32 v0, 28, v0
	v_add_u32_e32 v0, v2, v0
	v_ashrrev_i32_e32 v159, 4, v0
	v_and_b32_e32 v0, 0x1ffffff0, v0
	v_lshlrev_b32_e32 v1, 2, v159
	v_sub_u32_e32 v0, v2, v0
	v_and_b32_e32 v1, 12, v1
	v_bfe_u32 v2, v159, 2, 2
	v_bitop3_b32 v0, v1, v0, v2 bitop3:0x36
	s_lshl_b32 s2, s21, 10
	v_lshlrev_b32_e32 v160, 3, v0
	v_add_lshl_u32 v0, v159, s8, 11
	s_add_i32 s7, s2, 0
	v_mov_b32_e32 v11, v7
	v_add3_u32 v2, s18, v0, v160
	v_lshlrev_b32_e32 v0, 1, v10
	s_mov_b32 m0, s7
	v_mov_b32_e32 v9, v7
	v_lshl_add_u32 v4, v4, 3, v149
	global_load_lds_dwordx4 v0, s[84:85]
	v_lshlrev_b32_e32 v0, 1, v8
	s_add_i32 m0, s7, 0x2000
	v_mov_b32_e32 v5, v7
	global_load_lds_dwordx4 v0, s[84:85]
	v_lshlrev_b32_e32 v0, 1, v4
	s_add_i32 m0, s7, 0x4000
	v_mov_b32_e32 v13, v7
	global_load_lds_dwordx4 v0, s[84:85]
	s_add_i32 m0, s7, 0x6000
	v_lshlrev_b32_e32 v0, 1, v12
	v_mov_b32_e32 v3, v7
	global_load_lds_dwordx4 v0, s[84:85]
	v_lshlrev_b32_e32 v0, 1, v2
	s_add_i32 m0, s7, 0x8000
	s_cmpk_gt_u32 s14, 0xff
	global_load_lds_dwordx4 v0, s[84:85]
	v_mov_b32_e32 v0, v7
	s_waitcnt vmcnt(0) lgkmcnt(0)
	s_barrier
	s_waitcnt vmcnt(0)
	s_cselect_b64 s[10:11], -1, 0
	s_cmpk_lt_u32 s14, 0x100
	v_add_u32_e32 v6, v10, v154
	v_lshrrev_b32_e32 v0, 1, v222
	s_cselect_b64 s[14:15], -1, 0
	s_add_i32 m0, s7, 0xa000
	v_lshlrev_b32_e32 v10, 1, v6
	v_add_u32_e32 v6, v8, v155
	v_bfe_u32 v1, v222, 1, 3
	v_mul_u32_u24_e32 v13, 0x180, v194
	v_bitop3_b32 v3, v161, v0, 7 bitop3:0x78
	global_load_lds_dwordx4 v10, s[84:85]
	v_lshlrev_b32_e32 v8, 1, v6
	s_add_i32 m0, s7, 0xc000
	v_add_u32_e32 v6, v4, v156
	v_lshl_or_b32 v170, v3, 4, v13
	v_bitop3_b32 v3, v161, v1, 2 bitop3:0x36
	global_load_lds_dwordx4 v8, s[84:85]
	v_lshlrev_b32_e32 v4, 1, v6
	s_add_i32 m0, s7, 0xe000
	v_add_u32_e32 v6, 0x20000, v12
	v_lshl_or_b32 v171, v3, 4, v13
	v_bitop3_b32 v3, v161, v1, 4 bitop3:0x36
	global_load_lds_dwordx4 v4, s[84:85]
	s_add_i32 m0, s7, 0x10000
	v_lshlrev_b32_e32 v4, 1, v6
	v_add_u32_e32 v6, 0x20000, v2
	v_lshl_or_b32 v172, v3, 4, v13
	global_load_lds_dwordx4 v4, s[84:85]
	v_lshlrev_b32_e32 v2, 1, v6
	s_add_i32 m0, s7, 0x12000
	v_add_u32_e32 v190, 0, v170
	global_load_lds_dwordx4 v2, s[84:85]
	ds_read_b128 v[2:5], v190
	v_bitop3_b32 v1, v161, v1, 6 bitop3:0x36
	v_lshl_or_b32 v173, v1, 4, v13
	v_add_u32_e32 v191, 0, v171
	ds_read_b128 v[6:9], v191
	v_add_u32_e32 v192, 0, v172
	v_add_u32_e32 v193, 0, v173
	ds_read_b128 v[10:13], v192
	ds_read_b128 v[14:17], v193
	s_waitcnt lgkmcnt(3)
	v_mfma_f32_32x32x16_bf16 v[48:63], v[2:5], v[96:99], 0
	ds_read_b128 v[2:5], v190 offset:128
	v_or_b32_e32 v1, 2, v161
	s_and_b64 vcc, exec, s[14:15]
	s_waitcnt lgkmcnt(3)
	v_mfma_f32_32x32x16_bf16 v[48:63], v[6:9], v[100:103], v[48:63]
	ds_read_b128 v[6:9], v191 offset:128
	s_waitcnt lgkmcnt(3)
	v_mfma_f32_32x32x16_bf16 v[48:63], v[10:13], v[104:107], v[48:63]
	ds_read_b128 v[10:13], v192 offset:128
	s_waitcnt lgkmcnt(3)
	v_mfma_f32_32x32x16_bf16 v[48:63], v[14:17], v[108:111], v[48:63]
	ds_read_b128 v[14:17], v193 offset:128
	s_waitcnt lgkmcnt(3)
	v_mfma_f32_32x32x16_bf16 v[48:63], v[2:5], v[112:115], v[48:63]
	ds_read_b128 v[2:5], v190 offset:256
	s_waitcnt lgkmcnt(3)
	v_mfma_f32_32x32x16_bf16 v[48:63], v[6:9], v[116:119], v[48:63]
	ds_read_b128 v[6:9], v191 offset:256
	s_waitcnt lgkmcnt(3)
	v_mfma_f32_32x32x16_bf16 v[48:63], v[10:13], v[120:123], v[48:63]
	ds_read_b128 v[10:13], v192 offset:256
	s_waitcnt lgkmcnt(3)
	v_mfma_f32_32x32x16_bf16 v[48:63], v[14:17], v[124:127], v[48:63]
	ds_read_b128 v[14:17], v193 offset:256
	s_waitcnt lgkmcnt(3)
	v_mfma_f32_32x32x16_bf16 v[48:63], v[2:5], v[128:131], v[48:63]
	ds_read_b128 v[2:5], v190 offset:12288
	s_waitcnt lgkmcnt(3)
	v_mfma_f32_32x32x16_bf16 v[48:63], v[6:9], v[132:135], v[48:63]
	ds_read_b128 v[6:9], v191 offset:12288
	s_waitcnt lgkmcnt(3)
	v_mfma_f32_32x32x16_bf16 v[48:63], v[10:13], v[136:139], v[48:63]
	ds_read_b128 v[10:13], v192 offset:12288
	s_waitcnt lgkmcnt(2)
	v_mfma_f32_32x32x16_bf16 v[80:95], v[2:5], v[96:99], 0
	ds_read_b128 v[18:21], v193 offset:12288
	s_waitcnt lgkmcnt(2)
	v_mfma_f32_32x32x16_bf16 v[80:95], v[6:9], v[100:103], v[80:95]
	ds_read_b128 v[22:25], v190 offset:12416
	s_waitcnt lgkmcnt(2)
	v_mfma_f32_32x32x16_bf16 v[80:95], v[10:13], v[104:107], v[80:95]
	ds_read_b128 v[26:29], v191 offset:12416
	s_waitcnt lgkmcnt(2)
	v_mfma_f32_32x32x16_bf16 v[80:95], v[18:21], v[108:111], v[80:95]
	ds_read_b128 v[30:33], v192 offset:12416
	s_waitcnt lgkmcnt(2)
	v_mfma_f32_32x32x16_bf16 v[80:95], v[22:25], v[112:115], v[80:95]
	ds_read_b128 v[34:37], v193 offset:12416
	s_waitcnt lgkmcnt(2)
	v_mfma_f32_32x32x16_bf16 v[80:95], v[26:29], v[116:119], v[80:95]
	ds_read_b128 v[38:41], v190 offset:12544
	s_waitcnt lgkmcnt(2)
	v_mfma_f32_32x32x16_bf16 v[80:95], v[30:33], v[120:123], v[80:95]
	ds_read_b128 v[42:45], v191 offset:12544
	s_waitcnt lgkmcnt(2)
	v_mfma_f32_32x32x16_bf16 v[80:95], v[34:37], v[124:127], v[80:95]
	ds_read_b128 v[64:67], v192 offset:12544
	s_waitcnt lgkmcnt(2)
	v_mfma_f32_32x32x16_bf16 v[80:95], v[38:41], v[128:131], v[80:95]
	ds_read_b128 v[68:71], v193 offset:12544
	s_waitcnt lgkmcnt(2)
	v_mfma_f32_32x32x16_bf16 v[80:95], v[42:45], v[132:135], v[80:95]
	s_waitcnt lgkmcnt(1)
	v_mfma_f32_32x32x16_bf16 v[80:95], v[64:67], v[136:139], v[80:95]
	s_waitcnt lgkmcnt(0)
	v_mfma_f32_32x32x16_bf16 v[80:95], v[68:71], v[140:143], v[80:95]
	v_mfma_f32_32x32x16_bf16 v[48:63], v[14:17], v[140:143], v[48:63]
	s_cbranch_vccnz .LBB0_1809
	s_waitcnt vmcnt(0) lgkmcnt(0)
	s_barrier

.LBB0_1814:
	s_add_i32 s12, s7, s23
	v_lshlrev_b32_e32 v158, 1, v144
	s_mov_b32 m0, s12
	v_mov_b32_e32 v147, v145
	global_load_lds_dwordx4 v158, s[84:85]
	v_lshlrev_b32_e32 v158, 1, v146
	s_add_i32 m0, s12, 0x2000
	v_mov_b32_e32 v149, v145
	global_load_lds_dwordx4 v158, s[84:85]
	v_lshlrev_b32_e32 v158, 1, v148
	s_add_i32 m0, s12, 0x4000
	v_mov_b32_e32 v153, v145
	global_load_lds_dwordx4 v158, s[84:85]
	s_add_i32 m0, s12, 0x6000
	v_lshlrev_b32_e32 v158, 1, v152
	v_mov_b32_e32 v151, v145
	global_load_lds_dwordx4 v158, s[84:85]
	v_lshlrev_b32_e32 v158, 1, v150
	s_add_i32 m0, s12, 0x8000
	s_nop 0
	global_load_lds_dwordx4 v158, s[84:85]

.LBB0_1829:
	s_setprio 0
	v_mov_b32_e32 v48, v161
	s_nop 1
	v_permlane32_swap_b32_e32 v161, v48
	v_add_f32_e32 v48, v161, v48
	v_div_scale_f32 v49, s[2:3], v48, v48, 1.0
	v_rcp_f32_e32 v50, v49
	s_mulk_i32 s21, 0x2200
	s_add_i32 s7, s21, 0
	v_mul_u32_u24_e32 v195, 0x110, v194
	v_fma_f32 v51, -v49, v50, 1.0
	v_fmac_f32_e32 v50, v51, v50
	v_div_scale_f32 v51, vcc, 1.0, v48, 1.0
	v_mul_f32_e32 v52, v51, v50
	v_fma_f32 v53, -v49, v52, v51
	v_fmac_f32_e32 v52, v53, v50
	v_fma_f32 v49, -v49, v52, v51
	v_div_fmas_f32 v49, v49, v50, v52
	v_div_fixup_f32 v48, v49, v48, 1.0
	v_add3_u32 v49, s7, v195, v181
	v_pk_mul_f32 v[50:51], v[64:65], v[48:49] op_sel_hi:[1,0]
	v_pk_mul_f32 v[52:53], v[66:67], v[48:49] op_sel_hi:[1,0]
	v_cvt_pk_bf16_f32 v50, v50, v51
	v_cvt_pk_bf16_f32 v51, v52, v53
	v_pk_mul_f32 v[52:53], v[68:69], v[48:49] op_sel_hi:[1,0]
	v_pk_mul_f32 v[54:55], v[70:71], v[48:49] op_sel_hi:[1,0]
	v_add_u32_e32 v49, 0xa000, v49
	v_pk_mul_f32 v[32:33], v[32:33], v[48:49] op_sel_hi:[1,0]
	v_pk_mul_f32 v[34:35], v[34:35], v[48:49] op_sel_hi:[1,0]
	v_pk_mul_f32 v[16:17], v[16:17], v[48:49] op_sel_hi:[1,0]
	v_pk_mul_f32 v[18:19], v[18:19], v[48:49] op_sel_hi:[1,0]
	v_pk_mul_f32 v[0:1], v[0:1], v[48:49] op_sel_hi:[1,0]
	v_pk_mul_f32 v[2:3], v[2:3], v[48:49] op_sel_hi:[1,0]
	v_cvt_pk_bf16_f32 v32, v32, v33
	v_cvt_pk_bf16_f32 v33, v34, v35
	v_pk_mul_f32 v[34:35], v[36:37], v[48:49] op_sel_hi:[1,0]
	v_pk_mul_f32 v[36:37], v[38:39], v[48:49] op_sel_hi:[1,0]
	v_cvt_pk_bf16_f32 v16, v16, v17
	v_cvt_pk_bf16_f32 v17, v18, v19
	v_pk_mul_f32 v[18:19], v[20:21], v[48:49] op_sel_hi:[1,0]
	v_pk_mul_f32 v[20:21], v[22:23], v[48:49] op_sel_hi:[1,0]
	v_cvt_pk_bf16_f32 v0, v0, v1
	v_cvt_pk_bf16_f32 v1, v2, v3
	v_pk_mul_f32 v[2:3], v[4:5], v[48:49] op_sel_hi:[1,0]
	v_pk_mul_f32 v[4:5], v[6:7], v[48:49] op_sel_hi:[1,0]
	v_cvt_pk_bf16_f32 v52, v52, v53
	v_cvt_pk_bf16_f32 v53, v54, v55
	v_cvt_pk_bf16_f32 v34, v34, v35
	v_cvt_pk_bf16_f32 v35, v36, v37
	v_cvt_pk_bf16_f32 v18, v18, v19
	v_cvt_pk_bf16_f32 v19, v20, v21
	v_cvt_pk_bf16_f32 v2, v2, v3
	v_cvt_pk_bf16_f32 v3, v4, v5
	s_waitcnt vmcnt(0) lgkmcnt(0)
	s_barrier
	ds_write2_b64 v49, v[50:51], v[52:53] offset1:2
	v_pk_mul_f32 v[50:51], v[72:73], v[48:49] op_sel_hi:[1,0]
	v_pk_mul_f32 v[52:53], v[74:75], v[48:49] op_sel_hi:[1,0]
	ds_write2_b64 v49, v[32:33], v[34:35] offset0:8 offset1:10
	v_pk_mul_f32 v[32:33], v[40:41], v[48:49] op_sel_hi:[1,0]
	v_pk_mul_f32 v[34:35], v[42:43], v[48:49] op_sel_hi:[1,0]
	ds_write2_b64 v49, v[16:17], v[18:19] offset0:16 offset1:18
	v_pk_mul_f32 v[16:17], v[24:25], v[48:49] op_sel_hi:[1,0]
	v_pk_mul_f32 v[18:19], v[26:27], v[48:49] op_sel_hi:[1,0]
	ds_write2_b64 v49, v[0:1], v[2:3] offset0:24 offset1:26
	v_pk_mul_f32 v[0:1], v[8:9], v[48:49] op_sel_hi:[1,0]
	v_pk_mul_f32 v[2:3], v[10:11], v[48:49] op_sel_hi:[1,0]
	v_cvt_pk_bf16_f32 v50, v50, v51
	v_cvt_pk_bf16_f32 v51, v52, v53
	v_pk_mul_f32 v[52:53], v[76:77], v[48:49] op_sel_hi:[1,0]
	v_pk_mul_f32 v[54:55], v[78:79], v[48:49] op_sel_hi:[1,0]
	v_cvt_pk_bf16_f32 v32, v32, v33
	v_cvt_pk_bf16_f32 v33, v34, v35
	v_pk_mul_f32 v[34:35], v[44:45], v[48:49] op_sel_hi:[1,0]
	v_pk_mul_f32 v[36:37], v[46:47], v[48:49] op_sel_hi:[1,0]
	v_cvt_pk_bf16_f32 v16, v16, v17
	v_cvt_pk_bf16_f32 v17, v18, v19
	v_pk_mul_f32 v[18:19], v[28:29], v[48:49] op_sel_hi:[1,0]
	v_pk_mul_f32 v[20:21], v[30:31], v[48:49] op_sel_hi:[1,0]
	v_cvt_pk_bf16_f32 v0, v0, v1
	v_cvt_pk_bf16_f32 v1, v2, v3
	v_pk_mul_f32 v[2:3], v[12:13], v[48:49] op_sel_hi:[1,0]
	v_pk_mul_f32 v[4:5], v[14:15], v[48:49] op_sel_hi:[1,0]
	v_cvt_pk_bf16_f32 v52, v52, v53
	v_cvt_pk_bf16_f32 v53, v54, v55
	v_cvt_pk_bf16_f32 v34, v34, v35
	v_cvt_pk_bf16_f32 v35, v36, v37
	v_cvt_pk_bf16_f32 v18, v18, v19
	v_cvt_pk_bf16_f32 v19, v20, v21
	v_cvt_pk_bf16_f32 v2, v2, v3
	v_cvt_pk_bf16_f32 v3, v4, v5
	s_mulk_i32 s20, 0x1800
	s_mul_hi_u32 s2, s19, 0x1800
	v_lshrrev_b32_e32 v14, 4, v197
	v_and_b32_e32 v164, 15, v222
	ds_write2_b64 v49, v[50:51], v[52:53] offset0:4 offset1:6
	ds_write2_b64 v49, v[32:33], v[34:35] offset0:12 offset1:14
	ds_write2_b64 v49, v[16:17], v[18:19] offset0:20 offset1:22
	ds_write2_b64 v49, v[0:1], v[2:3] offset0:28 offset1:30
	s_add_i32 s2, s2, s20
	s_mulk_i32 s19, 0x1800
	v_lshlrev_b32_e32 v144, 4, v164
	v_mul_u32_u24_e32 v196, 0x110, v14
	s_nop 0
	s_add_u32 s3, s4, s19
	v_add3_u32 v15, s7, v144, v196
	s_addc_u32 s10, s5, s2
	ds_read_b128 v[0:3], v15 offset:40960
	s_add_u32 s2, s3, s6
	s_addc_u32 s3, s10, 0
	v_mov_b32_e32 v145, 0
	v_mul_u32_u24_e32 v16, 0xc00, v14
	ds_read_b128 v[4:7], v15 offset:42048
	v_lshl_add_u64 v[8:9], s[2:3], 0, v[144:145]
	v_lshlrev_b32_e32 v146, 1, v16
	v_mov_b32_e32 v147, v145
	v_lshl_add_u64 v[10:11], v[8:9], 0, v[146:147]
	s_movk_i32 s3, 0x6000
	s_waitcnt lgkmcnt(1)
	global_store_dwordx4 v[10:11], v[0:3], off
	v_mov_b32_e32 v149, v145
	s_movk_i32 s2, 0xc00
	v_add_co_u32_e32 v0, vcc, s3, v10
	s_mov_b32 s3, 0xc000
	s_nop 0
	v_addc_co_u32_e32 v1, vcc, 0, v11, vcc
	s_waitcnt lgkmcnt(0)
	global_store_dwordx4 v[0:1], v[4:7], off
	ds_read_b128 v[0:3], v15 offset:43136
	ds_read_b128 v[4:7], v15 offset:44224
	v_add_co_u32_e32 v12, vcc, s3, v10
	s_mov_b32 s3, 0x12000
	s_nop 0
	v_addc_co_u32_e32 v13, vcc, 0, v11, vcc
	s_waitcnt lgkmcnt(1)
	global_store_dwordx4 v[12:13], v[0:3], off
	v_mov_b32_e32 v153, v145
	v_mov_b32_e32 v151, v145
	v_add_co_u32_e32 v0, vcc, s3, v10
	v_mov_b32_e32 v155, v145
	s_nop 0
	v_addc_co_u32_e32 v1, vcc, 0, v11, vcc
	s_waitcnt lgkmcnt(0)
	global_store_dwordx4 v[0:1], v[4:7], off
	ds_read_b128 v[0:3], v15 offset:45312
	v_readfirstlane_b32 s12, v222
	v_or_b32_e32 v4, 0xc000, v16
	v_lshlrev_b32_e32 v148, 1, v4
	v_lshl_add_u64 v[10:11], v[8:9], 0, v[148:149]
	ds_read_b128 v[4:7], v15 offset:46400
	s_waitcnt lgkmcnt(1)
	global_store_dwordx4 v[10:11], v[0:3], off
	s_nop 1
	v_mov_b32_e32 v0, 0xf000
	v_mad_u32_u24 v0, v14, s2, v0
	v_lshlrev_b32_e32 v152, 1, v0
	v_lshl_add_u64 v[0:1], v[8:9], 0, v[152:153]
	s_waitcnt lgkmcnt(0)
	global_store_dwordx4 v[0:1], v[4:7], off
	ds_read_b128 v[0:3], v15 offset:47488
	s_nop 0
	v_mov_b32_e32 v4, 0x12000
	v_mad_u32_u24 v4, v14, s2, v4
	v_lshlrev_b32_e32 v150, 1, v4
	v_lshl_add_u64 v[10:11], v[8:9], 0, v[150:151]
	ds_read_b128 v[4:7], v15 offset:48576
	s_waitcnt lgkmcnt(1)
	global_store_dwordx4 v[10:11], v[0:3], off
	s_nop 1
	v_mov_b32_e32 v0, 0x15000
	v_mad_u32_u24 v0, v14, s2, v0
	v_lshlrev_b32_e32 v154, 1, v0
	v_lshl_add_u64 v[0:1], v[8:9], 0, v[154:155]
	s_and_b32 s2, s12, 0xffffffc0
	s_waitcnt lgkmcnt(0)
	global_store_dwordx4 v[0:1], v[4:7], off
	v_or_b32_e32 v0, s2, v197
	s_mov_b32 s2, 0x2aaaaaab
	v_mul_hi_i32 v1, v0, s2
	v_lshrrev_b32_e32 v2, 31, v1
	v_ashrrev_i32_e32 v1, 2, v1
	v_add_u32_e32 v2, v1, v2
	s_movk_i32 s2, 0xffe8
	v_lshrrev_b32_e32 v165, 1, v2
	v_mad_u64_u32 v[158:159], s[2:3], v2, s2, v[0:1]
	v_xor_b32_e32 v1, v165, v222
	v_bfi_b32 v1, -8, v158, v1
	v_cmp_lt_i32_e32 vcc, 15, v1
	v_add_u32_e32 v2, s8, v2
	s_and_saveexec_b64 s[2:3], vcc
	s_xor_b64 s[2:3], exec, s[2:3]
	v_mov_b32_e32 v3, 0xbfff80
	v_lshl_add_u32 v155, v2, 6, v3
	s_or_saveexec_b64 s[2:3], s[2:3]
	v_mov_b32_e32 v145, 0x1000
	s_xor_b64 exec, exec, s[2:3]
	v_lshl_or_b32 v2, v2, 11, s17
	v_add_u32_e32 v155, 0x8000000, v2
	v_mov_b32_e32 v145, 0x20000
	s_or_b64 exec, exec, s[2:3]
	v_add_u32_e32 v2, 0x200, v0
	s_mov_b32 s2, 0x2aaaaaab
	v_mul_hi_i32 v3, v2, s2
	v_lshrrev_b32_e32 v4, 31, v3
	v_ashrrev_i32_e32 v3, 2, v3
	v_add_u32_e32 v4, v3, v4
	s_movk_i32 s2, 0xffe8
	v_lshrrev_b32_e32 v166, 1, v4
	v_mad_u64_u32 v[160:161], s[2:3], v4, s2, v[2:3]
	v_xor_b32_e32 v3, v166, v222
	v_bfi_b32 v3, -8, v160, v3
	v_cmp_lt_i32_e32 vcc, 15, v3
	v_add_u32_e32 v4, s8, v4
	s_and_saveexec_b64 s[2:3], vcc
	s_xor_b64 s[2:3], exec, s[2:3]
	v_mov_b32_e32 v5, 0xbfff80
	v_lshl_add_u32 v159, v4, 6, v5
	s_or_saveexec_b64 s[2:3], s[2:3]
	v_mov_b32_e32 v147, 0x1000
	s_xor_b64 exec, exec, s[2:3]
	v_lshl_or_b32 v4, v4, 11, s17
	v_add_u32_e32 v159, 0x8000000, v4
	v_mov_b32_e32 v147, 0x20000
	s_or_b64 exec, exec, s[2:3]
	v_add_u32_e32 v4, 0x400, v0
	s_mov_b32 s2, 0x2aaaaaab
	v_mul_hi_i32 v5, v4, s2
	v_lshrrev_b32_e32 v6, 31, v5
	v_ashrrev_i32_e32 v5, 2, v5
	v_add_u32_e32 v5, v5, v6
	s_movk_i32 s2, 0xffe8
	v_mad_u64_u32 v[162:163], s[2:3], v5, s2, v[4:5]
	v_lshrrev_b32_e32 v163, 1, v5
	v_xor_b32_e32 v4, v163, v222
	v_bfi_b32 v4, -8, v162, v4
	v_cmp_lt_i32_e32 vcc, 15, v4
	v_add_u32_e32 v5, s8, v5
	s_and_saveexec_b64 s[2:3], vcc
	s_xor_b64 s[2:3], exec, s[2:3]
	v_mov_b32_e32 v6, 0xbfff80
	v_lshl_add_u32 v161, v5, 6, v6
	s_or_saveexec_b64 s[2:3], s[2:3]
	v_mov_b32_e32 v149, 0x1000
	s_xor_b64 exec, exec, s[2:3]
	v_lshl_or_b32 v5, v5, 11, s17
	v_add_u32_e32 v161, 0x8000000, v5
	v_mov_b32_e32 v149, 0x20000
	s_or_b64 exec, exec, s[2:3]
	s_lshr_b32 s21, s12, 6
	s_or_b32 s15, s16, 0x1800
	s_lshl_b32 s22, s21, 5
	s_or_b32 s3, s8, s15
	s_add_u32 s19, s3, s22
	s_movk_i32 s2, 0x1800
	v_or_b32_e32 v5, s19, v194
	v_mov_b64_e32 v[6:7], s[4:5]
	s_addc_u32 s20, s9, 0
	v_mad_u64_u32 v[6:7], s[2:3], v5, s2, v[6:7]
	v_mov_b32_e32 v5, 0x1800
	s_mov_b32 s7, 0
	v_mad_i32_i24 v7, s20, v5, v7
	v_lshl_add_u32 v8, v1, 3, v155
	v_ashrrev_i32_e32 v1, 31, v0
	v_lshl_add_u64 v[6:7], v[6:7], 0, s[6:7]
	v_lshlrev_b32_e32 v156, 1, v181
	v_mov_b32_e32 v157, 0
	v_lshrrev_b32_e32 v10, 28, v1
	v_lshl_add_u64 v[6:7], v[6:7], 0, v[156:157]
	v_lshl_add_u32 v4, v4, 3, v161
	v_mov_b32_e32 v5, v157
	v_add_u32_e32 v16, v0, v10
	global_load_dwordx4 v[96:99], v[6:7], off
	global_load_dwordx4 v[100:103], v[6:7], off offset:32
	global_load_dwordx4 v[104:107], v[6:7], off offset:64
	global_load_dwordx4 v[108:111], v[6:7], off offset:96
	global_load_dwordx4 v[112:115], v[6:7], off offset:128
	global_load_dwordx4 v[116:119], v[6:7], off offset:160
	global_load_dwordx4 v[120:123], v[6:7], off offset:192
	global_load_dwordx4 v[124:127], v[6:7], off offset:224
	global_load_dwordx4 v[128:131], v[6:7], off offset:256
	global_load_dwordx4 v[132:135], v[6:7], off offset:288
	global_load_dwordx4 v[136:139], v[6:7], off offset:320
	global_load_dwordx4 v[140:143], v[6:7], off offset:352
	v_lshl_add_u32 v6, v3, 3, v159
	v_ashrrev_i32_e32 v3, 31, v2
	v_lshl_add_u64 v[14:15], v[4:5], 1, s[84:85]
	v_ashrrev_i32_e32 v167, 4, v16
	v_and_b32_e32 v5, 0x1ffffff0, v16
	v_lshrrev_b32_e32 v11, 28, v3
	v_mov_b32_e32 v9, v157
	s_lshl_b32 s2, s21, 10
	v_sub_u32_e32 v0, v0, v5
	v_lshlrev_b32_e32 v5, 2, v167
	v_mov_b32_e32 v7, v157
	v_add_u32_e32 v17, v2, v11
	v_lshl_add_u64 v[10:11], v[8:9], 1, s[84:85]
	v_bfe_u32 v9, v167, 2, 2
	s_add_i32 s7, s2, 0
	v_and_b32_e32 v5, 12, v5
	v_lshl_add_u64 v[12:13], v[6:7], 1, s[84:85]
	v_ashrrev_i32_e32 v168, 4, v17
	v_and_b32_e32 v7, 0x1ffffff0, v17
	v_bitop3_b32 v0, v5, v0, v9 bitop3:0x36
	s_mov_b32 m0, s7
	v_add_lshl_u32 v16, v167, s8, 11
	v_sub_u32_e32 v2, v2, v7
	v_lshlrev_b32_e32 v7, 2, v168
	global_load_lds_dwordx4 v[10:11], off
	s_add_i32 m0, s7, 0x2000
	v_lshlrev_b32_e32 v169, 3, v0
	v_mov_b32_e32 v1, v157
	v_bfe_u32 v17, v168, 2, 2
	v_and_b32_e32 v7, 12, v7
	global_load_lds_dwordx4 v[12:13], off
	s_add_i32 m0, s7, 0x4000
	v_add3_u32 v0, s18, v16, v169
	v_bitop3_b32 v2, v7, v2, v17 bitop3:0x36
	global_load_lds_dwordx4 v[14:15], off
	s_add_i32 m0, s7, 0x6000
	v_lshlrev_b32_e32 v10, 1, v0
	v_add_lshl_u32 v18, v168, s8, 11
	v_lshlrev_b32_e32 v198, 3, v2
	global_load_lds_dwordx4 v10, s[84:85]
	s_add_i32 m0, s7, 0x8000
	v_mov_b32_e32 v3, v157
	v_add3_u32 v2, s18, v18, v198
	s_cmpk_gt_u32 s12, 0xff
	v_lshlrev_b32_e32 v12, 1, v2
	s_cselect_b64 s[10:11], -1, 0
	s_cmpk_lt_u32 s12, 0x100
	v_add_u32_e32 v8, v8, v145
	v_mov_b32_e32 v9, v157
	global_load_lds_dwordx4 v12, s[84:85]
	s_cselect_b64 s[12:13], -1, 0
	s_add_i32 m0, s7, 0xa000
	v_lshl_add_u64 v[8:9], v[8:9], 1, s[84:85]
	v_add_u32_e32 v6, v6, v147
	v_mov_b32_e32 v7, v157
	s_waitcnt vmcnt(0) lgkmcnt(0)
	s_barrier
	s_waitcnt vmcnt(0)
	global_load_lds_dwordx4 v[8:9], off
	v_lshl_add_u64 v[6:7], v[6:7], 1, s[84:85]
	s_add_i32 m0, s7, 0xc000
	v_add_u32_e32 v4, v4, v149
	v_mov_b32_e32 v5, v157
	global_load_lds_dwordx4 v[6:7], off
	v_lshl_add_u64 v[4:5], v[4:5], 1, s[84:85]
	s_add_i32 m0, s7, 0xe000
	v_add_u32_e32 v0, 0x20000, v0
	v_mov_b32_e32 v1, v157
	global_load_lds_dwordx4 v[4:5], off
	s_add_i32 m0, s7, 0x10000
	v_lshl_add_u64 v[0:1], v[0:1], 1, s[84:85]
	global_load_lds_dwordx4 v[0:1], off
	v_add_u32_e32 v0, 0x20000, v2
	v_mov_b32_e32 v1, v157
	v_lshl_add_u64 v[0:1], v[0:1], 1, s[84:85]
	s_add_i32 m0, s7, 0x12000
	s_and_b64 vcc, exec, s[12:13]
	global_load_lds_dwordx4 v[0:1], off
	ds_read_b128 v[0:3], v190
	ds_read_b128 v[4:7], v191
	ds_read_b128 v[8:11], v192
	ds_read_b128 v[12:15], v193
	s_waitcnt lgkmcnt(3)
	v_mfma_f32_32x32x16_bf16 v[48:63], v[0:3], v[96:99], 0
	ds_read_b128 v[0:3], v190 offset:128
	s_waitcnt lgkmcnt(3)
	v_mfma_f32_32x32x16_bf16 v[48:63], v[4:7], v[100:103], v[48:63]
	ds_read_b128 v[4:7], v191 offset:128
	s_waitcnt lgkmcnt(3)
	v_mfma_f32_32x32x16_bf16 v[48:63], v[8:11], v[104:107], v[48:63]
	ds_read_b128 v[8:11], v192 offset:128
	s_waitcnt lgkmcnt(3)
	v_mfma_f32_32x32x16_bf16 v[48:63], v[12:15], v[108:111], v[48:63]
	ds_read_b128 v[12:15], v193 offset:128
	s_waitcnt lgkmcnt(3)
	v_mfma_f32_32x32x16_bf16 v[48:63], v[0:3], v[112:115], v[48:63]
	ds_read_b128 v[0:3], v190 offset:256
	s_waitcnt lgkmcnt(3)
	v_mfma_f32_32x32x16_bf16 v[48:63], v[4:7], v[116:119], v[48:63]
	ds_read_b128 v[4:7], v191 offset:256
	s_waitcnt lgkmcnt(3)
	v_mfma_f32_32x32x16_bf16 v[48:63], v[8:11], v[120:123], v[48:63]
	ds_read_b128 v[8:11], v192 offset:256
	s_waitcnt lgkmcnt(3)
	v_mfma_f32_32x32x16_bf16 v[48:63], v[12:15], v[124:127], v[48:63]
	ds_read_b128 v[12:15], v193 offset:256
	s_waitcnt lgkmcnt(3)
	v_mfma_f32_32x32x16_bf16 v[48:63], v[0:3], v[128:131], v[48:63]
	ds_read_b128 v[0:3], v190 offset:12288
	s_waitcnt lgkmcnt(3)
	v_mfma_f32_32x32x16_bf16 v[48:63], v[4:7], v[132:135], v[48:63]
	ds_read_b128 v[4:7], v191 offset:12288
	s_waitcnt lgkmcnt(3)
	v_mfma_f32_32x32x16_bf16 v[48:63], v[8:11], v[136:139], v[48:63]
	ds_read_b128 v[8:11], v192 offset:12288
	s_waitcnt lgkmcnt(2)
	v_mfma_f32_32x32x16_bf16 v[80:95], v[0:3], v[96:99], 0
	ds_read_b128 v[16:19], v193 offset:12288
	s_waitcnt lgkmcnt(2)
	v_mfma_f32_32x32x16_bf16 v[80:95], v[4:7], v[100:103], v[80:95]
	ds_read_b128 v[20:23], v190 offset:12416
	s_waitcnt lgkmcnt(2)
	v_mfma_f32_32x32x16_bf16 v[80:95], v[8:11], v[104:107], v[80:95]
	ds_read_b128 v[24:27], v191 offset:12416
	s_waitcnt lgkmcnt(2)
	v_mfma_f32_32x32x16_bf16 v[80:95], v[16:19], v[108:111], v[80:95]
	ds_read_b128 v[28:31], v192 offset:12416
	s_waitcnt lgkmcnt(2)
	v_mfma_f32_32x32x16_bf16 v[80:95], v[20:23], v[112:115], v[80:95]
	ds_read_b128 v[32:35], v193 offset:12416
	s_waitcnt lgkmcnt(2)
	v_mfma_f32_32x32x16_bf16 v[80:95], v[24:27], v[116:119], v[80:95]
	ds_read_b128 v[36:39], v190 offset:12544
	s_waitcnt lgkmcnt(2)
	v_mfma_f32_32x32x16_bf16 v[80:95], v[28:31], v[120:123], v[80:95]
	ds_read_b128 v[40:43], v191 offset:12544
	s_waitcnt lgkmcnt(2)
	v_mfma_f32_32x32x16_bf16 v[80:95], v[32:35], v[124:127], v[80:95]
	ds_read_b128 v[44:47], v192 offset:12544
	s_waitcnt lgkmcnt(2)
	v_mfma_f32_32x32x16_bf16 v[80:95], v[36:39], v[128:131], v[80:95]
	ds_read_b128 v[64:67], v193 offset:12544
	s_waitcnt lgkmcnt(2)
	v_mfma_f32_32x32x16_bf16 v[80:95], v[40:43], v[132:135], v[80:95]
	s_waitcnt lgkmcnt(1)
	v_mfma_f32_32x32x16_bf16 v[80:95], v[44:47], v[136:139], v[80:95]
	s_waitcnt lgkmcnt(0)
	v_mfma_f32_32x32x16_bf16 v[80:95], v[64:67], v[140:143], v[80:95]
	v_mfma_f32_32x32x16_bf16 v[48:63], v[12:15], v[140:143], v[48:63]
	s_cbranch_vccnz .LBB0_1843
	s_waitcnt vmcnt(0) lgkmcnt(0)
	s_barrier

.LBB0_1848:
	s_add_i32 s12, s7, s24
	v_lshlrev_b32_e32 v168, 1, v158
	s_mov_b32 m0, s12
	v_mov_b32_e32 v161, v159
	global_load_lds_dwordx4 v168, s[84:85]
	v_lshlrev_b32_e32 v168, 1, v160
	s_add_i32 m0, s12, 0x2000
	v_mov_b32_e32 v163, v159
	global_load_lds_dwordx4 v168, s[84:85]
	v_lshlrev_b32_e32 v168, 1, v162
	s_add_i32 m0, s12, 0x4000
	v_mov_b32_e32 v167, v159
	global_load_lds_dwordx4 v168, s[84:85]
	s_add_i32 m0, s12, 0x6000
	v_lshlrev_b32_e32 v168, 1, v166
	v_mov_b32_e32 v165, v159
	global_load_lds_dwordx4 v168, s[84:85]
	v_lshlrev_b32_e32 v168, 1, v164
	s_add_i32 m0, s12, 0x8000
	s_nop 0
	global_load_lds_dwordx4 v168, s[84:85]

.LBB0_1863:
	s_setprio 0
	v_mov_b32_e32 v48, v157
	s_nop 1
	v_permlane32_swap_b32_e32 v157, v48
	v_add_f32_e32 v48, v157, v48
	v_div_scale_f32 v49, s[2:3], v48, v48, 1.0
	v_rcp_f32_e32 v50, v49
	s_mulk_i32 s21, 0x2200
	s_add_i32 s7, s21, 0
	s_waitcnt vmcnt(0) lgkmcnt(0)
	s_barrier
	v_fma_f32 v51, -v49, v50, 1.0
	v_fmac_f32_e32 v50, v51, v50
	v_div_scale_f32 v51, vcc, 1.0, v48, 1.0
	v_mul_f32_e32 v52, v51, v50
	v_fma_f32 v53, -v49, v52, v51
	v_fmac_f32_e32 v52, v53, v50
	v_fma_f32 v49, -v49, v52, v51
	v_div_fmas_f32 v49, v49, v50, v52
	v_div_fixup_f32 v48, v49, v48, 1.0
	v_add3_u32 v49, s7, v195, v181
	v_pk_mul_f32 v[50:51], v[64:65], v[48:49] op_sel_hi:[1,0]
	v_pk_mul_f32 v[52:53], v[66:67], v[48:49] op_sel_hi:[1,0]
	v_cvt_pk_bf16_f32 v50, v50, v51
	v_cvt_pk_bf16_f32 v51, v52, v53
	v_pk_mul_f32 v[52:53], v[68:69], v[48:49] op_sel_hi:[1,0]
	v_pk_mul_f32 v[54:55], v[70:71], v[48:49] op_sel_hi:[1,0]
	v_add_u32_e32 v49, 0xa000, v49
	v_pk_mul_f32 v[32:33], v[32:33], v[48:49] op_sel_hi:[1,0]
	v_pk_mul_f32 v[34:35], v[34:35], v[48:49] op_sel_hi:[1,0]
	v_pk_mul_f32 v[16:17], v[16:17], v[48:49] op_sel_hi:[1,0]
	v_pk_mul_f32 v[18:19], v[18:19], v[48:49] op_sel_hi:[1,0]
	v_pk_mul_f32 v[0:1], v[0:1], v[48:49] op_sel_hi:[1,0]
	v_pk_mul_f32 v[2:3], v[2:3], v[48:49] op_sel_hi:[1,0]
	v_cvt_pk_bf16_f32 v32, v32, v33
	v_cvt_pk_bf16_f32 v33, v34, v35
	v_pk_mul_f32 v[34:35], v[36:37], v[48:49] op_sel_hi:[1,0]
	v_pk_mul_f32 v[36:37], v[38:39], v[48:49] op_sel_hi:[1,0]
	v_cvt_pk_bf16_f32 v16, v16, v17
	v_cvt_pk_bf16_f32 v17, v18, v19
	v_pk_mul_f32 v[18:19], v[20:21], v[48:49] op_sel_hi:[1,0]
	v_pk_mul_f32 v[20:21], v[22:23], v[48:49] op_sel_hi:[1,0]
	v_cvt_pk_bf16_f32 v0, v0, v1
	v_cvt_pk_bf16_f32 v1, v2, v3
	v_pk_mul_f32 v[2:3], v[4:5], v[48:49] op_sel_hi:[1,0]
	v_pk_mul_f32 v[4:5], v[6:7], v[48:49] op_sel_hi:[1,0]
	v_cvt_pk_bf16_f32 v52, v52, v53
	v_cvt_pk_bf16_f32 v53, v54, v55
	v_cvt_pk_bf16_f32 v34, v34, v35
	v_cvt_pk_bf16_f32 v35, v36, v37
	v_cvt_pk_bf16_f32 v18, v18, v19
	v_cvt_pk_bf16_f32 v19, v20, v21
	v_cvt_pk_bf16_f32 v2, v2, v3
	v_cvt_pk_bf16_f32 v3, v4, v5
	ds_write2_b64 v49, v[50:51], v[52:53] offset1:2
	v_pk_mul_f32 v[50:51], v[72:73], v[48:49] op_sel_hi:[1,0]
	v_pk_mul_f32 v[52:53], v[74:75], v[48:49] op_sel_hi:[1,0]
	ds_write2_b64 v49, v[32:33], v[34:35] offset0:8 offset1:10
	v_pk_mul_f32 v[32:33], v[40:41], v[48:49] op_sel_hi:[1,0]
	v_pk_mul_f32 v[34:35], v[42:43], v[48:49] op_sel_hi:[1,0]
	ds_write2_b64 v49, v[16:17], v[18:19] offset0:16 offset1:18
	v_pk_mul_f32 v[16:17], v[24:25], v[48:49] op_sel_hi:[1,0]
	v_pk_mul_f32 v[18:19], v[26:27], v[48:49] op_sel_hi:[1,0]
	ds_write2_b64 v49, v[0:1], v[2:3] offset0:24 offset1:26
	v_pk_mul_f32 v[0:1], v[8:9], v[48:49] op_sel_hi:[1,0]
	v_pk_mul_f32 v[2:3], v[10:11], v[48:49] op_sel_hi:[1,0]
	v_cvt_pk_bf16_f32 v50, v50, v51
	v_cvt_pk_bf16_f32 v51, v52, v53
	v_pk_mul_f32 v[52:53], v[76:77], v[48:49] op_sel_hi:[1,0]
	v_pk_mul_f32 v[54:55], v[78:79], v[48:49] op_sel_hi:[1,0]
	v_cvt_pk_bf16_f32 v32, v32, v33
	v_cvt_pk_bf16_f32 v33, v34, v35
	v_pk_mul_f32 v[34:35], v[44:45], v[48:49] op_sel_hi:[1,0]
	v_pk_mul_f32 v[36:37], v[46:47], v[48:49] op_sel_hi:[1,0]
	v_cvt_pk_bf16_f32 v16, v16, v17
	v_cvt_pk_bf16_f32 v17, v18, v19
	v_pk_mul_f32 v[18:19], v[28:29], v[48:49] op_sel_hi:[1,0]
	v_pk_mul_f32 v[20:21], v[30:31], v[48:49] op_sel_hi:[1,0]
	v_cvt_pk_bf16_f32 v0, v0, v1
	v_cvt_pk_bf16_f32 v1, v2, v3
	v_pk_mul_f32 v[2:3], v[12:13], v[48:49] op_sel_hi:[1,0]
	v_pk_mul_f32 v[4:5], v[14:15], v[48:49] op_sel_hi:[1,0]
	v_cvt_pk_bf16_f32 v52, v52, v53
	v_cvt_pk_bf16_f32 v53, v54, v55
	v_cvt_pk_bf16_f32 v34, v34, v35
	v_cvt_pk_bf16_f32 v35, v36, v37
	v_cvt_pk_bf16_f32 v18, v18, v19
	v_cvt_pk_bf16_f32 v19, v20, v21
	v_cvt_pk_bf16_f32 v2, v2, v3
	v_cvt_pk_bf16_f32 v3, v4, v5
	s_mulk_i32 s20, 0x1800
	s_mul_hi_u32 s2, s19, 0x1800
	ds_write2_b64 v49, v[50:51], v[52:53] offset0:4 offset1:6
	ds_write2_b64 v49, v[32:33], v[34:35] offset0:12 offset1:14
	ds_write2_b64 v49, v[16:17], v[18:19] offset0:20 offset1:22
	ds_write2_b64 v49, v[0:1], v[2:3] offset0:28 offset1:30
	s_add_i32 s2, s2, s20
	s_mulk_i32 s19, 0x1800
	s_nop 0
	s_add_u32 s3, s4, s19
	v_add3_u32 v14, s7, v144, v196
	s_addc_u32 s10, s5, s2
	ds_read_b128 v[0:3], v14 offset:40960
	s_add_u32 s2, s3, s6
	s_addc_u32 s3, s10, 0
	v_lshlrev_b32_e32 v158, 1, v153
	v_mov_b32_e32 v159, 0
	ds_read_b128 v[4:7], v14 offset:42048
	v_lshl_add_u64 v[8:9], s[2:3], 0, v[158:159]
	v_mov_b32_e32 v147, v159
	v_lshl_add_u64 v[10:11], v[8:9], 0, v[146:147]
	s_movk_i32 s2, 0x6000
	s_waitcnt lgkmcnt(1)
	global_store_dwordx4 v[10:11], v[0:3], off
	v_mov_b32_e32 v149, v159
	v_mov_b32_e32 v153, v159
	v_add_co_u32_e32 v0, vcc, s2, v10
	s_mov_b32 s2, 0xc000
	s_nop 0
	v_addc_co_u32_e32 v1, vcc, 0, v11, vcc
	s_waitcnt lgkmcnt(0)
	global_store_dwordx4 v[0:1], v[4:7], off
	ds_read_b128 v[0:3], v14 offset:43136
	ds_read_b128 v[4:7], v14 offset:44224
	v_add_co_u32_e32 v12, vcc, s2, v10
	s_mov_b32 s2, 0x12000
	s_nop 0
	v_addc_co_u32_e32 v13, vcc, 0, v11, vcc
	v_add_co_u32_e32 v10, vcc, s2, v10
	s_waitcnt lgkmcnt(1)
	global_store_dwordx4 v[12:13], v[0:3], off
	v_addc_co_u32_e32 v11, vcc, 0, v11, vcc
	ds_read_b128 v[0:3], v14 offset:45312
	s_waitcnt lgkmcnt(1)
	global_store_dwordx4 v[10:11], v[4:7], off
	ds_read_b128 v[4:7], v14 offset:46400
	v_lshl_add_u64 v[10:11], v[8:9], 0, v[148:149]
	v_mov_b32_e32 v151, v159
	s_waitcnt lgkmcnt(1)
	global_store_dwordx4 v[10:11], v[0:3], off
	v_lshl_add_u64 v[10:11], v[8:9], 0, v[152:153]
	ds_read_b128 v[0:3], v14 offset:47488
	s_waitcnt lgkmcnt(1)
	global_store_dwordx4 v[10:11], v[4:7], off
	ds_read_b128 v[4:7], v14 offset:48576
	v_lshl_add_u64 v[10:11], v[8:9], 0, v[150:151]
	v_mov_b32_e32 v155, v159
	v_readfirstlane_b32 s12, v222
	s_waitcnt lgkmcnt(1)
	global_store_dwordx4 v[10:11], v[0:3], off
	s_and_b32 s2, s12, 0xffffffc0
	s_nop 0
	v_lshl_add_u64 v[0:1], v[8:9], 0, v[154:155]
	s_waitcnt lgkmcnt(0)
	global_store_dwordx4 v[0:1], v[4:7], off
	v_or_b32_e32 v0, s2, v197
	s_mov_b32 s2, 0x2aaaaaab
	v_mul_hi_i32 v1, v0, s2
	v_lshrrev_b32_e32 v2, 31, v1
	v_ashrrev_i32_e32 v1, 2, v1
	v_add_u32_e32 v2, v1, v2
	s_movk_i32 s2, 0xffe8
	v_lshrrev_b32_e32 v159, 1, v2
	v_mad_u64_u32 v[160:161], s[2:3], v2, s2, v[0:1]
	v_xor_b32_e32 v1, v159, v222
	v_bfi_b32 v1, -8, v160, v1
	v_cmp_lt_i32_e32 vcc, 15, v1
	v_add_u32_e32 v2, s8, v2
	s_and_saveexec_b64 s[2:3], vcc
	s_xor_b64 s[2:3], exec, s[2:3]
	v_mov_b32_e32 v3, 0xbfff80
	v_lshl_add_u32 v153, v2, 6, v3
	s_or_saveexec_b64 s[2:3], s[2:3]
	v_mov_b32_e32 v145, 0x1000
	s_xor_b64 exec, exec, s[2:3]
	v_lshl_or_b32 v2, v2, 11, s17
	v_add_u32_e32 v153, 0x8000000, v2
	v_mov_b32_e32 v145, 0x20000
	s_or_b64 exec, exec, s[2:3]
	v_add_u32_e32 v2, 0x200, v0
	s_mov_b32 s2, 0x2aaaaaab
	v_mul_hi_i32 v3, v2, s2
	v_lshrrev_b32_e32 v4, 31, v3
	v_ashrrev_i32_e32 v3, 2, v3
	v_add_u32_e32 v4, v3, v4
	s_movk_i32 s2, 0xffe8
	v_mad_u64_u32 v[162:163], s[2:3], v4, s2, v[2:3]
	v_lshrrev_b32_e32 v163, 1, v4
	v_xor_b32_e32 v3, v163, v222
	v_bfi_b32 v3, -8, v162, v3
	v_cmp_lt_i32_e32 vcc, 15, v3
	v_add_u32_e32 v4, s8, v4
	s_and_saveexec_b64 s[2:3], vcc
	s_xor_b64 s[2:3], exec, s[2:3]
	v_mov_b32_e32 v5, 0xbfff80
	v_lshl_add_u32 v155, v4, 6, v5
	s_or_saveexec_b64 s[2:3], s[2:3]
	v_mov_b32_e32 v147, 0x1000
	s_xor_b64 exec, exec, s[2:3]
	v_lshl_or_b32 v4, v4, 11, s17
	v_add_u32_e32 v155, 0x8000000, v4
	v_mov_b32_e32 v147, 0x20000
	s_or_b64 exec, exec, s[2:3]
	v_add_u32_e32 v4, 0x400, v0
	s_mov_b32 s2, 0x2aaaaaab
	v_mul_hi_i32 v5, v4, s2
	v_lshrrev_b32_e32 v6, 31, v5
	v_ashrrev_i32_e32 v5, 2, v5
	v_add_u32_e32 v5, v5, v6
	s_movk_i32 s2, 0xffe8
	v_mad_u64_u32 v[164:165], s[2:3], v5, s2, v[4:5]
	v_lshrrev_b32_e32 v165, 1, v5
	v_xor_b32_e32 v4, v165, v222
	v_bfi_b32 v4, -8, v164, v4
	v_cmp_lt_i32_e32 vcc, 15, v4
	v_add_u32_e32 v5, s8, v5
	s_and_saveexec_b64 s[2:3], vcc
	s_xor_b64 s[2:3], exec, s[2:3]
	v_mov_b32_e32 v6, 0xbfff80
	v_lshl_add_u32 v161, v5, 6, v6
	s_or_saveexec_b64 s[2:3], s[2:3]
	v_mov_b32_e32 v149, 0x1000
	s_xor_b64 exec, exec, s[2:3]
	v_lshl_or_b32 v5, v5, 11, s17
	v_add_u32_e32 v161, 0x8000000, v5
	v_mov_b32_e32 v149, 0x20000
	s_or_b64 exec, exec, s[2:3]
	s_lshr_b32 s21, s12, 6
	s_xor_b32 s22, s16, 0x1700
	s_lshl_b32 s23, s21, 5
	s_or_b32 s2, s8, s22
	s_add_u32 s19, s2, s23
	v_or_b32_e32 v5, s19, v194
	s_movk_i32 s2, 0x1800
	v_mov_b64_e32 v[6:7], s[4:5]
	s_addc_u32 s20, s9, 0
	v_mad_u64_u32 v[6:7], s[2:3], v5, s2, v[6:7]
	v_mov_b32_e32 v5, 0x1800
	s_mov_b32 s7, 0
	v_mad_i32_i24 v7, s20, v5, v7
	v_lshl_add_u32 v8, v1, 3, v153
	v_ashrrev_i32_e32 v1, 31, v0
	v_lshl_add_u64 v[6:7], v[6:7], 0, s[6:7]
	v_mov_b32_e32 v157, 0
	v_lshrrev_b32_e32 v10, 28, v1
	v_lshl_add_u64 v[6:7], v[6:7], 0, v[156:157]
	v_lshl_add_u32 v4, v4, 3, v161
	v_mov_b32_e32 v5, v157
	v_add_u32_e32 v16, v0, v10
	global_load_dwordx4 v[96:99], v[6:7], off
	global_load_dwordx4 v[100:103], v[6:7], off offset:32
	global_load_dwordx4 v[104:107], v[6:7], off offset:64
	global_load_dwordx4 v[108:111], v[6:7], off offset:96
	global_load_dwordx4 v[112:115], v[6:7], off offset:128
	global_load_dwordx4 v[116:119], v[6:7], off offset:160
	global_load_dwordx4 v[120:123], v[6:7], off offset:192
	global_load_dwordx4 v[124:127], v[6:7], off offset:224
	global_load_dwordx4 v[128:131], v[6:7], off offset:256
	global_load_dwordx4 v[132:135], v[6:7], off offset:288
	global_load_dwordx4 v[136:139], v[6:7], off offset:320
	global_load_dwordx4 v[140:143], v[6:7], off offset:352
	v_lshl_add_u32 v6, v3, 3, v155
	v_ashrrev_i32_e32 v3, 31, v2
	v_lshl_add_u64 v[14:15], v[4:5], 1, s[84:85]
	v_ashrrev_i32_e32 v167, 4, v16
	v_and_b32_e32 v5, 0x1ffffff0, v16
	v_lshrrev_b32_e32 v11, 28, v3
	v_mov_b32_e32 v9, v157
	s_lshl_b32 s2, s21, 10
	v_sub_u32_e32 v0, v0, v5
	v_lshlrev_b32_e32 v5, 2, v167
	v_mov_b32_e32 v7, v157
	v_add_u32_e32 v17, v2, v11
	v_lshl_add_u64 v[10:11], v[8:9], 1, s[84:85]
	v_bfe_u32 v9, v167, 2, 2
	s_add_i32 s7, s2, 0
	v_and_b32_e32 v5, 12, v5
	v_lshl_add_u64 v[12:13], v[6:7], 1, s[84:85]
	v_ashrrev_i32_e32 v166, 4, v17
	v_and_b32_e32 v7, 0x1ffffff0, v17
	v_bitop3_b32 v0, v5, v0, v9 bitop3:0x36
	s_mov_b32 m0, s7
	v_add_lshl_u32 v16, v167, s8, 11
	v_sub_u32_e32 v2, v2, v7
	v_lshlrev_b32_e32 v7, 2, v166
	global_load_lds_dwordx4 v[10:11], off
	s_add_i32 m0, s7, 0x2000
	v_lshlrev_b32_e32 v168, 3, v0
	v_mov_b32_e32 v1, v157
	v_bfe_u32 v17, v166, 2, 2
	v_and_b32_e32 v7, 12, v7
	global_load_lds_dwordx4 v[12:13], off
	s_add_i32 m0, s7, 0x4000
	v_add3_u32 v0, s18, v16, v168
	v_bitop3_b32 v2, v7, v2, v17 bitop3:0x36
	global_load_lds_dwordx4 v[14:15], off
	s_add_i32 m0, s7, 0x6000
	v_lshlrev_b32_e32 v10, 1, v0
	v_add_lshl_u32 v18, v166, s8, 11
	v_lshlrev_b32_e32 v169, 3, v2
	global_load_lds_dwordx4 v10, s[84:85]
	s_add_i32 m0, s7, 0x8000
	v_mov_b32_e32 v3, v157
	v_add3_u32 v2, s18, v18, v169
	s_cmpk_gt_u32 s12, 0xff
	v_lshlrev_b32_e32 v12, 1, v2
	s_cselect_b64 s[10:11], -1, 0
	s_cmpk_lt_u32 s12, 0x100
	v_add_u32_e32 v8, v8, v145
	v_mov_b32_e32 v9, v157
	global_load_lds_dwordx4 v12, s[84:85]
	s_cselect_b64 s[12:13], -1, 0
	s_add_i32 m0, s7, 0xa000
	v_lshl_add_u64 v[8:9], v[8:9], 1, s[84:85]
	v_add_u32_e32 v6, v6, v147
	v_mov_b32_e32 v7, v157
	s_waitcnt vmcnt(0) lgkmcnt(0)
	s_barrier
	s_waitcnt vmcnt(0)
	global_load_lds_dwordx4 v[8:9], off
	v_lshl_add_u64 v[6:7], v[6:7], 1, s[84:85]
	s_add_i32 m0, s7, 0xc000
	v_add_u32_e32 v4, v4, v149
	v_mov_b32_e32 v5, v157
	global_load_lds_dwordx4 v[6:7], off
	v_lshl_add_u64 v[4:5], v[4:5], 1, s[84:85]
	s_add_i32 m0, s7, 0xe000
	v_add_u32_e32 v0, 0x20000, v0
	v_mov_b32_e32 v1, v157
	global_load_lds_dwordx4 v[4:5], off
	s_add_i32 m0, s7, 0x10000
	v_lshl_add_u64 v[0:1], v[0:1], 1, s[84:85]
	global_load_lds_dwordx4 v[0:1], off
	v_add_u32_e32 v0, 0x20000, v2
	v_mov_b32_e32 v1, v157
	v_lshl_add_u64 v[0:1], v[0:1], 1, s[84:85]
	s_add_i32 m0, s7, 0x12000
	s_and_b64 vcc, exec, s[12:13]
	global_load_lds_dwordx4 v[0:1], off
	ds_read_b128 v[0:3], v190
	ds_read_b128 v[4:7], v191
	ds_read_b128 v[8:11], v192
	ds_read_b128 v[12:15], v193
	s_waitcnt lgkmcnt(3)
	v_mfma_f32_32x32x16_bf16 v[48:63], v[0:3], v[96:99], 0
	ds_read_b128 v[0:3], v190 offset:128
	s_waitcnt lgkmcnt(3)
	v_mfma_f32_32x32x16_bf16 v[48:63], v[4:7], v[100:103], v[48:63]
	ds_read_b128 v[4:7], v191 offset:128
	s_waitcnt lgkmcnt(3)
	v_mfma_f32_32x32x16_bf16 v[48:63], v[8:11], v[104:107], v[48:63]
	ds_read_b128 v[8:11], v192 offset:128
	s_waitcnt lgkmcnt(3)
	v_mfma_f32_32x32x16_bf16 v[48:63], v[12:15], v[108:111], v[48:63]
	ds_read_b128 v[12:15], v193 offset:128
	s_waitcnt lgkmcnt(3)
	v_mfma_f32_32x32x16_bf16 v[48:63], v[0:3], v[112:115], v[48:63]
	ds_read_b128 v[0:3], v190 offset:256
	s_waitcnt lgkmcnt(3)
	v_mfma_f32_32x32x16_bf16 v[48:63], v[4:7], v[116:119], v[48:63]
	ds_read_b128 v[4:7], v191 offset:256
	s_waitcnt lgkmcnt(3)
	v_mfma_f32_32x32x16_bf16 v[48:63], v[8:11], v[120:123], v[48:63]
	ds_read_b128 v[8:11], v192 offset:256
	s_waitcnt lgkmcnt(3)
	v_mfma_f32_32x32x16_bf16 v[48:63], v[12:15], v[124:127], v[48:63]
	ds_read_b128 v[12:15], v193 offset:256
	s_waitcnt lgkmcnt(3)
	v_mfma_f32_32x32x16_bf16 v[48:63], v[0:3], v[128:131], v[48:63]
	ds_read_b128 v[0:3], v190 offset:12288
	s_waitcnt lgkmcnt(3)
	v_mfma_f32_32x32x16_bf16 v[48:63], v[4:7], v[132:135], v[48:63]
	ds_read_b128 v[4:7], v191 offset:12288
	s_waitcnt lgkmcnt(3)
	v_mfma_f32_32x32x16_bf16 v[48:63], v[8:11], v[136:139], v[48:63]
	ds_read_b128 v[8:11], v192 offset:12288
	s_waitcnt lgkmcnt(2)
	v_mfma_f32_32x32x16_bf16 v[80:95], v[0:3], v[96:99], 0
	ds_read_b128 v[16:19], v193 offset:12288
	s_waitcnt lgkmcnt(2)
	v_mfma_f32_32x32x16_bf16 v[80:95], v[4:7], v[100:103], v[80:95]
	ds_read_b128 v[20:23], v190 offset:12416
	s_waitcnt lgkmcnt(2)
	v_mfma_f32_32x32x16_bf16 v[80:95], v[8:11], v[104:107], v[80:95]
	ds_read_b128 v[24:27], v191 offset:12416
	s_waitcnt lgkmcnt(2)
	v_mfma_f32_32x32x16_bf16 v[80:95], v[16:19], v[108:111], v[80:95]
	ds_read_b128 v[28:31], v192 offset:12416
	s_waitcnt lgkmcnt(2)
	v_mfma_f32_32x32x16_bf16 v[80:95], v[20:23], v[112:115], v[80:95]
	ds_read_b128 v[32:35], v193 offset:12416
	s_waitcnt lgkmcnt(2)
	v_mfma_f32_32x32x16_bf16 v[80:95], v[24:27], v[116:119], v[80:95]
	ds_read_b128 v[36:39], v190 offset:12544
	s_waitcnt lgkmcnt(2)
	v_mfma_f32_32x32x16_bf16 v[80:95], v[28:31], v[120:123], v[80:95]
	ds_read_b128 v[40:43], v191 offset:12544
	s_waitcnt lgkmcnt(2)
	v_mfma_f32_32x32x16_bf16 v[80:95], v[32:35], v[124:127], v[80:95]
	ds_read_b128 v[44:47], v192 offset:12544
	s_waitcnt lgkmcnt(2)
	v_mfma_f32_32x32x16_bf16 v[80:95], v[36:39], v[128:131], v[80:95]
	ds_read_b128 v[64:67], v193 offset:12544
	s_waitcnt lgkmcnt(2)
	v_mfma_f32_32x32x16_bf16 v[80:95], v[40:43], v[132:135], v[80:95]
	s_waitcnt lgkmcnt(1)
	v_mfma_f32_32x32x16_bf16 v[80:95], v[44:47], v[136:139], v[80:95]
	s_waitcnt lgkmcnt(0)
	v_mfma_f32_32x32x16_bf16 v[80:95], v[64:67], v[140:143], v[80:95]
	v_mfma_f32_32x32x16_bf16 v[48:63], v[12:15], v[140:143], v[48:63]
	s_cbranch_vccnz .LBB0_1877
	s_waitcnt vmcnt(0) lgkmcnt(0)
	s_barrier

.LBB0_1882:
	s_add_i32 s12, s7, s24
	v_lshlrev_b32_e32 v198, 1, v160
	s_mov_b32 m0, s12
	v_mov_b32_e32 v163, v161
	global_load_lds_dwordx4 v198, s[84:85]
	v_lshlrev_b32_e32 v198, 1, v162
	s_add_i32 m0, s12, 0x2000
	v_mov_b32_e32 v165, v161
	global_load_lds_dwordx4 v198, s[84:85]
	v_lshlrev_b32_e32 v198, 1, v164
	s_add_i32 m0, s12, 0x4000
	v_mov_b32_e32 v169, v161
	global_load_lds_dwordx4 v198, s[84:85]
	s_add_i32 m0, s12, 0x6000
	v_lshlrev_b32_e32 v198, 1, v168
	v_mov_b32_e32 v167, v161
	global_load_lds_dwordx4 v198, s[84:85]
	v_lshlrev_b32_e32 v198, 1, v166
	s_add_i32 m0, s12, 0x8000
	s_nop 0
	global_load_lds_dwordx4 v198, s[84:85]

.LBB0_1897:
	s_setprio 0
	v_mov_b32_e32 v48, v157
	s_nop 1
	v_permlane32_swap_b32_e32 v157, v48
	v_add_f32_e32 v48, v157, v48
	v_div_scale_f32 v49, s[2:3], v48, v48, 1.0
	v_rcp_f32_e32 v50, v49
	s_mulk_i32 s21, 0x2200
	s_add_i32 s7, s21, 0
	s_waitcnt vmcnt(0) lgkmcnt(0)
	s_barrier
	v_fma_f32 v51, -v49, v50, 1.0
	v_fmac_f32_e32 v50, v51, v50
	v_div_scale_f32 v51, vcc, 1.0, v48, 1.0
	v_mul_f32_e32 v52, v51, v50
	v_fma_f32 v53, -v49, v52, v51
	v_fmac_f32_e32 v52, v53, v50
	v_fma_f32 v49, -v49, v52, v51
	v_div_fmas_f32 v49, v49, v50, v52
	v_div_fixup_f32 v48, v49, v48, 1.0
	v_add3_u32 v49, s7, v195, v181
	v_pk_mul_f32 v[50:51], v[64:65], v[48:49] op_sel_hi:[1,0]
	v_pk_mul_f32 v[52:53], v[66:67], v[48:49] op_sel_hi:[1,0]
	v_cvt_pk_bf16_f32 v50, v50, v51
	v_cvt_pk_bf16_f32 v51, v52, v53
	v_pk_mul_f32 v[52:53], v[68:69], v[48:49] op_sel_hi:[1,0]
	v_pk_mul_f32 v[54:55], v[70:71], v[48:49] op_sel_hi:[1,0]
	v_add_u32_e32 v49, 0xa000, v49
	v_pk_mul_f32 v[32:33], v[32:33], v[48:49] op_sel_hi:[1,0]
	v_pk_mul_f32 v[34:35], v[34:35], v[48:49] op_sel_hi:[1,0]
	v_pk_mul_f32 v[16:17], v[16:17], v[48:49] op_sel_hi:[1,0]
	v_pk_mul_f32 v[18:19], v[18:19], v[48:49] op_sel_hi:[1,0]
	v_pk_mul_f32 v[0:1], v[0:1], v[48:49] op_sel_hi:[1,0]
	v_pk_mul_f32 v[2:3], v[2:3], v[48:49] op_sel_hi:[1,0]
	v_cvt_pk_bf16_f32 v32, v32, v33
	v_cvt_pk_bf16_f32 v33, v34, v35
	v_pk_mul_f32 v[34:35], v[36:37], v[48:49] op_sel_hi:[1,0]
	v_pk_mul_f32 v[36:37], v[38:39], v[48:49] op_sel_hi:[1,0]
	v_cvt_pk_bf16_f32 v16, v16, v17
	v_cvt_pk_bf16_f32 v17, v18, v19
	v_pk_mul_f32 v[18:19], v[20:21], v[48:49] op_sel_hi:[1,0]
	v_pk_mul_f32 v[20:21], v[22:23], v[48:49] op_sel_hi:[1,0]
	v_cvt_pk_bf16_f32 v0, v0, v1
	v_cvt_pk_bf16_f32 v1, v2, v3
	v_pk_mul_f32 v[2:3], v[4:5], v[48:49] op_sel_hi:[1,0]
	v_pk_mul_f32 v[4:5], v[6:7], v[48:49] op_sel_hi:[1,0]
	v_cvt_pk_bf16_f32 v52, v52, v53
	v_cvt_pk_bf16_f32 v53, v54, v55
	v_cvt_pk_bf16_f32 v34, v34, v35
	v_cvt_pk_bf16_f32 v35, v36, v37
	v_cvt_pk_bf16_f32 v18, v18, v19
	v_cvt_pk_bf16_f32 v19, v20, v21
	v_cvt_pk_bf16_f32 v2, v2, v3
	v_cvt_pk_bf16_f32 v3, v4, v5
	ds_write2_b64 v49, v[50:51], v[52:53] offset1:2
	v_pk_mul_f32 v[50:51], v[72:73], v[48:49] op_sel_hi:[1,0]
	v_pk_mul_f32 v[52:53], v[74:75], v[48:49] op_sel_hi:[1,0]
	ds_write2_b64 v49, v[32:33], v[34:35] offset0:8 offset1:10
	v_pk_mul_f32 v[32:33], v[40:41], v[48:49] op_sel_hi:[1,0]
	v_pk_mul_f32 v[34:35], v[42:43], v[48:49] op_sel_hi:[1,0]
	ds_write2_b64 v49, v[16:17], v[18:19] offset0:16 offset1:18
	v_pk_mul_f32 v[16:17], v[24:25], v[48:49] op_sel_hi:[1,0]
	v_pk_mul_f32 v[18:19], v[26:27], v[48:49] op_sel_hi:[1,0]
	ds_write2_b64 v49, v[0:1], v[2:3] offset0:24 offset1:26
	v_pk_mul_f32 v[0:1], v[8:9], v[48:49] op_sel_hi:[1,0]
	v_pk_mul_f32 v[2:3], v[10:11], v[48:49] op_sel_hi:[1,0]
	v_cvt_pk_bf16_f32 v50, v50, v51
	v_cvt_pk_bf16_f32 v51, v52, v53
	v_pk_mul_f32 v[52:53], v[76:77], v[48:49] op_sel_hi:[1,0]
	v_pk_mul_f32 v[54:55], v[78:79], v[48:49] op_sel_hi:[1,0]
	v_cvt_pk_bf16_f32 v32, v32, v33
	v_cvt_pk_bf16_f32 v33, v34, v35
	v_pk_mul_f32 v[34:35], v[44:45], v[48:49] op_sel_hi:[1,0]
	v_pk_mul_f32 v[36:37], v[46:47], v[48:49] op_sel_hi:[1,0]
	v_cvt_pk_bf16_f32 v16, v16, v17
	v_cvt_pk_bf16_f32 v17, v18, v19
	v_pk_mul_f32 v[18:19], v[28:29], v[48:49] op_sel_hi:[1,0]
	v_pk_mul_f32 v[20:21], v[30:31], v[48:49] op_sel_hi:[1,0]
	v_cvt_pk_bf16_f32 v0, v0, v1
	v_cvt_pk_bf16_f32 v1, v2, v3
	v_pk_mul_f32 v[2:3], v[12:13], v[48:49] op_sel_hi:[1,0]
	v_pk_mul_f32 v[4:5], v[14:15], v[48:49] op_sel_hi:[1,0]
	v_cvt_pk_bf16_f32 v52, v52, v53
	v_cvt_pk_bf16_f32 v53, v54, v55
	v_cvt_pk_bf16_f32 v34, v34, v35
	v_cvt_pk_bf16_f32 v35, v36, v37
	v_cvt_pk_bf16_f32 v18, v18, v19
	v_cvt_pk_bf16_f32 v19, v20, v21
	v_cvt_pk_bf16_f32 v2, v2, v3
	v_cvt_pk_bf16_f32 v3, v4, v5
	s_mulk_i32 s20, 0x1800
	s_mul_hi_u32 s2, s19, 0x1800
	ds_write2_b64 v49, v[50:51], v[52:53] offset0:4 offset1:6
	ds_write2_b64 v49, v[32:33], v[34:35] offset0:12 offset1:14
	ds_write2_b64 v49, v[16:17], v[18:19] offset0:20 offset1:22
	ds_write2_b64 v49, v[0:1], v[2:3] offset0:28 offset1:30
	s_add_i32 s2, s2, s20
	s_mulk_i32 s19, 0x1800
	s_nop 0
	s_add_u32 s3, s4, s19
	v_add3_u32 v14, s7, v144, v196
	s_addc_u32 s10, s5, s2
	ds_read_b128 v[0:3], v14 offset:40960
	s_add_u32 s2, s3, s6
	s_addc_u32 s3, s10, 0
	v_mov_b32_e32 v159, 0
	ds_read_b128 v[4:7], v14 offset:42048
	v_lshl_add_u64 v[8:9], s[2:3], 0, v[158:159]
	v_mov_b32_e32 v147, v159
	v_lshl_add_u64 v[10:11], v[8:9], 0, v[146:147]
	s_movk_i32 s2, 0x6000
	s_waitcnt lgkmcnt(1)
	global_store_dwordx4 v[10:11], v[0:3], off
	v_mov_b32_e32 v149, v159
	v_mov_b32_e32 v153, v159
	v_add_co_u32_e32 v0, vcc, s2, v10
	s_mov_b32 s2, 0xc000
	s_nop 0
	v_addc_co_u32_e32 v1, vcc, 0, v11, vcc
	s_waitcnt lgkmcnt(0)
	global_store_dwordx4 v[0:1], v[4:7], off
	ds_read_b128 v[0:3], v14 offset:43136
	ds_read_b128 v[4:7], v14 offset:44224
	v_add_co_u32_e32 v12, vcc, s2, v10
	s_mov_b32 s2, 0x12000
	s_nop 0
	v_addc_co_u32_e32 v13, vcc, 0, v11, vcc
	v_add_co_u32_e32 v10, vcc, s2, v10
	s_waitcnt lgkmcnt(1)
	global_store_dwordx4 v[12:13], v[0:3], off
	v_addc_co_u32_e32 v11, vcc, 0, v11, vcc
	ds_read_b128 v[0:3], v14 offset:45312
	s_waitcnt lgkmcnt(1)
	global_store_dwordx4 v[10:11], v[4:7], off
	ds_read_b128 v[4:7], v14 offset:46400
	v_lshl_add_u64 v[10:11], v[8:9], 0, v[148:149]
	v_mov_b32_e32 v151, v159
	s_waitcnt lgkmcnt(1)
	global_store_dwordx4 v[10:11], v[0:3], off
	v_lshl_add_u64 v[10:11], v[8:9], 0, v[152:153]
	ds_read_b128 v[0:3], v14 offset:47488
	s_waitcnt lgkmcnt(1)
	global_store_dwordx4 v[10:11], v[4:7], off
	ds_read_b128 v[4:7], v14 offset:48576
	v_lshl_add_u64 v[10:11], v[8:9], 0, v[150:151]
	v_mov_b32_e32 v155, v159
	v_readfirstlane_b32 s12, v222
	s_waitcnt lgkmcnt(1)
	global_store_dwordx4 v[10:11], v[0:3], off
	s_and_b32 s2, s12, 0xffffffc0
	s_nop 0
	v_lshl_add_u64 v[0:1], v[8:9], 0, v[154:155]
	s_waitcnt lgkmcnt(0)
	global_store_dwordx4 v[0:1], v[4:7], off
	v_or_b32_e32 v0, s2, v197
	s_mov_b32 s2, 0x2aaaaaab
	v_mul_hi_i32 v1, v0, s2
	v_lshrrev_b32_e32 v2, 31, v1
	v_ashrrev_i32_e32 v1, 2, v1
	v_add_u32_e32 v2, v1, v2
	s_movk_i32 s2, 0xffe8
	v_lshrrev_b32_e32 v159, 1, v2
	v_mad_u64_u32 v[160:161], s[2:3], v2, s2, v[0:1]
	v_xor_b32_e32 v1, v159, v222
	v_bfi_b32 v1, -8, v160, v1
	v_cmp_lt_i32_e32 vcc, 15, v1
	v_add_u32_e32 v2, s8, v2
	s_and_saveexec_b64 s[2:3], vcc
	s_xor_b64 s[2:3], exec, s[2:3]
	v_mov_b32_e32 v3, 0xbfff80
	v_lshl_add_u32 v153, v2, 6, v3
	s_or_saveexec_b64 s[2:3], s[2:3]
	v_mov_b32_e32 v145, 0x1000
	s_xor_b64 exec, exec, s[2:3]
	v_lshl_or_b32 v2, v2, 11, s17
	v_add_u32_e32 v153, 0x8000000, v2
	v_mov_b32_e32 v145, 0x20000
	s_or_b64 exec, exec, s[2:3]
	v_add_u32_e32 v2, 0x200, v0
	s_mov_b32 s2, 0x2aaaaaab
	v_mul_hi_i32 v3, v2, s2
	v_lshrrev_b32_e32 v4, 31, v3
	v_ashrrev_i32_e32 v3, 2, v3
	v_add_u32_e32 v4, v3, v4
	s_movk_i32 s2, 0xffe8
	v_mad_u64_u32 v[162:163], s[2:3], v4, s2, v[2:3]
	v_lshrrev_b32_e32 v163, 1, v4
	v_xor_b32_e32 v3, v163, v222
	v_bfi_b32 v3, -8, v162, v3
	v_cmp_lt_i32_e32 vcc, 15, v3
	v_add_u32_e32 v4, s8, v4
	s_and_saveexec_b64 s[2:3], vcc
	s_xor_b64 s[2:3], exec, s[2:3]
	v_mov_b32_e32 v5, 0xbfff80
	v_lshl_add_u32 v155, v4, 6, v5
	s_or_saveexec_b64 s[2:3], s[2:3]
	v_mov_b32_e32 v147, 0x1000
	s_xor_b64 exec, exec, s[2:3]
	v_lshl_or_b32 v4, v4, 11, s17
	v_add_u32_e32 v155, 0x8000000, v4
	v_mov_b32_e32 v147, 0x20000
	s_or_b64 exec, exec, s[2:3]
	v_add_u32_e32 v4, 0x400, v0
	s_mov_b32 s2, 0x2aaaaaab
	v_mul_hi_i32 v5, v4, s2
	v_lshrrev_b32_e32 v6, 31, v5
	v_ashrrev_i32_e32 v5, 2, v5
	v_add_u32_e32 v5, v5, v6
	s_movk_i32 s2, 0xffe8
	v_mad_u64_u32 v[164:165], s[2:3], v5, s2, v[4:5]
	v_lshrrev_b32_e32 v165, 1, v5
	v_xor_b32_e32 v4, v165, v222
	v_bfi_b32 v4, -8, v164, v4
	v_cmp_lt_i32_e32 vcc, 15, v4
	v_add_u32_e32 v5, s8, v5
	s_and_saveexec_b64 s[2:3], vcc
	s_xor_b64 s[2:3], exec, s[2:3]
	v_mov_b32_e32 v6, 0xbfff80
	v_lshl_add_u32 v161, v5, 6, v6
	s_or_saveexec_b64 s[2:3], s[2:3]
	v_mov_b32_e32 v149, 0x1000
	s_xor_b64 exec, exec, s[2:3]
	v_lshl_or_b32 v5, v5, 11, s17
	v_add_u32_e32 v161, 0x8000000, v5
	v_mov_b32_e32 v149, 0x20000
	s_or_b64 exec, exec, s[2:3]
	s_lshr_b32 s21, s12, 6
	s_or_b32 s22, s16, 0x1000
	s_lshl_b32 s23, s21, 5
	s_or_b32 s2, s8, s22
	s_add_u32 s19, s2, s23
	v_or_b32_e32 v5, s19, v194
	s_movk_i32 s2, 0x1800
	v_mov_b64_e32 v[6:7], s[4:5]
	s_addc_u32 s20, s9, 0
	v_mad_u64_u32 v[6:7], s[2:3], v5, s2, v[6:7]
	v_mov_b32_e32 v5, 0x1800
	s_mov_b32 s7, 0
	v_mad_i32_i24 v7, s20, v5, v7
	v_lshl_add_u32 v8, v1, 3, v153
	v_ashrrev_i32_e32 v1, 31, v0
	v_lshl_add_u64 v[6:7], v[6:7], 0, s[6:7]
	v_mov_b32_e32 v157, 0
	v_lshrrev_b32_e32 v10, 28, v1
	v_lshl_add_u64 v[6:7], v[6:7], 0, v[156:157]
	v_lshl_add_u32 v4, v4, 3, v161
	v_mov_b32_e32 v5, v157
	v_add_u32_e32 v16, v0, v10
	global_load_dwordx4 v[96:99], v[6:7], off
	global_load_dwordx4 v[100:103], v[6:7], off offset:32
	global_load_dwordx4 v[104:107], v[6:7], off offset:64
	global_load_dwordx4 v[108:111], v[6:7], off offset:96
	global_load_dwordx4 v[112:115], v[6:7], off offset:128
	global_load_dwordx4 v[116:119], v[6:7], off offset:160
	global_load_dwordx4 v[120:123], v[6:7], off offset:192
	global_load_dwordx4 v[124:127], v[6:7], off offset:224
	global_load_dwordx4 v[128:131], v[6:7], off offset:256
	global_load_dwordx4 v[132:135], v[6:7], off offset:288
	global_load_dwordx4 v[136:139], v[6:7], off offset:320
	global_load_dwordx4 v[140:143], v[6:7], off offset:352
	v_lshl_add_u32 v6, v3, 3, v155
	v_ashrrev_i32_e32 v3, 31, v2
	v_lshl_add_u64 v[14:15], v[4:5], 1, s[84:85]
	v_ashrrev_i32_e32 v167, 4, v16
	v_and_b32_e32 v5, 0x1ffffff0, v16
	v_lshrrev_b32_e32 v11, 28, v3
	v_mov_b32_e32 v9, v157
	s_lshl_b32 s2, s21, 10
	v_sub_u32_e32 v0, v0, v5
	v_lshlrev_b32_e32 v5, 2, v167
	v_mov_b32_e32 v7, v157
	v_add_u32_e32 v17, v2, v11
	v_lshl_add_u64 v[10:11], v[8:9], 1, s[84:85]
	v_bfe_u32 v9, v167, 2, 2
	s_add_i32 s7, s2, 0
	v_and_b32_e32 v5, 12, v5
	v_lshl_add_u64 v[12:13], v[6:7], 1, s[84:85]
	v_ashrrev_i32_e32 v166, 4, v17
	v_and_b32_e32 v7, 0x1ffffff0, v17
	v_bitop3_b32 v0, v5, v0, v9 bitop3:0x36
	s_mov_b32 m0, s7
	v_add_lshl_u32 v16, v167, s8, 11
	v_sub_u32_e32 v2, v2, v7
	v_lshlrev_b32_e32 v7, 2, v166
	global_load_lds_dwordx4 v[10:11], off
	s_add_i32 m0, s7, 0x2000
	v_lshlrev_b32_e32 v168, 3, v0
	v_mov_b32_e32 v1, v157
	v_bfe_u32 v17, v166, 2, 2
	v_and_b32_e32 v7, 12, v7
	global_load_lds_dwordx4 v[12:13], off
	s_add_i32 m0, s7, 0x4000
	v_add3_u32 v0, s18, v16, v168
	v_bitop3_b32 v2, v7, v2, v17 bitop3:0x36
	global_load_lds_dwordx4 v[14:15], off
	s_add_i32 m0, s7, 0x6000
	v_lshlrev_b32_e32 v10, 1, v0
	v_add_lshl_u32 v18, v166, s8, 11
	v_lshlrev_b32_e32 v169, 3, v2
	global_load_lds_dwordx4 v10, s[84:85]
	s_add_i32 m0, s7, 0x8000
	v_mov_b32_e32 v3, v157
	v_add3_u32 v2, s18, v18, v169
	s_cmpk_gt_u32 s12, 0xff
	v_lshlrev_b32_e32 v12, 1, v2
	s_cselect_b64 s[10:11], -1, 0
	s_cmpk_lt_u32 s12, 0x100
	v_add_u32_e32 v8, v8, v145
	v_mov_b32_e32 v9, v157
	global_load_lds_dwordx4 v12, s[84:85]
	s_cselect_b64 s[12:13], -1, 0
	s_add_i32 m0, s7, 0xa000
	v_lshl_add_u64 v[8:9], v[8:9], 1, s[84:85]
	v_add_u32_e32 v6, v6, v147
	v_mov_b32_e32 v7, v157
	s_waitcnt vmcnt(0) lgkmcnt(0)
	s_barrier
	s_waitcnt vmcnt(0)
	global_load_lds_dwordx4 v[8:9], off
	v_lshl_add_u64 v[6:7], v[6:7], 1, s[84:85]
	s_add_i32 m0, s7, 0xc000
	v_add_u32_e32 v4, v4, v149
	v_mov_b32_e32 v5, v157
	global_load_lds_dwordx4 v[6:7], off
	v_lshl_add_u64 v[4:5], v[4:5], 1, s[84:85]
	s_add_i32 m0, s7, 0xe000
	v_add_u32_e32 v0, 0x20000, v0
	v_mov_b32_e32 v1, v157
	global_load_lds_dwordx4 v[4:5], off
	s_add_i32 m0, s7, 0x10000
	v_lshl_add_u64 v[0:1], v[0:1], 1, s[84:85]
	global_load_lds_dwordx4 v[0:1], off
	v_add_u32_e32 v0, 0x20000, v2
	v_mov_b32_e32 v1, v157
	v_lshl_add_u64 v[0:1], v[0:1], 1, s[84:85]
	s_add_i32 m0, s7, 0x12000
	s_and_b64 vcc, exec, s[12:13]
	global_load_lds_dwordx4 v[0:1], off
	ds_read_b128 v[0:3], v190
	ds_read_b128 v[4:7], v191
	ds_read_b128 v[8:11], v192
	ds_read_b128 v[12:15], v193
	s_waitcnt lgkmcnt(3)
	v_mfma_f32_32x32x16_bf16 v[48:63], v[0:3], v[96:99], 0
	ds_read_b128 v[0:3], v190 offset:128
	s_waitcnt lgkmcnt(3)
	v_mfma_f32_32x32x16_bf16 v[48:63], v[4:7], v[100:103], v[48:63]
	ds_read_b128 v[4:7], v191 offset:128
	s_waitcnt lgkmcnt(3)
	v_mfma_f32_32x32x16_bf16 v[48:63], v[8:11], v[104:107], v[48:63]
	ds_read_b128 v[8:11], v192 offset:128
	s_waitcnt lgkmcnt(3)
	v_mfma_f32_32x32x16_bf16 v[48:63], v[12:15], v[108:111], v[48:63]
	ds_read_b128 v[12:15], v193 offset:128
	s_waitcnt lgkmcnt(3)
	v_mfma_f32_32x32x16_bf16 v[48:63], v[0:3], v[112:115], v[48:63]
	ds_read_b128 v[0:3], v190 offset:256
	s_waitcnt lgkmcnt(3)
	v_mfma_f32_32x32x16_bf16 v[48:63], v[4:7], v[116:119], v[48:63]
	ds_read_b128 v[4:7], v191 offset:256
	s_waitcnt lgkmcnt(3)
	v_mfma_f32_32x32x16_bf16 v[48:63], v[8:11], v[120:123], v[48:63]
	ds_read_b128 v[8:11], v192 offset:256
	s_waitcnt lgkmcnt(3)
	v_mfma_f32_32x32x16_bf16 v[48:63], v[12:15], v[124:127], v[48:63]
	ds_read_b128 v[12:15], v193 offset:256
	s_waitcnt lgkmcnt(3)
	v_mfma_f32_32x32x16_bf16 v[48:63], v[0:3], v[128:131], v[48:63]
	ds_read_b128 v[0:3], v190 offset:12288
	s_waitcnt lgkmcnt(3)
	v_mfma_f32_32x32x16_bf16 v[48:63], v[4:7], v[132:135], v[48:63]
	ds_read_b128 v[4:7], v191 offset:12288
	s_waitcnt lgkmcnt(3)
	v_mfma_f32_32x32x16_bf16 v[48:63], v[8:11], v[136:139], v[48:63]
	ds_read_b128 v[8:11], v192 offset:12288
	s_waitcnt lgkmcnt(2)
	v_mfma_f32_32x32x16_bf16 v[80:95], v[0:3], v[96:99], 0
	ds_read_b128 v[16:19], v193 offset:12288
	s_waitcnt lgkmcnt(2)
	v_mfma_f32_32x32x16_bf16 v[80:95], v[4:7], v[100:103], v[80:95]
	ds_read_b128 v[20:23], v190 offset:12416
	s_waitcnt lgkmcnt(2)
	v_mfma_f32_32x32x16_bf16 v[80:95], v[8:11], v[104:107], v[80:95]
	ds_read_b128 v[24:27], v191 offset:12416
	s_waitcnt lgkmcnt(2)
	v_mfma_f32_32x32x16_bf16 v[80:95], v[16:19], v[108:111], v[80:95]
	ds_read_b128 v[28:31], v192 offset:12416
	s_waitcnt lgkmcnt(2)
	v_mfma_f32_32x32x16_bf16 v[80:95], v[20:23], v[112:115], v[80:95]
	ds_read_b128 v[32:35], v193 offset:12416
	s_waitcnt lgkmcnt(2)
	v_mfma_f32_32x32x16_bf16 v[80:95], v[24:27], v[116:119], v[80:95]
	ds_read_b128 v[36:39], v190 offset:12544
	s_waitcnt lgkmcnt(2)
	v_mfma_f32_32x32x16_bf16 v[80:95], v[28:31], v[120:123], v[80:95]
	ds_read_b128 v[40:43], v191 offset:12544
	s_waitcnt lgkmcnt(2)
	v_mfma_f32_32x32x16_bf16 v[80:95], v[32:35], v[124:127], v[80:95]
	ds_read_b128 v[44:47], v192 offset:12544
	s_waitcnt lgkmcnt(2)
	v_mfma_f32_32x32x16_bf16 v[80:95], v[36:39], v[128:131], v[80:95]
	ds_read_b128 v[64:67], v193 offset:12544
	s_waitcnt lgkmcnt(2)
	v_mfma_f32_32x32x16_bf16 v[80:95], v[40:43], v[132:135], v[80:95]
	s_waitcnt lgkmcnt(1)
	v_mfma_f32_32x32x16_bf16 v[80:95], v[44:47], v[136:139], v[80:95]
	s_waitcnt lgkmcnt(0)
	v_mfma_f32_32x32x16_bf16 v[80:95], v[64:67], v[140:143], v[80:95]
	v_mfma_f32_32x32x16_bf16 v[48:63], v[12:15], v[140:143], v[48:63]
	s_cbranch_vccnz .LBB0_1911
	s_waitcnt vmcnt(0) lgkmcnt(0)
	s_barrier

.LBB0_1931:
	s_setprio 0
	v_mov_b32_e32 v48, v157
	s_nop 1
	v_permlane32_swap_b32_e32 v157, v48
	v_add_f32_e32 v48, v157, v48
	v_div_scale_f32 v49, s[2:3], v48, v48, 1.0
	v_rcp_f32_e32 v50, v49
	s_mulk_i32 s21, 0x2200
	s_add_i32 s7, s21, 0
	s_waitcnt vmcnt(0) lgkmcnt(0)
	s_barrier
	v_fma_f32 v51, -v49, v50, 1.0
	v_fmac_f32_e32 v50, v51, v50
	v_div_scale_f32 v51, vcc, 1.0, v48, 1.0
	v_mul_f32_e32 v52, v51, v50
	v_fma_f32 v53, -v49, v52, v51
	v_fmac_f32_e32 v52, v53, v50
	v_fma_f32 v49, -v49, v52, v51
	v_div_fmas_f32 v49, v49, v50, v52
	v_div_fixup_f32 v48, v49, v48, 1.0
	v_add3_u32 v49, s7, v195, v181
	v_pk_mul_f32 v[50:51], v[64:65], v[48:49] op_sel_hi:[1,0]
	v_pk_mul_f32 v[52:53], v[66:67], v[48:49] op_sel_hi:[1,0]
	v_cvt_pk_bf16_f32 v50, v50, v51
	v_cvt_pk_bf16_f32 v51, v52, v53
	v_pk_mul_f32 v[52:53], v[68:69], v[48:49] op_sel_hi:[1,0]
	v_pk_mul_f32 v[54:55], v[70:71], v[48:49] op_sel_hi:[1,0]
	v_add_u32_e32 v49, 0xa000, v49
	v_pk_mul_f32 v[32:33], v[32:33], v[48:49] op_sel_hi:[1,0]
	v_pk_mul_f32 v[34:35], v[34:35], v[48:49] op_sel_hi:[1,0]
	v_pk_mul_f32 v[16:17], v[16:17], v[48:49] op_sel_hi:[1,0]
	v_pk_mul_f32 v[18:19], v[18:19], v[48:49] op_sel_hi:[1,0]
	v_pk_mul_f32 v[0:1], v[0:1], v[48:49] op_sel_hi:[1,0]
	v_pk_mul_f32 v[2:3], v[2:3], v[48:49] op_sel_hi:[1,0]
	v_cvt_pk_bf16_f32 v32, v32, v33
	v_cvt_pk_bf16_f32 v33, v34, v35
	v_pk_mul_f32 v[34:35], v[36:37], v[48:49] op_sel_hi:[1,0]
	v_pk_mul_f32 v[36:37], v[38:39], v[48:49] op_sel_hi:[1,0]
	v_cvt_pk_bf16_f32 v16, v16, v17
	v_cvt_pk_bf16_f32 v17, v18, v19
	v_pk_mul_f32 v[18:19], v[20:21], v[48:49] op_sel_hi:[1,0]
	v_pk_mul_f32 v[20:21], v[22:23], v[48:49] op_sel_hi:[1,0]
	v_cvt_pk_bf16_f32 v0, v0, v1
	v_cvt_pk_bf16_f32 v1, v2, v3
	v_pk_mul_f32 v[2:3], v[4:5], v[48:49] op_sel_hi:[1,0]
	v_pk_mul_f32 v[4:5], v[6:7], v[48:49] op_sel_hi:[1,0]
	v_cvt_pk_bf16_f32 v52, v52, v53
	v_cvt_pk_bf16_f32 v53, v54, v55
	v_cvt_pk_bf16_f32 v34, v34, v35
	v_cvt_pk_bf16_f32 v35, v36, v37
	v_cvt_pk_bf16_f32 v18, v18, v19
	v_cvt_pk_bf16_f32 v19, v20, v21
	v_cvt_pk_bf16_f32 v2, v2, v3
	v_cvt_pk_bf16_f32 v3, v4, v5
	ds_write2_b64 v49, v[50:51], v[52:53] offset1:2
	v_pk_mul_f32 v[50:51], v[72:73], v[48:49] op_sel_hi:[1,0]
	v_pk_mul_f32 v[52:53], v[74:75], v[48:49] op_sel_hi:[1,0]
	ds_write2_b64 v49, v[32:33], v[34:35] offset0:8 offset1:10
	v_pk_mul_f32 v[32:33], v[40:41], v[48:49] op_sel_hi:[1,0]
	v_pk_mul_f32 v[34:35], v[42:43], v[48:49] op_sel_hi:[1,0]
	ds_write2_b64 v49, v[16:17], v[18:19] offset0:16 offset1:18
	v_pk_mul_f32 v[16:17], v[24:25], v[48:49] op_sel_hi:[1,0]
	v_pk_mul_f32 v[18:19], v[26:27], v[48:49] op_sel_hi:[1,0]
	ds_write2_b64 v49, v[0:1], v[2:3] offset0:24 offset1:26
	v_pk_mul_f32 v[0:1], v[8:9], v[48:49] op_sel_hi:[1,0]
	v_pk_mul_f32 v[2:3], v[10:11], v[48:49] op_sel_hi:[1,0]
	v_cvt_pk_bf16_f32 v50, v50, v51
	v_cvt_pk_bf16_f32 v51, v52, v53
	v_pk_mul_f32 v[52:53], v[76:77], v[48:49] op_sel_hi:[1,0]
	v_pk_mul_f32 v[54:55], v[78:79], v[48:49] op_sel_hi:[1,0]
	v_cvt_pk_bf16_f32 v32, v32, v33
	v_cvt_pk_bf16_f32 v33, v34, v35
	v_pk_mul_f32 v[34:35], v[44:45], v[48:49] op_sel_hi:[1,0]
	v_pk_mul_f32 v[36:37], v[46:47], v[48:49] op_sel_hi:[1,0]
	v_cvt_pk_bf16_f32 v16, v16, v17
	v_cvt_pk_bf16_f32 v17, v18, v19
	v_pk_mul_f32 v[18:19], v[28:29], v[48:49] op_sel_hi:[1,0]
	v_pk_mul_f32 v[20:21], v[30:31], v[48:49] op_sel_hi:[1,0]
	v_cvt_pk_bf16_f32 v0, v0, v1
	v_cvt_pk_bf16_f32 v1, v2, v3
	v_pk_mul_f32 v[2:3], v[12:13], v[48:49] op_sel_hi:[1,0]
	v_pk_mul_f32 v[4:5], v[14:15], v[48:49] op_sel_hi:[1,0]
	v_cvt_pk_bf16_f32 v52, v52, v53
	v_cvt_pk_bf16_f32 v53, v54, v55
	v_cvt_pk_bf16_f32 v34, v34, v35
	v_cvt_pk_bf16_f32 v35, v36, v37
	v_cvt_pk_bf16_f32 v18, v18, v19
	v_cvt_pk_bf16_f32 v19, v20, v21
	v_cvt_pk_bf16_f32 v2, v2, v3
	v_cvt_pk_bf16_f32 v3, v4, v5
	s_mulk_i32 s20, 0x1800
	s_mul_hi_u32 s2, s19, 0x1800
	ds_write2_b64 v49, v[50:51], v[52:53] offset0:4 offset1:6
	ds_write2_b64 v49, v[32:33], v[34:35] offset0:12 offset1:14
	ds_write2_b64 v49, v[16:17], v[18:19] offset0:20 offset1:22
	ds_write2_b64 v49, v[0:1], v[2:3] offset0:28 offset1:30
	s_add_i32 s2, s2, s20
	s_mulk_i32 s19, 0x1800
	s_nop 0
	s_add_u32 s3, s4, s19
	v_add3_u32 v14, s7, v144, v196
	s_addc_u32 s10, s5, s2
	ds_read_b128 v[0:3], v14 offset:40960
	s_add_u32 s2, s3, s6
	s_addc_u32 s3, s10, 0
	v_mov_b32_e32 v159, 0
	ds_read_b128 v[4:7], v14 offset:42048
	v_lshl_add_u64 v[8:9], s[2:3], 0, v[158:159]
	v_mov_b32_e32 v147, v159
	v_lshl_add_u64 v[10:11], v[8:9], 0, v[146:147]
	s_movk_i32 s2, 0x6000
	s_waitcnt lgkmcnt(1)
	global_store_dwordx4 v[10:11], v[0:3], off
	v_mov_b32_e32 v149, v159
	v_mov_b32_e32 v153, v159
	v_add_co_u32_e32 v0, vcc, s2, v10
	s_mov_b32 s2, 0xc000
	s_nop 0
	v_addc_co_u32_e32 v1, vcc, 0, v11, vcc
	s_waitcnt lgkmcnt(0)
	global_store_dwordx4 v[0:1], v[4:7], off
	ds_read_b128 v[0:3], v14 offset:43136
	ds_read_b128 v[4:7], v14 offset:44224
	v_add_co_u32_e32 v12, vcc, s2, v10
	s_mov_b32 s2, 0x12000
	s_nop 0
	v_addc_co_u32_e32 v13, vcc, 0, v11, vcc
	v_add_co_u32_e32 v10, vcc, s2, v10
	s_waitcnt lgkmcnt(1)
	global_store_dwordx4 v[12:13], v[0:3], off
	v_addc_co_u32_e32 v11, vcc, 0, v11, vcc
	ds_read_b128 v[0:3], v14 offset:45312
	s_waitcnt lgkmcnt(1)
	global_store_dwordx4 v[10:11], v[4:7], off
	ds_read_b128 v[4:7], v14 offset:46400
	v_lshl_add_u64 v[10:11], v[8:9], 0, v[148:149]
	v_mov_b32_e32 v151, v159
	s_waitcnt lgkmcnt(1)
	global_store_dwordx4 v[10:11], v[0:3], off
	v_lshl_add_u64 v[10:11], v[8:9], 0, v[152:153]
	ds_read_b128 v[0:3], v14 offset:47488
	s_waitcnt lgkmcnt(1)
	global_store_dwordx4 v[10:11], v[4:7], off
	ds_read_b128 v[4:7], v14 offset:48576
	v_lshl_add_u64 v[10:11], v[8:9], 0, v[150:151]
	v_mov_b32_e32 v155, v159
	v_readfirstlane_b32 s12, v222
	s_waitcnt lgkmcnt(1)
	global_store_dwordx4 v[10:11], v[0:3], off
	s_and_b32 s2, s12, 0xffffffc0
	s_nop 0
	v_lshl_add_u64 v[0:1], v[8:9], 0, v[154:155]
	s_waitcnt lgkmcnt(0)
	global_store_dwordx4 v[0:1], v[4:7], off
	v_or_b32_e32 v0, s2, v197
	s_mov_b32 s2, 0x2aaaaaab
	v_mul_hi_i32 v1, v0, s2
	v_lshrrev_b32_e32 v2, 31, v1
	v_ashrrev_i32_e32 v1, 2, v1
	v_add_u32_e32 v2, v1, v2
	s_movk_i32 s2, 0xffe8
	v_lshrrev_b32_e32 v159, 1, v2
	v_mad_u64_u32 v[160:161], s[2:3], v2, s2, v[0:1]
	v_xor_b32_e32 v1, v159, v222
	v_bfi_b32 v1, -8, v160, v1
	v_cmp_lt_i32_e32 vcc, 15, v1
	v_add_u32_e32 v2, s8, v2
	s_and_saveexec_b64 s[2:3], vcc
	s_xor_b64 s[2:3], exec, s[2:3]
	v_mov_b32_e32 v3, 0xbfff80
	v_lshl_add_u32 v153, v2, 6, v3
	s_or_saveexec_b64 s[2:3], s[2:3]
	v_mov_b32_e32 v145, 0x1000
	s_xor_b64 exec, exec, s[2:3]
	v_lshl_or_b32 v2, v2, 11, s17
	v_add_u32_e32 v153, 0x8000000, v2
	v_mov_b32_e32 v145, 0x20000
	s_or_b64 exec, exec, s[2:3]
	v_add_u32_e32 v2, 0x200, v0
	s_mov_b32 s2, 0x2aaaaaab
	v_mul_hi_i32 v3, v2, s2
	v_lshrrev_b32_e32 v4, 31, v3
	v_ashrrev_i32_e32 v3, 2, v3
	v_add_u32_e32 v4, v3, v4
	s_movk_i32 s2, 0xffe8
	v_mad_u64_u32 v[162:163], s[2:3], v4, s2, v[2:3]
	v_lshrrev_b32_e32 v163, 1, v4
	v_xor_b32_e32 v3, v163, v222
	v_bfi_b32 v3, -8, v162, v3
	v_cmp_lt_i32_e32 vcc, 15, v3
	v_add_u32_e32 v4, s8, v4
	s_and_saveexec_b64 s[2:3], vcc
	s_xor_b64 s[2:3], exec, s[2:3]
	v_mov_b32_e32 v5, 0xbfff80
	v_lshl_add_u32 v155, v4, 6, v5
	s_or_saveexec_b64 s[2:3], s[2:3]
	v_mov_b32_e32 v147, 0x1000
	s_xor_b64 exec, exec, s[2:3]
	v_lshl_or_b32 v4, v4, 11, s17
	v_add_u32_e32 v155, 0x8000000, v4
	v_mov_b32_e32 v147, 0x20000
	s_or_b64 exec, exec, s[2:3]
	v_add_u32_e32 v4, 0x400, v0
	s_mov_b32 s2, 0x2aaaaaab
	v_mul_hi_i32 v5, v4, s2
	v_lshrrev_b32_e32 v6, 31, v5
	v_ashrrev_i32_e32 v5, 2, v5
	v_add_u32_e32 v5, v5, v6
	s_movk_i32 s2, 0xffe8
	v_mad_u64_u32 v[164:165], s[2:3], v5, s2, v[4:5]
	v_lshrrev_b32_e32 v165, 1, v5
	v_xor_b32_e32 v4, v165, v222
	v_bfi_b32 v4, -8, v164, v4
	v_cmp_lt_i32_e32 vcc, 15, v4
	v_add_u32_e32 v5, s8, v5
	s_and_saveexec_b64 s[2:3], vcc
	s_xor_b64 s[2:3], exec, s[2:3]
	v_mov_b32_e32 v6, 0xbfff80
	v_lshl_add_u32 v161, v5, 6, v6
	s_or_saveexec_b64 s[2:3], s[2:3]
	v_mov_b32_e32 v149, 0x1000
	s_xor_b64 exec, exec, s[2:3]
	v_lshl_or_b32 v5, v5, 11, s17
	v_add_u32_e32 v161, 0x8000000, v5
	v_mov_b32_e32 v149, 0x20000
	s_or_b64 exec, exec, s[2:3]
	s_lshr_b32 s21, s12, 6
	s_xor_b32 s22, s16, 0xf00
	s_lshl_b32 s23, s21, 5
	s_or_b32 s2, s8, s22
	s_add_u32 s19, s2, s23
	v_or_b32_e32 v5, s19, v194
	s_movk_i32 s2, 0x1800
	v_mov_b64_e32 v[6:7], s[4:5]
	s_addc_u32 s20, s9, 0
	v_mad_u64_u32 v[6:7], s[2:3], v5, s2, v[6:7]
	v_mov_b32_e32 v5, 0x1800
	s_mov_b32 s7, 0
	v_mad_i32_i24 v7, s20, v5, v7
	v_lshl_add_u32 v8, v1, 3, v153
	v_ashrrev_i32_e32 v1, 31, v0
	v_lshl_add_u64 v[6:7], v[6:7], 0, s[6:7]
	v_mov_b32_e32 v157, 0
	v_lshrrev_b32_e32 v10, 28, v1
	v_lshl_add_u64 v[6:7], v[6:7], 0, v[156:157]
	v_lshl_add_u32 v4, v4, 3, v161
	v_mov_b32_e32 v5, v157
	v_add_u32_e32 v16, v0, v10
	global_load_dwordx4 v[96:99], v[6:7], off
	global_load_dwordx4 v[100:103], v[6:7], off offset:32
	global_load_dwordx4 v[104:107], v[6:7], off offset:64
	global_load_dwordx4 v[108:111], v[6:7], off offset:96
	global_load_dwordx4 v[112:115], v[6:7], off offset:128
	global_load_dwordx4 v[116:119], v[6:7], off offset:160
	global_load_dwordx4 v[120:123], v[6:7], off offset:192
	global_load_dwordx4 v[124:127], v[6:7], off offset:224
	global_load_dwordx4 v[128:131], v[6:7], off offset:256
	global_load_dwordx4 v[132:135], v[6:7], off offset:288
	global_load_dwordx4 v[136:139], v[6:7], off offset:320
	global_load_dwordx4 v[140:143], v[6:7], off offset:352
	v_lshl_add_u32 v6, v3, 3, v155
	v_ashrrev_i32_e32 v3, 31, v2
	v_lshl_add_u64 v[14:15], v[4:5], 1, s[84:85]
	v_ashrrev_i32_e32 v167, 4, v16
	v_and_b32_e32 v5, 0x1ffffff0, v16
	v_lshrrev_b32_e32 v11, 28, v3
	v_mov_b32_e32 v9, v157
	s_lshl_b32 s2, s21, 10
	v_sub_u32_e32 v0, v0, v5
	v_lshlrev_b32_e32 v5, 2, v167
	v_mov_b32_e32 v7, v157
	v_add_u32_e32 v17, v2, v11
	v_lshl_add_u64 v[10:11], v[8:9], 1, s[84:85]
	v_bfe_u32 v9, v167, 2, 2
	s_add_i32 s7, s2, 0
	v_and_b32_e32 v5, 12, v5
	v_lshl_add_u64 v[12:13], v[6:7], 1, s[84:85]
	v_ashrrev_i32_e32 v166, 4, v17
	v_and_b32_e32 v7, 0x1ffffff0, v17
	v_bitop3_b32 v0, v5, v0, v9 bitop3:0x36
	s_mov_b32 m0, s7
	v_add_lshl_u32 v16, v167, s8, 11
	v_sub_u32_e32 v2, v2, v7
	v_lshlrev_b32_e32 v7, 2, v166
	global_load_lds_dwordx4 v[10:11], off
	s_add_i32 m0, s7, 0x2000
	v_lshlrev_b32_e32 v168, 3, v0
	v_mov_b32_e32 v1, v157
	v_bfe_u32 v17, v166, 2, 2
	v_and_b32_e32 v7, 12, v7
	global_load_lds_dwordx4 v[12:13], off
	s_add_i32 m0, s7, 0x4000
	v_add3_u32 v0, s18, v16, v168
	v_bitop3_b32 v2, v7, v2, v17 bitop3:0x36
	global_load_lds_dwordx4 v[14:15], off
	s_add_i32 m0, s7, 0x6000
	v_lshlrev_b32_e32 v10, 1, v0
	v_add_lshl_u32 v18, v166, s8, 11
	v_lshlrev_b32_e32 v169, 3, v2
	global_load_lds_dwordx4 v10, s[84:85]
	s_add_i32 m0, s7, 0x8000
	v_mov_b32_e32 v3, v157
	v_add3_u32 v2, s18, v18, v169
	s_cmpk_gt_u32 s12, 0xff
	v_lshlrev_b32_e32 v12, 1, v2
	s_cselect_b64 s[10:11], -1, 0
	s_cmpk_lt_u32 s12, 0x100
	v_add_u32_e32 v8, v8, v145
	v_mov_b32_e32 v9, v157
	global_load_lds_dwordx4 v12, s[84:85]
	s_cselect_b64 s[12:13], -1, 0
	s_add_i32 m0, s7, 0xa000
	v_lshl_add_u64 v[8:9], v[8:9], 1, s[84:85]
	v_add_u32_e32 v6, v6, v147
	v_mov_b32_e32 v7, v157
	s_waitcnt vmcnt(0) lgkmcnt(0)
	s_barrier
	s_waitcnt vmcnt(0)
	global_load_lds_dwordx4 v[8:9], off
	v_lshl_add_u64 v[6:7], v[6:7], 1, s[84:85]
	s_add_i32 m0, s7, 0xc000
	v_add_u32_e32 v4, v4, v149
	v_mov_b32_e32 v5, v157
	global_load_lds_dwordx4 v[6:7], off
	v_lshl_add_u64 v[4:5], v[4:5], 1, s[84:85]
	s_add_i32 m0, s7, 0xe000
	v_add_u32_e32 v0, 0x20000, v0
	v_mov_b32_e32 v1, v157
	global_load_lds_dwordx4 v[4:5], off
	s_add_i32 m0, s7, 0x10000
	v_lshl_add_u64 v[0:1], v[0:1], 1, s[84:85]
	global_load_lds_dwordx4 v[0:1], off
	v_add_u32_e32 v0, 0x20000, v2
	v_mov_b32_e32 v1, v157
	v_lshl_add_u64 v[0:1], v[0:1], 1, s[84:85]
	s_add_i32 m0, s7, 0x12000
	s_and_b64 vcc, exec, s[12:13]
	global_load_lds_dwordx4 v[0:1], off
	ds_read_b128 v[0:3], v190
	ds_read_b128 v[4:7], v191
	ds_read_b128 v[8:11], v192
	ds_read_b128 v[12:15], v193
	s_waitcnt lgkmcnt(3)
	v_mfma_f32_32x32x16_bf16 v[48:63], v[0:3], v[96:99], 0
	ds_read_b128 v[0:3], v190 offset:128
	s_waitcnt lgkmcnt(3)
	v_mfma_f32_32x32x16_bf16 v[48:63], v[4:7], v[100:103], v[48:63]
	ds_read_b128 v[4:7], v191 offset:128
	s_waitcnt lgkmcnt(3)
	v_mfma_f32_32x32x16_bf16 v[48:63], v[8:11], v[104:107], v[48:63]
	ds_read_b128 v[8:11], v192 offset:128
	s_waitcnt lgkmcnt(3)
	v_mfma_f32_32x32x16_bf16 v[48:63], v[12:15], v[108:111], v[48:63]
	ds_read_b128 v[12:15], v193 offset:128
	s_waitcnt lgkmcnt(3)
	v_mfma_f32_32x32x16_bf16 v[48:63], v[0:3], v[112:115], v[48:63]
	ds_read_b128 v[0:3], v190 offset:256
	s_waitcnt lgkmcnt(3)
	v_mfma_f32_32x32x16_bf16 v[48:63], v[4:7], v[116:119], v[48:63]
	ds_read_b128 v[4:7], v191 offset:256
	s_waitcnt lgkmcnt(3)
	v_mfma_f32_32x32x16_bf16 v[48:63], v[8:11], v[120:123], v[48:63]
	ds_read_b128 v[8:11], v192 offset:256
	s_waitcnt lgkmcnt(3)
	v_mfma_f32_32x32x16_bf16 v[48:63], v[12:15], v[124:127], v[48:63]
	ds_read_b128 v[12:15], v193 offset:256
	s_waitcnt lgkmcnt(3)
	v_mfma_f32_32x32x16_bf16 v[48:63], v[0:3], v[128:131], v[48:63]
	ds_read_b128 v[0:3], v190 offset:12288
	s_waitcnt lgkmcnt(3)
	v_mfma_f32_32x32x16_bf16 v[48:63], v[4:7], v[132:135], v[48:63]
	ds_read_b128 v[4:7], v191 offset:12288
	s_waitcnt lgkmcnt(3)
	v_mfma_f32_32x32x16_bf16 v[48:63], v[8:11], v[136:139], v[48:63]
	ds_read_b128 v[8:11], v192 offset:12288
	s_waitcnt lgkmcnt(2)
	v_mfma_f32_32x32x16_bf16 v[80:95], v[0:3], v[96:99], 0
	ds_read_b128 v[16:19], v193 offset:12288
	s_waitcnt lgkmcnt(2)
	v_mfma_f32_32x32x16_bf16 v[80:95], v[4:7], v[100:103], v[80:95]
	ds_read_b128 v[20:23], v190 offset:12416
	s_waitcnt lgkmcnt(2)
	v_mfma_f32_32x32x16_bf16 v[80:95], v[8:11], v[104:107], v[80:95]
	ds_read_b128 v[24:27], v191 offset:12416
	s_waitcnt lgkmcnt(2)
	v_mfma_f32_32x32x16_bf16 v[80:95], v[16:19], v[108:111], v[80:95]
	ds_read_b128 v[28:31], v192 offset:12416
	s_waitcnt lgkmcnt(2)
	v_mfma_f32_32x32x16_bf16 v[80:95], v[20:23], v[112:115], v[80:95]
	ds_read_b128 v[32:35], v193 offset:12416
	s_waitcnt lgkmcnt(2)
	v_mfma_f32_32x32x16_bf16 v[80:95], v[24:27], v[116:119], v[80:95]
	ds_read_b128 v[36:39], v190 offset:12544
	s_waitcnt lgkmcnt(2)
	v_mfma_f32_32x32x16_bf16 v[80:95], v[28:31], v[120:123], v[80:95]
	ds_read_b128 v[40:43], v191 offset:12544
	s_waitcnt lgkmcnt(2)
	v_mfma_f32_32x32x16_bf16 v[80:95], v[32:35], v[124:127], v[80:95]
	ds_read_b128 v[44:47], v192 offset:12544
	s_waitcnt lgkmcnt(2)
	v_mfma_f32_32x32x16_bf16 v[80:95], v[36:39], v[128:131], v[80:95]
	ds_read_b128 v[64:67], v193 offset:12544
	s_waitcnt lgkmcnt(2)
	v_mfma_f32_32x32x16_bf16 v[80:95], v[40:43], v[132:135], v[80:95]
	s_waitcnt lgkmcnt(1)
	v_mfma_f32_32x32x16_bf16 v[80:95], v[44:47], v[136:139], v[80:95]
	s_waitcnt lgkmcnt(0)
	v_mfma_f32_32x32x16_bf16 v[80:95], v[64:67], v[140:143], v[80:95]
	v_mfma_f32_32x32x16_bf16 v[48:63], v[12:15], v[140:143], v[48:63]
	s_cbranch_vccnz .LBB0_1945
	s_waitcnt vmcnt(0) lgkmcnt(0)
	s_barrier

.LBB0_1965:
	s_setprio 0
	v_mov_b32_e32 v48, v157
	s_nop 1
	v_permlane32_swap_b32_e32 v157, v48
	v_add_f32_e32 v48, v157, v48
	v_div_scale_f32 v49, s[2:3], v48, v48, 1.0
	v_rcp_f32_e32 v50, v49
	s_mulk_i32 s21, 0x2200
	s_add_i32 s7, s21, 0
	s_waitcnt vmcnt(0) lgkmcnt(0)
	s_barrier
	v_fma_f32 v51, -v49, v50, 1.0
	v_fmac_f32_e32 v50, v51, v50
	v_div_scale_f32 v51, vcc, 1.0, v48, 1.0
	v_mul_f32_e32 v52, v51, v50
	v_fma_f32 v53, -v49, v52, v51
	v_fmac_f32_e32 v52, v53, v50
	v_fma_f32 v49, -v49, v52, v51
	v_div_fmas_f32 v49, v49, v50, v52
	v_div_fixup_f32 v48, v49, v48, 1.0
	v_add3_u32 v49, s7, v195, v181
	v_pk_mul_f32 v[50:51], v[64:65], v[48:49] op_sel_hi:[1,0]
	v_pk_mul_f32 v[52:53], v[66:67], v[48:49] op_sel_hi:[1,0]
	v_cvt_pk_bf16_f32 v50, v50, v51
	v_cvt_pk_bf16_f32 v51, v52, v53
	v_pk_mul_f32 v[52:53], v[68:69], v[48:49] op_sel_hi:[1,0]
	v_pk_mul_f32 v[54:55], v[70:71], v[48:49] op_sel_hi:[1,0]
	v_add_u32_e32 v49, 0xa000, v49
	v_pk_mul_f32 v[32:33], v[32:33], v[48:49] op_sel_hi:[1,0]
	v_pk_mul_f32 v[34:35], v[34:35], v[48:49] op_sel_hi:[1,0]
	v_pk_mul_f32 v[16:17], v[16:17], v[48:49] op_sel_hi:[1,0]
	v_pk_mul_f32 v[18:19], v[18:19], v[48:49] op_sel_hi:[1,0]
	v_pk_mul_f32 v[0:1], v[0:1], v[48:49] op_sel_hi:[1,0]
	v_pk_mul_f32 v[2:3], v[2:3], v[48:49] op_sel_hi:[1,0]
	v_cvt_pk_bf16_f32 v32, v32, v33
	v_cvt_pk_bf16_f32 v33, v34, v35
	v_pk_mul_f32 v[34:35], v[36:37], v[48:49] op_sel_hi:[1,0]
	v_pk_mul_f32 v[36:37], v[38:39], v[48:49] op_sel_hi:[1,0]
	v_cvt_pk_bf16_f32 v16, v16, v17
	v_cvt_pk_bf16_f32 v17, v18, v19
	v_pk_mul_f32 v[18:19], v[20:21], v[48:49] op_sel_hi:[1,0]
	v_pk_mul_f32 v[20:21], v[22:23], v[48:49] op_sel_hi:[1,0]
	v_cvt_pk_bf16_f32 v0, v0, v1
	v_cvt_pk_bf16_f32 v1, v2, v3
	v_pk_mul_f32 v[2:3], v[4:5], v[48:49] op_sel_hi:[1,0]
	v_pk_mul_f32 v[4:5], v[6:7], v[48:49] op_sel_hi:[1,0]
	v_cvt_pk_bf16_f32 v52, v52, v53
	v_cvt_pk_bf16_f32 v53, v54, v55
	v_cvt_pk_bf16_f32 v34, v34, v35
	v_cvt_pk_bf16_f32 v35, v36, v37
	v_cvt_pk_bf16_f32 v18, v18, v19
	v_cvt_pk_bf16_f32 v19, v20, v21
	v_cvt_pk_bf16_f32 v2, v2, v3
	v_cvt_pk_bf16_f32 v3, v4, v5
	ds_write2_b64 v49, v[50:51], v[52:53] offset1:2
	v_pk_mul_f32 v[50:51], v[72:73], v[48:49] op_sel_hi:[1,0]
	v_pk_mul_f32 v[52:53], v[74:75], v[48:49] op_sel_hi:[1,0]
	ds_write2_b64 v49, v[32:33], v[34:35] offset0:8 offset1:10
	v_pk_mul_f32 v[32:33], v[40:41], v[48:49] op_sel_hi:[1,0]
	v_pk_mul_f32 v[34:35], v[42:43], v[48:49] op_sel_hi:[1,0]
	ds_write2_b64 v49, v[16:17], v[18:19] offset0:16 offset1:18
	v_pk_mul_f32 v[16:17], v[24:25], v[48:49] op_sel_hi:[1,0]
	v_pk_mul_f32 v[18:19], v[26:27], v[48:49] op_sel_hi:[1,0]
	ds_write2_b64 v49, v[0:1], v[2:3] offset0:24 offset1:26
	v_pk_mul_f32 v[0:1], v[8:9], v[48:49] op_sel_hi:[1,0]
	v_pk_mul_f32 v[2:3], v[10:11], v[48:49] op_sel_hi:[1,0]
	v_cvt_pk_bf16_f32 v50, v50, v51
	v_cvt_pk_bf16_f32 v51, v52, v53
	v_pk_mul_f32 v[52:53], v[76:77], v[48:49] op_sel_hi:[1,0]
	v_pk_mul_f32 v[54:55], v[78:79], v[48:49] op_sel_hi:[1,0]
	v_cvt_pk_bf16_f32 v32, v32, v33
	v_cvt_pk_bf16_f32 v33, v34, v35
	v_pk_mul_f32 v[34:35], v[44:45], v[48:49] op_sel_hi:[1,0]
	v_pk_mul_f32 v[36:37], v[46:47], v[48:49] op_sel_hi:[1,0]
	v_cvt_pk_bf16_f32 v16, v16, v17
	v_cvt_pk_bf16_f32 v17, v18, v19
	v_pk_mul_f32 v[18:19], v[28:29], v[48:49] op_sel_hi:[1,0]
	v_pk_mul_f32 v[20:21], v[30:31], v[48:49] op_sel_hi:[1,0]
	v_cvt_pk_bf16_f32 v0, v0, v1
	v_cvt_pk_bf16_f32 v1, v2, v3
	v_pk_mul_f32 v[2:3], v[12:13], v[48:49] op_sel_hi:[1,0]
	v_pk_mul_f32 v[4:5], v[14:15], v[48:49] op_sel_hi:[1,0]
	v_cvt_pk_bf16_f32 v52, v52, v53
	v_cvt_pk_bf16_f32 v53, v54, v55
	v_cvt_pk_bf16_f32 v34, v34, v35
	v_cvt_pk_bf16_f32 v35, v36, v37
	v_cvt_pk_bf16_f32 v18, v18, v19
	v_cvt_pk_bf16_f32 v19, v20, v21
	v_cvt_pk_bf16_f32 v2, v2, v3
	v_cvt_pk_bf16_f32 v3, v4, v5
	s_mulk_i32 s20, 0x1800
	s_mul_hi_u32 s2, s19, 0x1800
	ds_write2_b64 v49, v[50:51], v[52:53] offset0:4 offset1:6
	ds_write2_b64 v49, v[32:33], v[34:35] offset0:12 offset1:14
	ds_write2_b64 v49, v[16:17], v[18:19] offset0:20 offset1:22
	ds_write2_b64 v49, v[0:1], v[2:3] offset0:28 offset1:30
	s_add_i32 s2, s2, s20
	s_mulk_i32 s19, 0x1800
	s_nop 0
	s_add_u32 s3, s4, s19
	v_add3_u32 v14, s7, v144, v196
	s_addc_u32 s10, s5, s2
	ds_read_b128 v[0:3], v14 offset:40960
	s_add_u32 s2, s3, s6
	s_addc_u32 s3, s10, 0
	v_mov_b32_e32 v159, 0
	ds_read_b128 v[4:7], v14 offset:42048
	v_lshl_add_u64 v[8:9], s[2:3], 0, v[158:159]
	v_mov_b32_e32 v147, v159
	v_lshl_add_u64 v[10:11], v[8:9], 0, v[146:147]
	s_movk_i32 s2, 0x6000
	s_waitcnt lgkmcnt(1)
	global_store_dwordx4 v[10:11], v[0:3], off
	v_mov_b32_e32 v149, v159
	v_mov_b32_e32 v153, v159
	v_add_co_u32_e32 v0, vcc, s2, v10
	s_mov_b32 s2, 0xc000
	s_nop 0
	v_addc_co_u32_e32 v1, vcc, 0, v11, vcc
	s_waitcnt lgkmcnt(0)
	global_store_dwordx4 v[0:1], v[4:7], off
	ds_read_b128 v[0:3], v14 offset:43136
	ds_read_b128 v[4:7], v14 offset:44224
	v_add_co_u32_e32 v12, vcc, s2, v10
	s_mov_b32 s2, 0x12000
	s_nop 0
	v_addc_co_u32_e32 v13, vcc, 0, v11, vcc
	v_add_co_u32_e32 v10, vcc, s2, v10
	s_waitcnt lgkmcnt(1)
	global_store_dwordx4 v[12:13], v[0:3], off
	v_addc_co_u32_e32 v11, vcc, 0, v11, vcc
	ds_read_b128 v[0:3], v14 offset:45312
	s_waitcnt lgkmcnt(1)
	global_store_dwordx4 v[10:11], v[4:7], off
	ds_read_b128 v[4:7], v14 offset:46400
	v_lshl_add_u64 v[10:11], v[8:9], 0, v[148:149]
	v_mov_b32_e32 v151, v159
	s_waitcnt lgkmcnt(1)
	global_store_dwordx4 v[10:11], v[0:3], off
	v_lshl_add_u64 v[10:11], v[8:9], 0, v[152:153]
	ds_read_b128 v[0:3], v14 offset:47488
	s_waitcnt lgkmcnt(1)
	global_store_dwordx4 v[10:11], v[4:7], off
	ds_read_b128 v[4:7], v14 offset:48576
	v_lshl_add_u64 v[10:11], v[8:9], 0, v[150:151]
	v_mov_b32_e32 v155, v159
	v_readfirstlane_b32 s12, v222
	s_waitcnt lgkmcnt(1)
	global_store_dwordx4 v[10:11], v[0:3], off
	s_and_b32 s2, s12, 0xffffffc0
	s_nop 0
	v_lshl_add_u64 v[0:1], v[8:9], 0, v[154:155]
	s_waitcnt lgkmcnt(0)
	global_store_dwordx4 v[0:1], v[4:7], off
	v_or_b32_e32 v0, s2, v197
	s_mov_b32 s2, 0x2aaaaaab
	v_mul_hi_i32 v1, v0, s2
	v_lshrrev_b32_e32 v2, 31, v1
	v_ashrrev_i32_e32 v1, 2, v1
	v_add_u32_e32 v2, v1, v2
	s_movk_i32 s2, 0xffe8
	v_lshrrev_b32_e32 v159, 1, v2
	v_mad_u64_u32 v[160:161], s[2:3], v2, s2, v[0:1]
	v_xor_b32_e32 v1, v159, v222
	v_bfi_b32 v1, -8, v160, v1
	v_cmp_lt_i32_e32 vcc, 15, v1
	v_add_u32_e32 v2, s8, v2
	s_and_saveexec_b64 s[2:3], vcc
	s_xor_b64 s[2:3], exec, s[2:3]
	v_mov_b32_e32 v3, 0xbfff80
	v_lshl_add_u32 v153, v2, 6, v3
	s_or_saveexec_b64 s[2:3], s[2:3]
	v_mov_b32_e32 v145, 0x1000
	s_xor_b64 exec, exec, s[2:3]
	v_lshl_or_b32 v2, v2, 11, s17
	v_add_u32_e32 v153, 0x8000000, v2
	v_mov_b32_e32 v145, 0x20000
	s_or_b64 exec, exec, s[2:3]
	v_add_u32_e32 v2, 0x200, v0
	s_mov_b32 s2, 0x2aaaaaab
	v_mul_hi_i32 v3, v2, s2
	v_lshrrev_b32_e32 v4, 31, v3
	v_ashrrev_i32_e32 v3, 2, v3
	v_add_u32_e32 v4, v3, v4
	s_movk_i32 s2, 0xffe8
	v_mad_u64_u32 v[162:163], s[2:3], v4, s2, v[2:3]
	v_lshrrev_b32_e32 v163, 1, v4
	v_xor_b32_e32 v3, v163, v222
	v_bfi_b32 v3, -8, v162, v3
	v_cmp_lt_i32_e32 vcc, 15, v3
	v_add_u32_e32 v4, s8, v4
	s_and_saveexec_b64 s[2:3], vcc
	s_xor_b64 s[2:3], exec, s[2:3]
	v_mov_b32_e32 v5, 0xbfff80
	v_lshl_add_u32 v155, v4, 6, v5
	s_or_saveexec_b64 s[2:3], s[2:3]
	v_mov_b32_e32 v147, 0x1000
	s_xor_b64 exec, exec, s[2:3]
	v_lshl_or_b32 v4, v4, 11, s17
	v_add_u32_e32 v155, 0x8000000, v4
	v_mov_b32_e32 v147, 0x20000
	s_or_b64 exec, exec, s[2:3]
	v_add_u32_e32 v4, 0x400, v0
	s_mov_b32 s2, 0x2aaaaaab
	v_mul_hi_i32 v5, v4, s2
	v_lshrrev_b32_e32 v6, 31, v5
	v_ashrrev_i32_e32 v5, 2, v5
	v_add_u32_e32 v5, v5, v6
	s_movk_i32 s2, 0xffe8
	v_mad_u64_u32 v[164:165], s[2:3], v5, s2, v[4:5]
	v_lshrrev_b32_e32 v165, 1, v5
	v_xor_b32_e32 v4, v165, v222
	v_bfi_b32 v4, -8, v164, v4
	v_cmp_lt_i32_e32 vcc, 15, v4
	v_add_u32_e32 v5, s8, v5
	s_and_saveexec_b64 s[2:3], vcc
	s_xor_b64 s[2:3], exec, s[2:3]
	v_mov_b32_e32 v6, 0xbfff80
	v_lshl_add_u32 v161, v5, 6, v6
	s_or_saveexec_b64 s[2:3], s[2:3]
	v_mov_b32_e32 v149, 0x1000
	s_xor_b64 exec, exec, s[2:3]
	v_lshl_or_b32 v5, v5, 11, s17
	v_add_u32_e32 v161, 0x8000000, v5
	v_mov_b32_e32 v149, 0x20000
	s_or_b64 exec, exec, s[2:3]
	s_lshr_b32 s21, s12, 6
	s_or_b32 s22, s16, 0x800
	s_lshl_b32 s23, s21, 5
	s_or_b32 s2, s8, s22
	s_add_u32 s19, s2, s23
	v_or_b32_e32 v5, s19, v194
	s_movk_i32 s2, 0x1800
	v_mov_b64_e32 v[6:7], s[4:5]
	s_addc_u32 s20, s9, 0
	v_mad_u64_u32 v[6:7], s[2:3], v5, s2, v[6:7]
	v_mov_b32_e32 v5, 0x1800
	s_mov_b32 s7, 0
	v_mad_i32_i24 v7, s20, v5, v7
	v_lshl_add_u32 v8, v1, 3, v153
	v_ashrrev_i32_e32 v1, 31, v0
	v_lshl_add_u64 v[6:7], v[6:7], 0, s[6:7]
	v_mov_b32_e32 v157, 0
	v_lshrrev_b32_e32 v10, 28, v1
	v_lshl_add_u64 v[6:7], v[6:7], 0, v[156:157]
	v_lshl_add_u32 v4, v4, 3, v161
	v_mov_b32_e32 v5, v157
	v_add_u32_e32 v16, v0, v10
	global_load_dwordx4 v[96:99], v[6:7], off
	global_load_dwordx4 v[100:103], v[6:7], off offset:32
	global_load_dwordx4 v[104:107], v[6:7], off offset:64
	global_load_dwordx4 v[108:111], v[6:7], off offset:96
	global_load_dwordx4 v[112:115], v[6:7], off offset:128
	global_load_dwordx4 v[116:119], v[6:7], off offset:160
	global_load_dwordx4 v[120:123], v[6:7], off offset:192
	global_load_dwordx4 v[124:127], v[6:7], off offset:224
	global_load_dwordx4 v[128:131], v[6:7], off offset:256
	global_load_dwordx4 v[132:135], v[6:7], off offset:288
	global_load_dwordx4 v[136:139], v[6:7], off offset:320
	global_load_dwordx4 v[140:143], v[6:7], off offset:352
	v_lshl_add_u32 v6, v3, 3, v155
	v_ashrrev_i32_e32 v3, 31, v2
	v_lshl_add_u64 v[14:15], v[4:5], 1, s[84:85]
	v_ashrrev_i32_e32 v167, 4, v16
	v_and_b32_e32 v5, 0x1ffffff0, v16
	v_lshrrev_b32_e32 v11, 28, v3
	v_mov_b32_e32 v9, v157
	s_lshl_b32 s2, s21, 10
	v_sub_u32_e32 v0, v0, v5
	v_lshlrev_b32_e32 v5, 2, v167
	v_mov_b32_e32 v7, v157
	v_add_u32_e32 v17, v2, v11
	v_lshl_add_u64 v[10:11], v[8:9], 1, s[84:85]
	v_bfe_u32 v9, v167, 2, 2
	s_add_i32 s7, s2, 0
	v_and_b32_e32 v5, 12, v5
	v_lshl_add_u64 v[12:13], v[6:7], 1, s[84:85]
	v_ashrrev_i32_e32 v166, 4, v17
	v_and_b32_e32 v7, 0x1ffffff0, v17
	v_bitop3_b32 v0, v5, v0, v9 bitop3:0x36
	s_mov_b32 m0, s7
	v_add_lshl_u32 v16, v167, s8, 11
	v_sub_u32_e32 v2, v2, v7
	v_lshlrev_b32_e32 v7, 2, v166
	global_load_lds_dwordx4 v[10:11], off
	s_add_i32 m0, s7, 0x2000
	v_lshlrev_b32_e32 v168, 3, v0
	v_mov_b32_e32 v1, v157
	v_bfe_u32 v17, v166, 2, 2
	v_and_b32_e32 v7, 12, v7
	global_load_lds_dwordx4 v[12:13], off
	s_add_i32 m0, s7, 0x4000
	v_add3_u32 v0, s18, v16, v168
	v_bitop3_b32 v2, v7, v2, v17 bitop3:0x36
	global_load_lds_dwordx4 v[14:15], off
	s_add_i32 m0, s7, 0x6000
	v_lshlrev_b32_e32 v10, 1, v0
	v_add_lshl_u32 v18, v166, s8, 11
	v_lshlrev_b32_e32 v169, 3, v2
	global_load_lds_dwordx4 v10, s[84:85]
	s_add_i32 m0, s7, 0x8000
	v_mov_b32_e32 v3, v157
	v_add3_u32 v2, s18, v18, v169
	s_cmpk_gt_u32 s12, 0xff
	v_lshlrev_b32_e32 v12, 1, v2
	s_cselect_b64 s[10:11], -1, 0
	s_cmpk_lt_u32 s12, 0x100
	v_add_u32_e32 v8, v8, v145
	v_mov_b32_e32 v9, v157
	global_load_lds_dwordx4 v12, s[84:85]
	s_cselect_b64 s[12:13], -1, 0
	s_add_i32 m0, s7, 0xa000
	v_lshl_add_u64 v[8:9], v[8:9], 1, s[84:85]
	v_add_u32_e32 v6, v6, v147
	v_mov_b32_e32 v7, v157
	s_waitcnt vmcnt(0) lgkmcnt(0)
	s_barrier
	s_waitcnt vmcnt(0)
	global_load_lds_dwordx4 v[8:9], off
	v_lshl_add_u64 v[6:7], v[6:7], 1, s[84:85]
	s_add_i32 m0, s7, 0xc000
	v_add_u32_e32 v4, v4, v149
	v_mov_b32_e32 v5, v157
	global_load_lds_dwordx4 v[6:7], off
	v_lshl_add_u64 v[4:5], v[4:5], 1, s[84:85]
	s_add_i32 m0, s7, 0xe000
	v_add_u32_e32 v0, 0x20000, v0
	v_mov_b32_e32 v1, v157
	global_load_lds_dwordx4 v[4:5], off
	s_add_i32 m0, s7, 0x10000
	v_lshl_add_u64 v[0:1], v[0:1], 1, s[84:85]
	global_load_lds_dwordx4 v[0:1], off
	v_add_u32_e32 v0, 0x20000, v2
	v_mov_b32_e32 v1, v157
	v_lshl_add_u64 v[0:1], v[0:1], 1, s[84:85]
	s_add_i32 m0, s7, 0x12000
	s_and_b64 vcc, exec, s[12:13]
	global_load_lds_dwordx4 v[0:1], off
	ds_read_b128 v[0:3], v190
	ds_read_b128 v[4:7], v191
	ds_read_b128 v[8:11], v192
	ds_read_b128 v[12:15], v193
	s_waitcnt lgkmcnt(3)
	v_mfma_f32_32x32x16_bf16 v[48:63], v[0:3], v[96:99], 0
	ds_read_b128 v[0:3], v190 offset:128
	s_waitcnt lgkmcnt(3)
	v_mfma_f32_32x32x16_bf16 v[48:63], v[4:7], v[100:103], v[48:63]
	ds_read_b128 v[4:7], v191 offset:128
	s_waitcnt lgkmcnt(3)
	v_mfma_f32_32x32x16_bf16 v[48:63], v[8:11], v[104:107], v[48:63]
	ds_read_b128 v[8:11], v192 offset:128
	s_waitcnt lgkmcnt(3)
	v_mfma_f32_32x32x16_bf16 v[48:63], v[12:15], v[108:111], v[48:63]
	ds_read_b128 v[12:15], v193 offset:128
	s_waitcnt lgkmcnt(3)
	v_mfma_f32_32x32x16_bf16 v[48:63], v[0:3], v[112:115], v[48:63]
	ds_read_b128 v[0:3], v190 offset:256
	s_waitcnt lgkmcnt(3)
	v_mfma_f32_32x32x16_bf16 v[48:63], v[4:7], v[116:119], v[48:63]
	ds_read_b128 v[4:7], v191 offset:256
	s_waitcnt lgkmcnt(3)
	v_mfma_f32_32x32x16_bf16 v[48:63], v[8:11], v[120:123], v[48:63]
	ds_read_b128 v[8:11], v192 offset:256
	s_waitcnt lgkmcnt(3)
	v_mfma_f32_32x32x16_bf16 v[48:63], v[12:15], v[124:127], v[48:63]
	ds_read_b128 v[12:15], v193 offset:256
	s_waitcnt lgkmcnt(3)
	v_mfma_f32_32x32x16_bf16 v[48:63], v[0:3], v[128:131], v[48:63]
	ds_read_b128 v[0:3], v190 offset:12288
	s_waitcnt lgkmcnt(3)
	v_mfma_f32_32x32x16_bf16 v[48:63], v[4:7], v[132:135], v[48:63]
	ds_read_b128 v[4:7], v191 offset:12288
	s_waitcnt lgkmcnt(3)
	v_mfma_f32_32x32x16_bf16 v[48:63], v[8:11], v[136:139], v[48:63]
	ds_read_b128 v[8:11], v192 offset:12288
	s_waitcnt lgkmcnt(2)
	v_mfma_f32_32x32x16_bf16 v[80:95], v[0:3], v[96:99], 0
	ds_read_b128 v[16:19], v193 offset:12288
	s_waitcnt lgkmcnt(2)
	v_mfma_f32_32x32x16_bf16 v[80:95], v[4:7], v[100:103], v[80:95]
	ds_read_b128 v[20:23], v190 offset:12416
	s_waitcnt lgkmcnt(2)
	v_mfma_f32_32x32x16_bf16 v[80:95], v[8:11], v[104:107], v[80:95]
	ds_read_b128 v[24:27], v191 offset:12416
	s_waitcnt lgkmcnt(2)
	v_mfma_f32_32x32x16_bf16 v[80:95], v[16:19], v[108:111], v[80:95]
	ds_read_b128 v[28:31], v192 offset:12416
	s_waitcnt lgkmcnt(2)
	v_mfma_f32_32x32x16_bf16 v[80:95], v[20:23], v[112:115], v[80:95]
	ds_read_b128 v[32:35], v193 offset:12416
	s_waitcnt lgkmcnt(2)
	v_mfma_f32_32x32x16_bf16 v[80:95], v[24:27], v[116:119], v[80:95]
	ds_read_b128 v[36:39], v190 offset:12544
	s_waitcnt lgkmcnt(2)
	v_mfma_f32_32x32x16_bf16 v[80:95], v[28:31], v[120:123], v[80:95]
	ds_read_b128 v[40:43], v191 offset:12544
	s_waitcnt lgkmcnt(2)
	v_mfma_f32_32x32x16_bf16 v[80:95], v[32:35], v[124:127], v[80:95]
	ds_read_b128 v[44:47], v192 offset:12544
	s_waitcnt lgkmcnt(2)
	v_mfma_f32_32x32x16_bf16 v[80:95], v[36:39], v[128:131], v[80:95]
	ds_read_b128 v[64:67], v193 offset:12544
	s_waitcnt lgkmcnt(2)
	v_mfma_f32_32x32x16_bf16 v[80:95], v[40:43], v[132:135], v[80:95]
	s_waitcnt lgkmcnt(1)
	v_mfma_f32_32x32x16_bf16 v[80:95], v[44:47], v[136:139], v[80:95]
	s_waitcnt lgkmcnt(0)
	v_mfma_f32_32x32x16_bf16 v[80:95], v[64:67], v[140:143], v[80:95]
	v_mfma_f32_32x32x16_bf16 v[48:63], v[12:15], v[140:143], v[48:63]
	s_cbranch_vccnz .LBB0_1979
	s_waitcnt vmcnt(0) lgkmcnt(0)
	s_barrier

.LBB0_1999:
	s_setprio 0
	v_mov_b32_e32 v48, v157
	s_nop 1
	v_permlane32_swap_b32_e32 v157, v48
	v_add_f32_e32 v48, v157, v48
	v_div_scale_f32 v49, s[2:3], v48, v48, 1.0
	v_rcp_f32_e32 v50, v49
	s_mulk_i32 s21, 0x2200
	s_add_i32 s7, s21, 0
	s_waitcnt vmcnt(0) lgkmcnt(0)
	s_barrier
	v_fma_f32 v51, -v49, v50, 1.0
	v_fmac_f32_e32 v50, v51, v50
	v_div_scale_f32 v51, vcc, 1.0, v48, 1.0
	v_mul_f32_e32 v52, v51, v50
	v_fma_f32 v53, -v49, v52, v51
	v_fmac_f32_e32 v52, v53, v50
	v_fma_f32 v49, -v49, v52, v51
	v_div_fmas_f32 v49, v49, v50, v52
	v_div_fixup_f32 v48, v49, v48, 1.0
	v_add3_u32 v49, s7, v195, v181
	v_pk_mul_f32 v[50:51], v[64:65], v[48:49] op_sel_hi:[1,0]
	v_pk_mul_f32 v[52:53], v[66:67], v[48:49] op_sel_hi:[1,0]
	v_cvt_pk_bf16_f32 v50, v50, v51
	v_cvt_pk_bf16_f32 v51, v52, v53
	v_pk_mul_f32 v[52:53], v[68:69], v[48:49] op_sel_hi:[1,0]
	v_pk_mul_f32 v[54:55], v[70:71], v[48:49] op_sel_hi:[1,0]
	v_add_u32_e32 v49, 0xa000, v49
	v_pk_mul_f32 v[32:33], v[32:33], v[48:49] op_sel_hi:[1,0]
	v_pk_mul_f32 v[34:35], v[34:35], v[48:49] op_sel_hi:[1,0]
	v_pk_mul_f32 v[16:17], v[16:17], v[48:49] op_sel_hi:[1,0]
	v_pk_mul_f32 v[18:19], v[18:19], v[48:49] op_sel_hi:[1,0]
	v_pk_mul_f32 v[0:1], v[0:1], v[48:49] op_sel_hi:[1,0]
	v_pk_mul_f32 v[2:3], v[2:3], v[48:49] op_sel_hi:[1,0]
	v_cvt_pk_bf16_f32 v32, v32, v33
	v_cvt_pk_bf16_f32 v33, v34, v35
	v_pk_mul_f32 v[34:35], v[36:37], v[48:49] op_sel_hi:[1,0]
	v_pk_mul_f32 v[36:37], v[38:39], v[48:49] op_sel_hi:[1,0]
	v_cvt_pk_bf16_f32 v16, v16, v17
	v_cvt_pk_bf16_f32 v17, v18, v19
	v_pk_mul_f32 v[18:19], v[20:21], v[48:49] op_sel_hi:[1,0]
	v_pk_mul_f32 v[20:21], v[22:23], v[48:49] op_sel_hi:[1,0]
	v_cvt_pk_bf16_f32 v0, v0, v1
	v_cvt_pk_bf16_f32 v1, v2, v3
	v_pk_mul_f32 v[2:3], v[4:5], v[48:49] op_sel_hi:[1,0]
	v_pk_mul_f32 v[4:5], v[6:7], v[48:49] op_sel_hi:[1,0]
	v_cvt_pk_bf16_f32 v52, v52, v53
	v_cvt_pk_bf16_f32 v53, v54, v55
	v_cvt_pk_bf16_f32 v34, v34, v35
	v_cvt_pk_bf16_f32 v35, v36, v37
	v_cvt_pk_bf16_f32 v18, v18, v19
	v_cvt_pk_bf16_f32 v19, v20, v21
	v_cvt_pk_bf16_f32 v2, v2, v3
	v_cvt_pk_bf16_f32 v3, v4, v5
	ds_write2_b64 v49, v[50:51], v[52:53] offset1:2
	v_pk_mul_f32 v[50:51], v[72:73], v[48:49] op_sel_hi:[1,0]
	v_pk_mul_f32 v[52:53], v[74:75], v[48:49] op_sel_hi:[1,0]
	ds_write2_b64 v49, v[32:33], v[34:35] offset0:8 offset1:10
	v_pk_mul_f32 v[32:33], v[40:41], v[48:49] op_sel_hi:[1,0]
	v_pk_mul_f32 v[34:35], v[42:43], v[48:49] op_sel_hi:[1,0]
	ds_write2_b64 v49, v[16:17], v[18:19] offset0:16 offset1:18
	v_pk_mul_f32 v[16:17], v[24:25], v[48:49] op_sel_hi:[1,0]
	v_pk_mul_f32 v[18:19], v[26:27], v[48:49] op_sel_hi:[1,0]
	ds_write2_b64 v49, v[0:1], v[2:3] offset0:24 offset1:26
	v_pk_mul_f32 v[0:1], v[8:9], v[48:49] op_sel_hi:[1,0]
	v_pk_mul_f32 v[2:3], v[10:11], v[48:49] op_sel_hi:[1,0]
	v_cvt_pk_bf16_f32 v50, v50, v51
	v_cvt_pk_bf16_f32 v51, v52, v53
	v_pk_mul_f32 v[52:53], v[76:77], v[48:49] op_sel_hi:[1,0]
	v_pk_mul_f32 v[54:55], v[78:79], v[48:49] op_sel_hi:[1,0]
	v_cvt_pk_bf16_f32 v32, v32, v33
	v_cvt_pk_bf16_f32 v33, v34, v35
	v_pk_mul_f32 v[34:35], v[44:45], v[48:49] op_sel_hi:[1,0]
	v_pk_mul_f32 v[36:37], v[46:47], v[48:49] op_sel_hi:[1,0]
	v_cvt_pk_bf16_f32 v16, v16, v17
	v_cvt_pk_bf16_f32 v17, v18, v19
	v_pk_mul_f32 v[18:19], v[28:29], v[48:49] op_sel_hi:[1,0]
	v_pk_mul_f32 v[20:21], v[30:31], v[48:49] op_sel_hi:[1,0]
	v_cvt_pk_bf16_f32 v0, v0, v1
	v_cvt_pk_bf16_f32 v1, v2, v3
	v_pk_mul_f32 v[2:3], v[12:13], v[48:49] op_sel_hi:[1,0]
	v_pk_mul_f32 v[4:5], v[14:15], v[48:49] op_sel_hi:[1,0]
	v_cvt_pk_bf16_f32 v52, v52, v53
	v_cvt_pk_bf16_f32 v53, v54, v55
	v_cvt_pk_bf16_f32 v34, v34, v35
	v_cvt_pk_bf16_f32 v35, v36, v37
	v_cvt_pk_bf16_f32 v18, v18, v19
	v_cvt_pk_bf16_f32 v19, v20, v21
	v_cvt_pk_bf16_f32 v2, v2, v3
	v_cvt_pk_bf16_f32 v3, v4, v5
	s_mulk_i32 s20, 0x1800
	s_mul_hi_u32 s2, s19, 0x1800
	ds_write2_b64 v49, v[50:51], v[52:53] offset0:4 offset1:6
	ds_write2_b64 v49, v[32:33], v[34:35] offset0:12 offset1:14
	ds_write2_b64 v49, v[16:17], v[18:19] offset0:20 offset1:22
	ds_write2_b64 v49, v[0:1], v[2:3] offset0:28 offset1:30
	s_add_i32 s2, s2, s20
	s_mulk_i32 s19, 0x1800
	s_nop 0
	s_add_u32 s3, s4, s19
	v_add3_u32 v14, s7, v144, v196
	s_addc_u32 s10, s5, s2
	ds_read_b128 v[0:3], v14 offset:40960
	s_add_u32 s2, s3, s6
	s_addc_u32 s3, s10, 0
	v_mov_b32_e32 v159, 0
	ds_read_b128 v[4:7], v14 offset:42048
	v_lshl_add_u64 v[8:9], s[2:3], 0, v[158:159]
	v_mov_b32_e32 v147, v159
	v_lshl_add_u64 v[10:11], v[8:9], 0, v[146:147]
	s_movk_i32 s2, 0x6000
	s_waitcnt lgkmcnt(1)
	global_store_dwordx4 v[10:11], v[0:3], off
	v_mov_b32_e32 v149, v159
	v_mov_b32_e32 v153, v159
	v_add_co_u32_e32 v0, vcc, s2, v10
	s_mov_b32 s2, 0xc000
	s_nop 0
	v_addc_co_u32_e32 v1, vcc, 0, v11, vcc
	s_waitcnt lgkmcnt(0)
	global_store_dwordx4 v[0:1], v[4:7], off
	ds_read_b128 v[0:3], v14 offset:43136
	ds_read_b128 v[4:7], v14 offset:44224
	v_add_co_u32_e32 v12, vcc, s2, v10
	s_mov_b32 s2, 0x12000
	s_nop 0
	v_addc_co_u32_e32 v13, vcc, 0, v11, vcc
	v_add_co_u32_e32 v10, vcc, s2, v10
	s_waitcnt lgkmcnt(1)
	global_store_dwordx4 v[12:13], v[0:3], off
	v_addc_co_u32_e32 v11, vcc, 0, v11, vcc
	ds_read_b128 v[0:3], v14 offset:45312
	s_waitcnt lgkmcnt(1)
	global_store_dwordx4 v[10:11], v[4:7], off
	ds_read_b128 v[4:7], v14 offset:46400
	v_lshl_add_u64 v[10:11], v[8:9], 0, v[148:149]
	v_mov_b32_e32 v151, v159
	s_waitcnt lgkmcnt(1)
	global_store_dwordx4 v[10:11], v[0:3], off
	v_lshl_add_u64 v[10:11], v[8:9], 0, v[152:153]
	ds_read_b128 v[0:3], v14 offset:47488
	s_waitcnt lgkmcnt(1)
	global_store_dwordx4 v[10:11], v[4:7], off
	ds_read_b128 v[4:7], v14 offset:48576
	v_lshl_add_u64 v[10:11], v[8:9], 0, v[150:151]
	v_mov_b32_e32 v155, v159
	v_readfirstlane_b32 s12, v222
	s_waitcnt lgkmcnt(1)
	global_store_dwordx4 v[10:11], v[0:3], off
	s_and_b32 s2, s12, 0xffffffc0
	s_nop 0
	v_lshl_add_u64 v[0:1], v[8:9], 0, v[154:155]
	s_waitcnt lgkmcnt(0)
	global_store_dwordx4 v[0:1], v[4:7], off
	v_or_b32_e32 v0, s2, v197
	s_mov_b32 s2, 0x2aaaaaab
	v_mul_hi_i32 v1, v0, s2
	v_lshrrev_b32_e32 v2, 31, v1
	v_ashrrev_i32_e32 v1, 2, v1
	v_add_u32_e32 v2, v1, v2
	s_movk_i32 s2, 0xffe8
	v_lshrrev_b32_e32 v159, 1, v2
	v_mad_u64_u32 v[160:161], s[2:3], v2, s2, v[0:1]
	v_xor_b32_e32 v1, v159, v222
	v_bfi_b32 v1, -8, v160, v1
	v_cmp_lt_i32_e32 vcc, 15, v1
	v_add_u32_e32 v2, s8, v2
	s_and_saveexec_b64 s[2:3], vcc
	s_xor_b64 s[2:3], exec, s[2:3]
	v_mov_b32_e32 v3, 0xbfff80
	v_lshl_add_u32 v153, v2, 6, v3
	s_or_saveexec_b64 s[2:3], s[2:3]
	v_mov_b32_e32 v145, 0x1000
	s_xor_b64 exec, exec, s[2:3]
	v_lshl_or_b32 v2, v2, 11, s17
	v_add_u32_e32 v153, 0x8000000, v2
	v_mov_b32_e32 v145, 0x20000
	s_or_b64 exec, exec, s[2:3]
	v_add_u32_e32 v2, 0x200, v0
	s_mov_b32 s2, 0x2aaaaaab
	v_mul_hi_i32 v3, v2, s2
	v_lshrrev_b32_e32 v4, 31, v3
	v_ashrrev_i32_e32 v3, 2, v3
	v_add_u32_e32 v4, v3, v4
	s_movk_i32 s2, 0xffe8
	v_mad_u64_u32 v[162:163], s[2:3], v4, s2, v[2:3]
	v_lshrrev_b32_e32 v163, 1, v4
	v_xor_b32_e32 v3, v163, v222
	v_bfi_b32 v3, -8, v162, v3
	v_cmp_lt_i32_e32 vcc, 15, v3
	v_add_u32_e32 v4, s8, v4
	s_and_saveexec_b64 s[2:3], vcc
	s_xor_b64 s[2:3], exec, s[2:3]
	v_mov_b32_e32 v5, 0xbfff80
	v_lshl_add_u32 v155, v4, 6, v5
	s_or_saveexec_b64 s[2:3], s[2:3]
	v_mov_b32_e32 v147, 0x1000
	s_xor_b64 exec, exec, s[2:3]
	v_lshl_or_b32 v4, v4, 11, s17
	v_add_u32_e32 v155, 0x8000000, v4
	v_mov_b32_e32 v147, 0x20000
	s_or_b64 exec, exec, s[2:3]
	v_add_u32_e32 v4, 0x400, v0
	s_mov_b32 s2, 0x2aaaaaab
	v_mul_hi_i32 v5, v4, s2
	v_lshrrev_b32_e32 v6, 31, v5
	v_ashrrev_i32_e32 v5, 2, v5
	v_add_u32_e32 v5, v5, v6
	s_movk_i32 s2, 0xffe8
	v_mad_u64_u32 v[164:165], s[2:3], v5, s2, v[4:5]
	v_lshrrev_b32_e32 v165, 1, v5
	v_xor_b32_e32 v4, v165, v222
	v_bfi_b32 v4, -8, v164, v4
	v_cmp_lt_i32_e32 vcc, 15, v4
	v_add_u32_e32 v5, s8, v5
	s_and_saveexec_b64 s[2:3], vcc
	s_xor_b64 s[2:3], exec, s[2:3]
	v_mov_b32_e32 v6, 0xbfff80
	v_lshl_add_u32 v161, v5, 6, v6
	s_or_saveexec_b64 s[2:3], s[2:3]
	v_mov_b32_e32 v149, 0x1000
	s_xor_b64 exec, exec, s[2:3]
	v_lshl_or_b32 v5, v5, 11, s17
	v_add_u32_e32 v161, 0x8000000, v5
	v_mov_b32_e32 v149, 0x20000
	s_or_b64 exec, exec, s[2:3]
	s_lshr_b32 s21, s12, 6
	s_xor_b32 s22, s16, 0x700
	s_lshl_b32 s23, s21, 5
	s_or_b32 s2, s8, s22
	s_add_u32 s19, s2, s23
	v_or_b32_e32 v5, s19, v194
	s_movk_i32 s2, 0x1800
	v_mov_b64_e32 v[6:7], s[4:5]
	s_addc_u32 s20, s9, 0
	v_mad_u64_u32 v[6:7], s[2:3], v5, s2, v[6:7]
	v_mov_b32_e32 v5, 0x1800
	s_mov_b32 s7, 0
	v_mad_i32_i24 v7, s20, v5, v7
	v_lshl_add_u32 v8, v1, 3, v153
	v_ashrrev_i32_e32 v1, 31, v0
	v_lshl_add_u64 v[6:7], v[6:7], 0, s[6:7]
	v_mov_b32_e32 v157, 0
	v_lshrrev_b32_e32 v10, 28, v1
	v_lshl_add_u64 v[6:7], v[6:7], 0, v[156:157]
	v_lshl_add_u32 v4, v4, 3, v161
	v_mov_b32_e32 v5, v157
	v_add_u32_e32 v16, v0, v10
	global_load_dwordx4 v[96:99], v[6:7], off
	global_load_dwordx4 v[100:103], v[6:7], off offset:32
	global_load_dwordx4 v[104:107], v[6:7], off offset:64
	global_load_dwordx4 v[108:111], v[6:7], off offset:96
	global_load_dwordx4 v[112:115], v[6:7], off offset:128
	global_load_dwordx4 v[116:119], v[6:7], off offset:160
	global_load_dwordx4 v[120:123], v[6:7], off offset:192
	global_load_dwordx4 v[124:127], v[6:7], off offset:224
	global_load_dwordx4 v[128:131], v[6:7], off offset:256
	global_load_dwordx4 v[132:135], v[6:7], off offset:288
	global_load_dwordx4 v[136:139], v[6:7], off offset:320
	global_load_dwordx4 v[140:143], v[6:7], off offset:352
	v_lshl_add_u32 v6, v3, 3, v155
	v_ashrrev_i32_e32 v3, 31, v2
	v_lshl_add_u64 v[14:15], v[4:5], 1, s[84:85]
	v_ashrrev_i32_e32 v167, 4, v16
	v_and_b32_e32 v5, 0x1ffffff0, v16
	v_lshrrev_b32_e32 v11, 28, v3
	v_mov_b32_e32 v9, v157
	s_lshl_b32 s2, s21, 10
	v_sub_u32_e32 v0, v0, v5
	v_lshlrev_b32_e32 v5, 2, v167
	v_mov_b32_e32 v7, v157
	v_add_u32_e32 v17, v2, v11
	v_lshl_add_u64 v[10:11], v[8:9], 1, s[84:85]
	v_bfe_u32 v9, v167, 2, 2
	s_add_i32 s7, s2, 0
	v_and_b32_e32 v5, 12, v5
	v_lshl_add_u64 v[12:13], v[6:7], 1, s[84:85]
	v_ashrrev_i32_e32 v166, 4, v17
	v_and_b32_e32 v7, 0x1ffffff0, v17
	v_bitop3_b32 v0, v5, v0, v9 bitop3:0x36
	s_mov_b32 m0, s7
	v_add_lshl_u32 v16, v167, s8, 11
	v_sub_u32_e32 v2, v2, v7
	v_lshlrev_b32_e32 v7, 2, v166
	global_load_lds_dwordx4 v[10:11], off
	s_add_i32 m0, s7, 0x2000
	v_lshlrev_b32_e32 v168, 3, v0
	v_mov_b32_e32 v1, v157
	v_bfe_u32 v17, v166, 2, 2
	v_and_b32_e32 v7, 12, v7
	global_load_lds_dwordx4 v[12:13], off
	s_add_i32 m0, s7, 0x4000
	v_add3_u32 v0, s18, v16, v168
	v_bitop3_b32 v2, v7, v2, v17 bitop3:0x36
	global_load_lds_dwordx4 v[14:15], off
	s_add_i32 m0, s7, 0x6000
	v_lshlrev_b32_e32 v10, 1, v0
	v_add_lshl_u32 v18, v166, s8, 11
	v_lshlrev_b32_e32 v169, 3, v2
	global_load_lds_dwordx4 v10, s[84:85]
	s_add_i32 m0, s7, 0x8000
	v_mov_b32_e32 v3, v157
	v_add3_u32 v2, s18, v18, v169
	s_cmpk_gt_u32 s12, 0xff
	v_lshlrev_b32_e32 v12, 1, v2
	s_cselect_b64 s[10:11], -1, 0
	s_cmpk_lt_u32 s12, 0x100
	v_add_u32_e32 v8, v8, v145
	v_mov_b32_e32 v9, v157
	global_load_lds_dwordx4 v12, s[84:85]
	s_cselect_b64 s[12:13], -1, 0
	s_add_i32 m0, s7, 0xa000
	v_lshl_add_u64 v[8:9], v[8:9], 1, s[84:85]
	v_add_u32_e32 v6, v6, v147
	v_mov_b32_e32 v7, v157
	s_waitcnt vmcnt(0) lgkmcnt(0)
	s_barrier
	s_waitcnt vmcnt(0)
	global_load_lds_dwordx4 v[8:9], off
	v_lshl_add_u64 v[6:7], v[6:7], 1, s[84:85]
	s_add_i32 m0, s7, 0xc000
	v_add_u32_e32 v4, v4, v149
	v_mov_b32_e32 v5, v157
	global_load_lds_dwordx4 v[6:7], off
	v_lshl_add_u64 v[4:5], v[4:5], 1, s[84:85]
	s_add_i32 m0, s7, 0xe000
	v_add_u32_e32 v0, 0x20000, v0
	v_mov_b32_e32 v1, v157
	global_load_lds_dwordx4 v[4:5], off
	s_add_i32 m0, s7, 0x10000
	v_lshl_add_u64 v[0:1], v[0:1], 1, s[84:85]
	global_load_lds_dwordx4 v[0:1], off
	v_add_u32_e32 v0, 0x20000, v2
	v_mov_b32_e32 v1, v157
	v_lshl_add_u64 v[0:1], v[0:1], 1, s[84:85]
	s_add_i32 m0, s7, 0x12000
	s_and_b64 vcc, exec, s[12:13]
	global_load_lds_dwordx4 v[0:1], off
	ds_read_b128 v[0:3], v190
	ds_read_b128 v[4:7], v191
	ds_read_b128 v[8:11], v192
	ds_read_b128 v[12:15], v193
	s_waitcnt lgkmcnt(3)
	v_mfma_f32_32x32x16_bf16 v[48:63], v[0:3], v[96:99], 0
	ds_read_b128 v[0:3], v190 offset:128
	s_waitcnt lgkmcnt(3)
	v_mfma_f32_32x32x16_bf16 v[48:63], v[4:7], v[100:103], v[48:63]
	ds_read_b128 v[4:7], v191 offset:128
	s_waitcnt lgkmcnt(3)
	v_mfma_f32_32x32x16_bf16 v[48:63], v[8:11], v[104:107], v[48:63]
	ds_read_b128 v[8:11], v192 offset:128
	s_waitcnt lgkmcnt(3)
	v_mfma_f32_32x32x16_bf16 v[48:63], v[12:15], v[108:111], v[48:63]
	ds_read_b128 v[12:15], v193 offset:128
	s_waitcnt lgkmcnt(3)
	v_mfma_f32_32x32x16_bf16 v[48:63], v[0:3], v[112:115], v[48:63]
	ds_read_b128 v[0:3], v190 offset:256
	s_waitcnt lgkmcnt(3)
	v_mfma_f32_32x32x16_bf16 v[48:63], v[4:7], v[116:119], v[48:63]
	ds_read_b128 v[4:7], v191 offset:256
	s_waitcnt lgkmcnt(3)
	v_mfma_f32_32x32x16_bf16 v[48:63], v[8:11], v[120:123], v[48:63]
	ds_read_b128 v[8:11], v192 offset:256
	s_waitcnt lgkmcnt(3)
	v_mfma_f32_32x32x16_bf16 v[48:63], v[12:15], v[124:127], v[48:63]
	ds_read_b128 v[12:15], v193 offset:256
	s_waitcnt lgkmcnt(3)
	v_mfma_f32_32x32x16_bf16 v[48:63], v[0:3], v[128:131], v[48:63]
	ds_read_b128 v[0:3], v190 offset:12288
	s_waitcnt lgkmcnt(3)
	v_mfma_f32_32x32x16_bf16 v[48:63], v[4:7], v[132:135], v[48:63]
	ds_read_b128 v[4:7], v191 offset:12288
	s_waitcnt lgkmcnt(3)
	v_mfma_f32_32x32x16_bf16 v[48:63], v[8:11], v[136:139], v[48:63]
	ds_read_b128 v[8:11], v192 offset:12288
	s_waitcnt lgkmcnt(2)
	v_mfma_f32_32x32x16_bf16 v[80:95], v[0:3], v[96:99], 0
	ds_read_b128 v[16:19], v193 offset:12288
	s_waitcnt lgkmcnt(2)
	v_mfma_f32_32x32x16_bf16 v[80:95], v[4:7], v[100:103], v[80:95]
	ds_read_b128 v[20:23], v190 offset:12416
	s_waitcnt lgkmcnt(2)
	v_mfma_f32_32x32x16_bf16 v[80:95], v[8:11], v[104:107], v[80:95]
	ds_read_b128 v[24:27], v191 offset:12416
	s_waitcnt lgkmcnt(2)
	v_mfma_f32_32x32x16_bf16 v[80:95], v[16:19], v[108:111], v[80:95]
	ds_read_b128 v[28:31], v192 offset:12416
	s_waitcnt lgkmcnt(2)
	v_mfma_f32_32x32x16_bf16 v[80:95], v[20:23], v[112:115], v[80:95]
	ds_read_b128 v[32:35], v193 offset:12416
	s_waitcnt lgkmcnt(2)
	v_mfma_f32_32x32x16_bf16 v[80:95], v[24:27], v[116:119], v[80:95]
	ds_read_b128 v[36:39], v190 offset:12544
	s_waitcnt lgkmcnt(2)
	v_mfma_f32_32x32x16_bf16 v[80:95], v[28:31], v[120:123], v[80:95]
	ds_read_b128 v[40:43], v191 offset:12544
	s_waitcnt lgkmcnt(2)
	v_mfma_f32_32x32x16_bf16 v[80:95], v[32:35], v[124:127], v[80:95]
	ds_read_b128 v[44:47], v192 offset:12544
	s_waitcnt lgkmcnt(2)
	v_mfma_f32_32x32x16_bf16 v[80:95], v[36:39], v[128:131], v[80:95]
	ds_read_b128 v[64:67], v193 offset:12544
	s_waitcnt lgkmcnt(2)
	v_mfma_f32_32x32x16_bf16 v[80:95], v[40:43], v[132:135], v[80:95]
	s_waitcnt lgkmcnt(1)
	v_mfma_f32_32x32x16_bf16 v[80:95], v[44:47], v[136:139], v[80:95]
	s_waitcnt lgkmcnt(0)
	v_mfma_f32_32x32x16_bf16 v[80:95], v[64:67], v[140:143], v[80:95]
	v_mfma_f32_32x32x16_bf16 v[48:63], v[12:15], v[140:143], v[48:63]
	s_cbranch_vccnz .LBB0_2013
	s_waitcnt vmcnt(0) lgkmcnt(0)
	s_barrier

.LBB0_2033:
	s_setprio 0
	v_mov_b32_e32 v48, v157
	s_nop 1
	v_permlane32_swap_b32_e32 v157, v48
	v_add_f32_e32 v48, v157, v48
	v_div_scale_f32 v49, s[2:3], v48, v48, 1.0
	v_rcp_f32_e32 v50, v49
	s_mulk_i32 s21, 0x2200
	s_add_i32 s7, s21, 0
	s_waitcnt vmcnt(0) lgkmcnt(0)
	s_barrier
	v_fma_f32 v51, -v49, v50, 1.0
	v_fmac_f32_e32 v50, v51, v50
	v_div_scale_f32 v51, vcc, 1.0, v48, 1.0
	v_mul_f32_e32 v52, v51, v50
	v_fma_f32 v53, -v49, v52, v51
	v_fmac_f32_e32 v52, v53, v50
	v_fma_f32 v49, -v49, v52, v51
	v_div_fmas_f32 v49, v49, v50, v52
	v_div_fixup_f32 v48, v49, v48, 1.0
	v_add3_u32 v49, s7, v195, v181
	v_pk_mul_f32 v[50:51], v[64:65], v[48:49] op_sel_hi:[1,0]
	v_pk_mul_f32 v[52:53], v[66:67], v[48:49] op_sel_hi:[1,0]
	v_cvt_pk_bf16_f32 v50, v50, v51
	v_cvt_pk_bf16_f32 v51, v52, v53
	v_pk_mul_f32 v[52:53], v[68:69], v[48:49] op_sel_hi:[1,0]
	v_pk_mul_f32 v[54:55], v[70:71], v[48:49] op_sel_hi:[1,0]
	v_add_u32_e32 v49, 0xa000, v49
	v_pk_mul_f32 v[32:33], v[32:33], v[48:49] op_sel_hi:[1,0]
	v_pk_mul_f32 v[34:35], v[34:35], v[48:49] op_sel_hi:[1,0]
	v_pk_mul_f32 v[16:17], v[16:17], v[48:49] op_sel_hi:[1,0]
	v_pk_mul_f32 v[18:19], v[18:19], v[48:49] op_sel_hi:[1,0]
	v_pk_mul_f32 v[0:1], v[0:1], v[48:49] op_sel_hi:[1,0]
	v_pk_mul_f32 v[2:3], v[2:3], v[48:49] op_sel_hi:[1,0]
	v_cvt_pk_bf16_f32 v32, v32, v33
	v_cvt_pk_bf16_f32 v33, v34, v35
	v_pk_mul_f32 v[34:35], v[36:37], v[48:49] op_sel_hi:[1,0]
	v_pk_mul_f32 v[36:37], v[38:39], v[48:49] op_sel_hi:[1,0]
	v_cvt_pk_bf16_f32 v16, v16, v17
	v_cvt_pk_bf16_f32 v17, v18, v19
	v_pk_mul_f32 v[18:19], v[20:21], v[48:49] op_sel_hi:[1,0]
	v_pk_mul_f32 v[20:21], v[22:23], v[48:49] op_sel_hi:[1,0]
	v_cvt_pk_bf16_f32 v0, v0, v1
	v_cvt_pk_bf16_f32 v1, v2, v3
	v_pk_mul_f32 v[2:3], v[4:5], v[48:49] op_sel_hi:[1,0]
	v_pk_mul_f32 v[4:5], v[6:7], v[48:49] op_sel_hi:[1,0]
	v_cvt_pk_bf16_f32 v52, v52, v53
	v_cvt_pk_bf16_f32 v53, v54, v55
	v_cvt_pk_bf16_f32 v34, v34, v35
	v_cvt_pk_bf16_f32 v35, v36, v37
	v_cvt_pk_bf16_f32 v18, v18, v19
	v_cvt_pk_bf16_f32 v19, v20, v21
	v_cvt_pk_bf16_f32 v2, v2, v3
	v_cvt_pk_bf16_f32 v3, v4, v5
	ds_write2_b64 v49, v[50:51], v[52:53] offset1:2
	v_pk_mul_f32 v[50:51], v[72:73], v[48:49] op_sel_hi:[1,0]
	v_pk_mul_f32 v[52:53], v[74:75], v[48:49] op_sel_hi:[1,0]
	ds_write2_b64 v49, v[32:33], v[34:35] offset0:8 offset1:10
	v_pk_mul_f32 v[32:33], v[40:41], v[48:49] op_sel_hi:[1,0]
	v_pk_mul_f32 v[34:35], v[42:43], v[48:49] op_sel_hi:[1,0]
	ds_write2_b64 v49, v[16:17], v[18:19] offset0:16 offset1:18
	v_pk_mul_f32 v[16:17], v[24:25], v[48:49] op_sel_hi:[1,0]
	v_pk_mul_f32 v[18:19], v[26:27], v[48:49] op_sel_hi:[1,0]
	ds_write2_b64 v49, v[0:1], v[2:3] offset0:24 offset1:26
	v_pk_mul_f32 v[0:1], v[8:9], v[48:49] op_sel_hi:[1,0]
	v_pk_mul_f32 v[2:3], v[10:11], v[48:49] op_sel_hi:[1,0]
	v_cvt_pk_bf16_f32 v50, v50, v51
	v_cvt_pk_bf16_f32 v51, v52, v53
	v_pk_mul_f32 v[52:53], v[76:77], v[48:49] op_sel_hi:[1,0]
	v_pk_mul_f32 v[54:55], v[78:79], v[48:49] op_sel_hi:[1,0]
	v_cvt_pk_bf16_f32 v32, v32, v33
	v_cvt_pk_bf16_f32 v33, v34, v35
	v_pk_mul_f32 v[34:35], v[44:45], v[48:49] op_sel_hi:[1,0]
	v_pk_mul_f32 v[36:37], v[46:47], v[48:49] op_sel_hi:[1,0]
	v_cvt_pk_bf16_f32 v16, v16, v17
	v_cvt_pk_bf16_f32 v17, v18, v19
	v_pk_mul_f32 v[18:19], v[28:29], v[48:49] op_sel_hi:[1,0]
	v_pk_mul_f32 v[20:21], v[30:31], v[48:49] op_sel_hi:[1,0]
	v_cvt_pk_bf16_f32 v0, v0, v1
	v_cvt_pk_bf16_f32 v1, v2, v3
	v_pk_mul_f32 v[2:3], v[12:13], v[48:49] op_sel_hi:[1,0]
	v_pk_mul_f32 v[4:5], v[14:15], v[48:49] op_sel_hi:[1,0]
	v_cvt_pk_bf16_f32 v52, v52, v53
	v_cvt_pk_bf16_f32 v53, v54, v55
	v_cvt_pk_bf16_f32 v34, v34, v35
	v_cvt_pk_bf16_f32 v35, v36, v37
	v_cvt_pk_bf16_f32 v18, v18, v19
	v_cvt_pk_bf16_f32 v19, v20, v21
	v_cvt_pk_bf16_f32 v2, v2, v3
	v_cvt_pk_bf16_f32 v3, v4, v5
	s_mulk_i32 s20, 0x1800
	s_mul_hi_u32 s2, s19, 0x1800
	ds_write2_b64 v49, v[50:51], v[52:53] offset0:4 offset1:6
	ds_write2_b64 v49, v[32:33], v[34:35] offset0:12 offset1:14
	ds_write2_b64 v49, v[16:17], v[18:19] offset0:20 offset1:22
	ds_write2_b64 v49, v[0:1], v[2:3] offset0:28 offset1:30
	s_add_i32 s2, s2, s20
	s_mulk_i32 s19, 0x1800
	s_nop 0
	s_add_u32 s3, s4, s19
	v_add3_u32 v14, s7, v144, v196
	s_addc_u32 s10, s5, s2
	ds_read_b128 v[0:3], v14 offset:40960
	s_add_u32 s2, s3, s6
	s_addc_u32 s3, s10, 0
	v_mov_b32_e32 v159, 0
	ds_read_b128 v[4:7], v14 offset:42048
	v_lshl_add_u64 v[8:9], s[2:3], 0, v[158:159]
	v_mov_b32_e32 v147, v159
	v_lshl_add_u64 v[10:11], v[8:9], 0, v[146:147]
	s_movk_i32 s2, 0x6000
	s_waitcnt lgkmcnt(1)
	global_store_dwordx4 v[10:11], v[0:3], off
	v_mov_b32_e32 v149, v159
	v_mov_b32_e32 v153, v159
	v_add_co_u32_e32 v0, vcc, s2, v10
	s_mov_b32 s2, 0xc000
	s_nop 0
	v_addc_co_u32_e32 v1, vcc, 0, v11, vcc
	s_waitcnt lgkmcnt(0)
	global_store_dwordx4 v[0:1], v[4:7], off
	ds_read_b128 v[0:3], v14 offset:43136
	ds_read_b128 v[4:7], v14 offset:44224
	v_add_co_u32_e32 v12, vcc, s2, v10
	s_mov_b32 s2, 0x12000
	s_nop 0
	v_addc_co_u32_e32 v13, vcc, 0, v11, vcc
	v_add_co_u32_e32 v10, vcc, s2, v10
	s_waitcnt lgkmcnt(1)
	global_store_dwordx4 v[12:13], v[0:3], off
	v_addc_co_u32_e32 v11, vcc, 0, v11, vcc
	ds_read_b128 v[0:3], v14 offset:45312
	s_waitcnt lgkmcnt(1)
	global_store_dwordx4 v[10:11], v[4:7], off
	ds_read_b128 v[4:7], v14 offset:46400
	v_lshl_add_u64 v[10:11], v[8:9], 0, v[148:149]
	v_mov_b32_e32 v151, v159
	s_waitcnt lgkmcnt(1)
	global_store_dwordx4 v[10:11], v[0:3], off
	v_lshl_add_u64 v[10:11], v[8:9], 0, v[152:153]
	ds_read_b128 v[0:3], v14 offset:47488
	s_waitcnt lgkmcnt(1)
	global_store_dwordx4 v[10:11], v[4:7], off
	ds_read_b128 v[4:7], v14 offset:48576
	v_lshl_add_u64 v[10:11], v[8:9], 0, v[150:151]
	v_mov_b32_e32 v155, v159
	v_readfirstlane_b32 s10, v222
	s_waitcnt lgkmcnt(1)
	global_store_dwordx4 v[10:11], v[0:3], off
	s_and_b32 s2, s10, 0xffffffc0
	s_nop 0
	v_lshl_add_u64 v[0:1], v[8:9], 0, v[154:155]
	s_waitcnt lgkmcnt(0)
	global_store_dwordx4 v[0:1], v[4:7], off
	v_or_b32_e32 v0, s2, v197
	s_mov_b32 s2, 0x2aaaaaab
	v_mul_hi_i32 v1, v0, s2
	v_lshrrev_b32_e32 v2, 31, v1
	v_ashrrev_i32_e32 v1, 2, v1
	v_add_u32_e32 v2, v1, v2
	s_movk_i32 s2, 0xffe8
	v_lshrrev_b32_e32 v159, 1, v2
	v_mad_u64_u32 v[160:161], s[2:3], v2, s2, v[0:1]
	v_xor_b32_e32 v1, v159, v222
	v_bfi_b32 v1, -8, v160, v1
	v_cmp_lt_i32_e32 vcc, 15, v1
	v_add_u32_e32 v2, s8, v2
	s_and_saveexec_b64 s[2:3], vcc
	s_xor_b64 s[2:3], exec, s[2:3]
	v_mov_b32_e32 v3, 0xbfff80
	v_lshl_add_u32 v153, v2, 6, v3
	s_or_saveexec_b64 s[2:3], s[2:3]
	v_mov_b32_e32 v145, 0x1000
	s_xor_b64 exec, exec, s[2:3]
	v_lshl_or_b32 v2, v2, 11, s17
	v_add_u32_e32 v153, 0x8000000, v2
	v_mov_b32_e32 v145, 0x20000
	s_or_b64 exec, exec, s[2:3]
	v_add_u32_e32 v2, 0x200, v0
	s_mov_b32 s2, 0x2aaaaaab
	v_mul_hi_i32 v3, v2, s2
	v_lshrrev_b32_e32 v4, 31, v3
	v_ashrrev_i32_e32 v3, 2, v3
	v_add_u32_e32 v4, v3, v4
	s_movk_i32 s2, 0xffe8
	v_mad_u64_u32 v[162:163], s[2:3], v4, s2, v[2:3]
	v_lshrrev_b32_e32 v163, 1, v4
	v_xor_b32_e32 v3, v163, v222
	v_bfi_b32 v3, -8, v162, v3
	v_cmp_lt_i32_e32 vcc, 15, v3
	v_add_u32_e32 v4, s8, v4
	s_and_saveexec_b64 s[2:3], vcc
	s_xor_b64 s[2:3], exec, s[2:3]
	v_mov_b32_e32 v5, 0xbfff80
	v_lshl_add_u32 v155, v4, 6, v5
	s_or_saveexec_b64 s[2:3], s[2:3]
	v_mov_b32_e32 v147, 0x1000
	s_xor_b64 exec, exec, s[2:3]
	v_lshl_or_b32 v4, v4, 11, s17
	v_add_u32_e32 v155, 0x8000000, v4
	v_mov_b32_e32 v147, 0x20000
	s_or_b64 exec, exec, s[2:3]
	v_add_u32_e32 v4, 0x400, v0
	s_mov_b32 s2, 0x2aaaaaab
	v_mul_hi_i32 v5, v4, s2
	v_lshrrev_b32_e32 v6, 31, v5
	v_ashrrev_i32_e32 v5, 2, v5
	v_add_u32_e32 v5, v5, v6
	s_movk_i32 s2, 0xffe8
	v_mad_u64_u32 v[164:165], s[2:3], v5, s2, v[4:5]
	v_lshrrev_b32_e32 v165, 1, v5
	v_xor_b32_e32 v4, v165, v222
	v_bfi_b32 v4, -8, v164, v4
	v_cmp_lt_i32_e32 vcc, 15, v4
	v_add_u32_e32 v5, s8, v5
	s_and_saveexec_b64 s[2:3], vcc
	s_xor_b64 s[2:3], exec, s[2:3]
	v_mov_b32_e32 v6, 0xbfff80
	v_lshl_add_u32 v161, v5, 6, v6
	s_or_saveexec_b64 s[2:3], s[2:3]
	v_mov_b32_e32 v149, 0x1000
	s_xor_b64 exec, exec, s[2:3]
	v_lshl_or_b32 v5, v5, 11, s17
	v_add_u32_e32 v161, 0x8000000, v5
	v_mov_b32_e32 v149, 0x20000
	s_or_b64 exec, exec, s[2:3]
	s_lshr_b32 s17, s10, 6
	s_lshl_b32 s19, s17, 5
	s_or_b32 s2, s8, s16
	s_add_u32 s12, s2, s19
	v_or_b32_e32 v5, s12, v194
	s_movk_i32 s2, 0x1800
	v_mov_b64_e32 v[6:7], s[4:5]
	s_addc_u32 s13, s9, 0
	v_mad_u64_u32 v[6:7], s[2:3], v5, s2, v[6:7]
	v_mov_b32_e32 v5, 0x1800
	s_mov_b32 s7, 0
	v_mad_i32_i24 v7, s13, v5, v7
	v_lshl_add_u32 v8, v1, 3, v153
	v_ashrrev_i32_e32 v1, 31, v0
	v_lshl_add_u64 v[6:7], v[6:7], 0, s[6:7]
	v_mov_b32_e32 v157, 0
	v_lshrrev_b32_e32 v10, 28, v1
	v_lshl_add_u64 v[6:7], v[6:7], 0, v[156:157]
	v_lshl_add_u32 v4, v4, 3, v161
	v_mov_b32_e32 v5, v157
	v_add_u32_e32 v16, v0, v10
	global_load_dwordx4 v[96:99], v[6:7], off
	global_load_dwordx4 v[100:103], v[6:7], off offset:32
	global_load_dwordx4 v[104:107], v[6:7], off offset:64
	global_load_dwordx4 v[108:111], v[6:7], off offset:96
	global_load_dwordx4 v[112:115], v[6:7], off offset:128
	global_load_dwordx4 v[116:119], v[6:7], off offset:160
	global_load_dwordx4 v[120:123], v[6:7], off offset:192
	global_load_dwordx4 v[124:127], v[6:7], off offset:224
	global_load_dwordx4 v[128:131], v[6:7], off offset:256
	global_load_dwordx4 v[132:135], v[6:7], off offset:288
	global_load_dwordx4 v[136:139], v[6:7], off offset:320
	global_load_dwordx4 v[140:143], v[6:7], off offset:352
	v_lshl_add_u32 v6, v3, 3, v155
	v_ashrrev_i32_e32 v3, 31, v2
	v_lshl_add_u64 v[14:15], v[4:5], 1, s[84:85]
	v_ashrrev_i32_e32 v166, 4, v16
	v_and_b32_e32 v5, 0x1ffffff0, v16
	v_lshrrev_b32_e32 v11, 28, v3
	v_mov_b32_e32 v9, v157
	s_lshl_b32 s2, s17, 10
	v_sub_u32_e32 v0, v0, v5
	v_lshlrev_b32_e32 v5, 2, v166
	v_mov_b32_e32 v7, v157
	v_add_u32_e32 v17, v2, v11
	v_lshl_add_u64 v[10:11], v[8:9], 1, s[84:85]
	v_bfe_u32 v9, v166, 2, 2
	s_add_i32 s7, s2, 0
	v_and_b32_e32 v5, 12, v5
	v_lshl_add_u64 v[12:13], v[6:7], 1, s[84:85]
	v_ashrrev_i32_e32 v167, 4, v17
	v_and_b32_e32 v7, 0x1ffffff0, v17
	v_bitop3_b32 v0, v5, v0, v9 bitop3:0x36
	s_mov_b32 m0, s7
	v_add_lshl_u32 v16, v166, s8, 11
	v_sub_u32_e32 v2, v2, v7
	v_lshlrev_b32_e32 v7, 2, v167
	global_load_lds_dwordx4 v[10:11], off
	s_add_i32 m0, s7, 0x2000
	v_lshlrev_b32_e32 v168, 3, v0
	v_mov_b32_e32 v1, v157
	v_bfe_u32 v17, v167, 2, 2
	v_and_b32_e32 v7, 12, v7
	global_load_lds_dwordx4 v[12:13], off
	s_add_i32 m0, s7, 0x4000
	v_add3_u32 v0, s18, v16, v168
	v_bitop3_b32 v2, v7, v2, v17 bitop3:0x36
	global_load_lds_dwordx4 v[14:15], off
	s_add_i32 m0, s7, 0x6000
	v_lshlrev_b32_e32 v10, 1, v0
	v_add_lshl_u32 v18, v167, s8, 11
	v_lshlrev_b32_e32 v169, 3, v2
	global_load_lds_dwordx4 v10, s[84:85]
	s_add_i32 m0, s7, 0x8000
	v_mov_b32_e32 v3, v157
	v_add3_u32 v2, s18, v18, v169
	s_cmpk_gt_u32 s10, 0xff
	v_lshlrev_b32_e32 v12, 1, v2
	s_cselect_b64 s[8:9], -1, 0
	s_cmpk_lt_u32 s10, 0x100
	v_add_u32_e32 v156, v8, v145
	global_load_lds_dwordx4 v12, s[84:85]
	s_cselect_b64 s[10:11], -1, 0
	s_add_i32 m0, s7, 0xa000
	v_lshl_add_u64 v[8:9], v[156:157], 1, s[84:85]
	v_add_u32_e32 v156, v6, v147
	s_waitcnt vmcnt(0) lgkmcnt(0)
	s_barrier
	s_waitcnt vmcnt(0)
	global_load_lds_dwordx4 v[8:9], off
	v_lshlrev_b32_e32 v6, 1, v156
	s_add_i32 m0, s7, 0xc000
	v_add_u32_e32 v156, v4, v149
	global_load_lds_dwordx4 v6, s[84:85]
	v_lshlrev_b32_e32 v4, 1, v156
	s_add_i32 m0, s7, 0xe000
	v_add_u32_e32 v156, 0x20000, v0
	global_load_lds_dwordx4 v4, s[84:85]
	s_add_i32 m0, s7, 0x10000
	v_lshlrev_b32_e32 v0, 1, v156
	v_add_u32_e32 v156, 0x20000, v2
	global_load_lds_dwordx4 v0, s[84:85]
	v_lshlrev_b32_e32 v0, 1, v156
	s_add_i32 m0, s7, 0x12000
	s_and_b64 vcc, exec, s[10:11]
	global_load_lds_dwordx4 v0, s[84:85]
	ds_read_b128 v[0:3], v190
	ds_read_b128 v[4:7], v191
	ds_read_b128 v[8:11], v192
	ds_read_b128 v[12:15], v193
	s_waitcnt lgkmcnt(3)
	v_mfma_f32_32x32x16_bf16 v[48:63], v[0:3], v[96:99], 0
	ds_read_b128 v[0:3], v190 offset:128
	s_waitcnt lgkmcnt(3)
	v_mfma_f32_32x32x16_bf16 v[48:63], v[4:7], v[100:103], v[48:63]
	ds_read_b128 v[4:7], v191 offset:128
	s_waitcnt lgkmcnt(3)
	v_mfma_f32_32x32x16_bf16 v[48:63], v[8:11], v[104:107], v[48:63]
	ds_read_b128 v[8:11], v192 offset:128
	s_waitcnt lgkmcnt(3)
	v_mfma_f32_32x32x16_bf16 v[48:63], v[12:15], v[108:111], v[48:63]
	ds_read_b128 v[12:15], v193 offset:128
	s_waitcnt lgkmcnt(3)
	v_mfma_f32_32x32x16_bf16 v[48:63], v[0:3], v[112:115], v[48:63]
	ds_read_b128 v[0:3], v190 offset:256
	s_waitcnt lgkmcnt(3)
	v_mfma_f32_32x32x16_bf16 v[48:63], v[4:7], v[116:119], v[48:63]
	ds_read_b128 v[4:7], v191 offset:256
	s_waitcnt lgkmcnt(3)
	v_mfma_f32_32x32x16_bf16 v[48:63], v[8:11], v[120:123], v[48:63]
	ds_read_b128 v[8:11], v192 offset:256
	s_waitcnt lgkmcnt(3)
	v_mfma_f32_32x32x16_bf16 v[48:63], v[12:15], v[124:127], v[48:63]
	ds_read_b128 v[12:15], v193 offset:256
	s_waitcnt lgkmcnt(3)
	v_mfma_f32_32x32x16_bf16 v[48:63], v[0:3], v[128:131], v[48:63]
	ds_read_b128 v[0:3], v190 offset:12288
	s_waitcnt lgkmcnt(3)
	v_mfma_f32_32x32x16_bf16 v[48:63], v[4:7], v[132:135], v[48:63]
	ds_read_b128 v[4:7], v191 offset:12288
	s_waitcnt lgkmcnt(3)
	v_mfma_f32_32x32x16_bf16 v[48:63], v[8:11], v[136:139], v[48:63]
	ds_read_b128 v[8:11], v192 offset:12288
	s_waitcnt lgkmcnt(2)
	v_mfma_f32_32x32x16_bf16 v[80:95], v[0:3], v[96:99], 0
	ds_read_b128 v[16:19], v193 offset:12288
	s_waitcnt lgkmcnt(2)
	v_mfma_f32_32x32x16_bf16 v[80:95], v[4:7], v[100:103], v[80:95]
	ds_read_b128 v[20:23], v190 offset:12416
	s_waitcnt lgkmcnt(2)
	v_mfma_f32_32x32x16_bf16 v[80:95], v[8:11], v[104:107], v[80:95]
	ds_read_b128 v[24:27], v191 offset:12416
	s_waitcnt lgkmcnt(2)
	v_mfma_f32_32x32x16_bf16 v[80:95], v[16:19], v[108:111], v[80:95]
	ds_read_b128 v[28:31], v192 offset:12416
	s_waitcnt lgkmcnt(2)
	v_mfma_f32_32x32x16_bf16 v[80:95], v[20:23], v[112:115], v[80:95]
	ds_read_b128 v[32:35], v193 offset:12416
	s_waitcnt lgkmcnt(2)
	v_mfma_f32_32x32x16_bf16 v[80:95], v[24:27], v[116:119], v[80:95]
	ds_read_b128 v[36:39], v190 offset:12544
	s_waitcnt lgkmcnt(2)
	v_mfma_f32_32x32x16_bf16 v[80:95], v[28:31], v[120:123], v[80:95]
	ds_read_b128 v[40:43], v191 offset:12544
	s_waitcnt lgkmcnt(2)
	v_mfma_f32_32x32x16_bf16 v[80:95], v[32:35], v[124:127], v[80:95]
	ds_read_b128 v[44:47], v192 offset:12544
	s_waitcnt lgkmcnt(2)
	v_mfma_f32_32x32x16_bf16 v[80:95], v[36:39], v[128:131], v[80:95]
	ds_read_b128 v[64:67], v193 offset:12544
	s_waitcnt lgkmcnt(2)
	v_mfma_f32_32x32x16_bf16 v[80:95], v[40:43], v[132:135], v[80:95]
	s_waitcnt lgkmcnt(1)
	v_mfma_f32_32x32x16_bf16 v[80:95], v[44:47], v[136:139], v[80:95]
	s_waitcnt lgkmcnt(0)
	v_mfma_f32_32x32x16_bf16 v[80:95], v[64:67], v[140:143], v[80:95]
	v_mfma_f32_32x32x16_bf16 v[48:63], v[12:15], v[140:143], v[48:63]
	s_cbranch_vccnz .LBB0_2047
	s_waitcnt vmcnt(0) lgkmcnt(0)
	s_barrier

.LBB0_2052:
	s_add_i32 s10, s7, s15
	v_lshlrev_b32_e32 v168, 1, v156
	s_mov_b32 m0, s10
	v_mov_b32_e32 v161, v157
	global_load_lds_dwordx4 v168, s[84:85]
	v_lshlrev_b32_e32 v168, 1, v160
	s_add_i32 m0, s10, 0x2000
	v_mov_b32_e32 v163, v157
	global_load_lds_dwordx4 v168, s[84:85]
	v_lshlrev_b32_e32 v168, 1, v162
	s_add_i32 m0, s10, 0x4000
	v_mov_b32_e32 v167, v157
	global_load_lds_dwordx4 v168, s[84:85]
	s_add_i32 m0, s10, 0x6000
	v_lshlrev_b32_e32 v168, 1, v166
	v_mov_b32_e32 v165, v157
	global_load_lds_dwordx4 v168, s[84:85]
	v_lshlrev_b32_e32 v168, 1, v164
	s_add_i32 m0, s10, 0x8000
	s_nop 0
	global_load_lds_dwordx4 v168, s[84:85]
